# speedup vs baseline: 1.0224x; 1.0224x over previous
.LBB0_147:
	v_max_u32_dpp v18, v5, v5 quad_perm:[1,0,3,2] row_mask:0xf bank_mask:0xf
	v_max_u32_dpp v19, v10, v10 quad_perm:[1,0,3,2] row_mask:0xf bank_mask:0xf
	s_nop 0
	v_max_u32_dpp v18, v18, v18 quad_perm:[2,3,0,1] row_mask:0xf bank_mask:0xf
	v_max_u32_dpp v19, v19, v19 quad_perm:[2,3,0,1] row_mask:0xf bank_mask:0xf
	s_nop 0
	v_max_u32_dpp v18, v18, v18 row_half_mirror row_mask:0xf bank_mask:0xf
	v_max_u32_dpp v19, v19, v19 row_half_mirror row_mask:0xf bank_mask:0xf
	s_nop 0
	v_max_u32_dpp v18, v18, v18 row_mirror row_mask:0xf bank_mask:0xf
	v_max_u32_dpp v19, v19, v19 row_mirror row_mask:0xf bank_mask:0xf
	v_cmp_eq_u32_e32 vcc, v5, v18
	v_cmp_eq_u32_e64 s[10:11], v10, v19
	s_nop 0
	v_cndmask_b32_e32 v5, v5, v3, vcc
	v_cndmask_b32_e32 v3, v3, v7, vcc
	v_cndmask_b32_e32 v7, v7, v2, vcc
	v_cndmask_b32_e32 v2, v2, v8, vcc
	v_cndmask_b32_e32 v8, v8, v4, vcc
	v_cndmask_b32_e32 v4, v4, v9, vcc
	v_cndmask_b32_e32 v9, v9, v6, vcc
	v_cndmask_b32_e64 v6, v6, 0, vcc
	v_cndmask_b32_e64 v10, v10, v12, s[10:11]
	v_cndmask_b32_e64 v12, v12, v13, s[10:11]
	v_cndmask_b32_e64 v13, v13, v14, s[10:11]
	v_cndmask_b32_e64 v14, v14, v15, s[10:11]
	v_cndmask_b32_e64 v15, v15, v16, s[10:11]
	v_cndmask_b32_e64 v16, v16, v17, s[10:11]
	v_cndmask_b32_e64 v17, v17, v11, s[10:11]
	v_cndmask_b32_e64 v11, v11, 0, s[10:11]
	v_cmp_eq_u32_e32 vcc, s0, v83
	s_add_i32 s0, s0, 1
	s_cmp_eq_u32 s0, 16
	v_cndmask_b32_e32 v96, v96, v18, vcc
	v_cndmask_b32_e32 v97, v97, v19, vcc
	s_cbranch_scc0 .LBB0_147
	s_movk_i32 s0, 0x400
	s_mov_b64 s[6:7], 0
	s_and_b64 vcc, exec, s[60:61]
	s_cbranch_vccnz .LBB0_150
	v_mov_b32_e32 v225, v97
	v_mov_b32_e32 v158, v96
	s_branch .LBB0_142

.LBB0_159:
	v_max_u32_dpp v7, v3, v3 quad_perm:[1,0,3,2] row_mask:0xf bank_mask:0xf
	s_nop 1
	v_max_u32_dpp v7, v7, v7 quad_perm:[2,3,0,1] row_mask:0xf bank_mask:0xf
	s_nop 1
	v_max_u32_dpp v7, v7, v7 row_half_mirror row_mask:0xf bank_mask:0xf
	s_nop 1
	v_max_u32_dpp v7, v7, v7 row_mirror row_mask:0xf bank_mask:0xf
	v_cmp_eq_u32_e32 vcc, v3, v7
	s_nop 1
	v_cndmask_b32_e32 v3, v3, v5, vcc
	v_cndmask_b32_e32 v5, v5, v6, vcc
	v_cndmask_b32_e32 v6, v6, v4, vcc
	v_cndmask_b32_e64 v4, v4, 0, vcc
	v_cmp_eq_u32_e32 vcc, s0, v83
	s_add_i32 s0, s0, 1
	s_cmp_eq_u32 s0, 16
	v_cndmask_b32_e32 v2, v2, v7, vcc
	s_cbranch_scc0 .LBB0_159
	v_cmp_lt_i32_e32 vcc, -1, v2
	s_movk_i32 s0, 0xff00
	v_not_b32_e32 v3, v2
	v_cndmask_b32_e64 v4, v189, -1, vcc
	v_bitop3_b32 v4, v4, v2, s0 bitop3:0x78
	ds_bpermute_b32 v5, v157, v4
	v_lshrrev_b32_e32 v3, 4, v3
	v_and_or_b32 v3, v3, 15, v156
	v_lshlrev_b32_e32 v3, 2, v3
	v_bitop3_b32 v2, v2, v156, 15 bitop3:0xce
	s_waitcnt lgkmcnt(0)
	v_sub_f32_e32 v4, v4, v5
	v_mul_f32_e32 v4, 0x3fb8aa3b, v4
	v_exp_f32_e32 v4, v4
	ds_bpermute_b32 v3, v3, v158
	v_lshlrev_b32_e32 v2, 2, v2
	ds_bpermute_b32 v2, v2, v225
	v_add_f32_dpp v5, v4, v4 quad_perm:[1,0,3,2] row_mask:0xf bank_mask:0xf bound_ctrl:1
	ds_bpermute_b32 v100, v166, v96
	s_waitcnt lgkmcnt(2)
	v_lshlrev_b32_e32 v3, 7, v3
	v_add_f32_dpp v5, v5, v5 quad_perm:[2,3,0,1] row_mask:0xf bank_mask:0xf bound_ctrl:1
	v_and_b32_e32 v3, 0x3f80, v3
	s_waitcnt lgkmcnt(1)
	v_and_b32_e32 v2, 0x7f, v2
	v_add_f32_dpp v5, v5, v5 row_half_mirror row_mask:0xf bank_mask:0xf bound_ctrl:1
	v_bitop3_b32 v2, v2, s74, v3 bitop3:0x36
	ds_bpermute_b32 v101, v167, v97
	v_add_f32_dpp v5, v5, v5 row_mirror row_mask:0xf bank_mask:0xf bound_ctrl:1
	v_div_scale_f32 v6, s[6:7], v5, v5, v4
	v_rcp_f32_e32 v7, v6
	v_mov_b32_e32 v98, 0
	v_mov_b32_e32 v99, 0
	v_fma_f32 v3, -v6, v7, 1.0
	v_fmac_f32_e32 v7, v3, v7
	v_div_scale_f32 v3, vcc, v4, v5, v4
	v_mul_f32_e32 v8, v3, v7
	v_fma_f32 v9, -v6, v8, v3
	v_fmac_f32_e32 v8, v9, v7
	v_fma_f32 v3, -v6, v8, v3
	v_div_fmas_f32 v3, v3, v7, v8
	v_div_fixup_f32 v3, v3, v5, v4
	ds_write2st64_b32 v154, v3, v2 offset0:136 offset1:138
	v_add_u32_e32 v2, 0x8800, v224
	ds_read2_b32 v[6:7], v2 offset0:128 offset1:132
	ds_read_b32 v18, v224 offset:35360
	s_waitcnt lgkmcnt(1)
	v_ashrrev_i32_e32 v3, 31, v6
	v_mov_b32_e32 v2, v6
	v_ashrrev_i32_e32 v9, 31, v7
	v_mov_b32_e32 v8, v7
	s_waitcnt lgkmcnt(0)
	v_ashrrev_i32_e32 v19, 31, v18
	v_lshlrev_b64 v[2:3], 9, v[2:3]
	v_lshlrev_b64 v[6:7], 9, v[8:9]
	v_lshlrev_b64 v[18:19], 9, v[18:19]
	v_or_b32_e32 v2, v2, v0
	v_or_b32_e32 v6, v6, v0
	v_or_b32_e32 v18, v18, v0
	v_lshl_add_u64 v[4:5], s[12:13], 0, v[2:3]
	v_lshl_add_u64 v[2:3], s[14:15], 0, v[2:3]
	v_lshl_add_u64 v[8:9], s[12:13], 0, v[6:7]
	v_lshl_add_u64 v[6:7], s[14:15], 0, v[6:7]
	v_lshl_add_u64 v[20:21], s[12:13], 0, v[18:19]
	v_lshl_add_u64 v[18:19], s[14:15], 0, v[18:19]
	global_load_dwordx4 v[66:69], v[4:5], off
	global_load_dwordx4 v[58:61], v[4:5], off offset:256
	global_load_dwordx4 v[10:13], v[2:3], off
	s_nop 0
	global_load_dwordx4 v[2:5], v[2:3], off offset:256
	s_nop 0
	global_load_dwordx4 v[74:77], v[8:9], off
	global_load_dwordx4 v[62:65], v[8:9], off offset:256
	global_load_dwordx4 v[14:17], v[6:7], off
	s_nop 0
	global_load_dwordx4 v[6:9], v[6:7], off offset:256
	s_nop 0
	global_load_dwordx4 v[78:81], v[20:21], off
	global_load_dwordx4 v[70:73], v[20:21], off offset:256
	global_load_dwordx4 v[22:25], v[18:19], off
	s_nop 0
	global_load_dwordx4 v[18:21], v[18:19], off offset:256
	s_and_saveexec_b64 s[6:7], s[46:47]
	s_cbranch_execz .LBB0_162
	v_cmp_lt_i32_e32 vcc, -1, v101
	v_and_b32_e32 v99, 0xffffff80, v101
	v_and_b32_e32 v102, 0xffffff80, v100
	v_cndmask_b32_e64 v101, v189, -1, vcc
	v_cmp_lt_i32_e32 vcc, -1, v100
	v_xor_b32_e32 v101, v101, v99
	s_nop 0
	v_cndmask_b32_e64 v100, v189, -1, vcc
	v_xor_b32_e32 v100, v100, v102
	v_pk_add_f32 v[100:101], v[100:101], v[100:101] op_sel:[1,0] op_sel_hi:[0,1]
	v_ashrrev_i32_e32 v99, 31, v100
	v_or_b32_e32 v99, 0x80000000, v99
	v_bitop3_b32 v99, v99, s0, v100 bitop3:0x48
	v_bitop3_b32 v99, v99, s26, v213 bitop3:0x36

.LBB0_169:
	v_max_u32_dpp v103, v99, v99 quad_perm:[1,0,3,2] row_mask:0xf bank_mask:0xf
	s_nop 1
	v_max_u32_dpp v103, v103, v103 quad_perm:[2,3,0,1] row_mask:0xf bank_mask:0xf
	s_nop 1
	v_max_u32_dpp v103, v103, v103 row_half_mirror row_mask:0xf bank_mask:0xf
	s_nop 1
	v_max_u32_dpp v103, v103, v103 row_mirror row_mask:0xf bank_mask:0xf
	v_cmp_eq_u32_e32 vcc, v99, v103
	s_nop 1
	v_cndmask_b32_e32 v99, v99, v101, vcc
	v_cndmask_b32_e32 v101, v101, v102, vcc
	v_cndmask_b32_e32 v102, v102, v100, vcc
	v_cndmask_b32_e64 v100, v100, 0, vcc
	v_cmp_eq_u32_e32 vcc, s0, v83
	s_add_i32 s0, s0, 1
	s_cmp_lg_u32 s0, 16
	v_cndmask_b32_e32 v98, v98, v103, vcc
	s_cbranch_scc1 .LBB0_169
	v_not_b32_e32 v99, v98
	v_lshrrev_b32_e32 v99, 4, v99
	v_and_or_b32 v99, v99, 15, v156
	v_lshlrev_b32_e32 v99, 2, v99
	v_cmp_lt_i32_e32 vcc, -1, v98
	ds_bpermute_b32 v96, v99, v96
	s_movk_i32 s0, 0xff00
	v_cndmask_b32_e64 v99, v189, -1, vcc
	v_bitop3_b32 v99, v99, v98, s0 bitop3:0x78
	ds_bpermute_b32 v100, v157, v99
	v_bitop3_b32 v98, v98, v156, 15 bitop3:0xce
	v_lshlrev_b32_e32 v98, 2, v98
	ds_bpermute_b32 v97, v98, v97
	s_waitcnt lgkmcnt(2)
	v_lshlrev_b32_e32 v96, 7, v96
	s_waitcnt lgkmcnt(1)
	v_sub_f32_e32 v98, v99, v100
	v_mul_f32_e32 v98, 0x3fb8aa3b, v98
	v_exp_f32_e32 v112, v98
	v_and_b32_e32 v96, 0x3f80, v96
	s_waitcnt lgkmcnt(0)
	v_and_b32_e32 v97, 0x7f, v97
	v_bitop3_b32 v113, v97, s74, v96 bitop3:0x36
	v_add_f32_dpp v96, v112, v112 quad_perm:[1,0,3,2] row_mask:0xf bank_mask:0xf bound_ctrl:1
	v_readlane_b32 s0, v254, 52
	s_waitcnt vmcnt(18)
	v_lshlrev_b32_e32 v120, 16, v46
	v_add_f32_dpp v96, v96, v96 quad_perm:[2,3,0,1] row_mask:0xf bank_mask:0xf bound_ctrl:1
	v_add_u32_e32 v226, s0, v94
	v_and_b32_e32 v121, 0xffff0000, v46
	v_add_f32_dpp v96, v96, v96 row_half_mirror row_mask:0xf bank_mask:0xf bound_ctrl:1
	v_lshlrev_b32_e32 v46, 16, v47
	v_and_b32_e32 v47, 0xffff0000, v47
	v_add_f32_dpp v114, v96, v96 row_mirror row_mask:0xf bank_mask:0xf bound_ctrl:1
	v_min_i32_e32 v96, 0x3fff, v226
	v_ashrrev_i32_e32 v97, 31, v96
	v_lshlrev_b64 v[96:97], 12, v[96:97]
	v_lshl_add_u64 v[96:97], v[92:93], 0, v[96:97]
	global_load_dwordx2 v[110:111], v[96:97], off
	global_load_dwordx2 v[108:109], v[96:97], off offset:512
	global_load_dwordx2 v[106:107], v[96:97], off offset:1024
	global_load_dwordx2 v[104:105], v[96:97], off offset:1536
	global_load_dwordx2 v[102:103], v[96:97], off offset:2048
	global_load_dwordx2 v[100:101], v[96:97], off offset:2560
	global_load_dwordx2 v[98:99], v[96:97], off offset:3072
	s_nop 0
	global_load_dwordx2 v[96:97], v[96:97], off offset:3584
	v_div_scale_f32 v115, s[6:7], v114, v114, v112
	v_rcp_f32_e32 v116, v115
	v_lshlrev_b32_e32 v122, 16, v48
	v_and_b32_e32 v123, 0xffff0000, v48
	v_lshlrev_b32_e32 v48, 16, v49
	v_fma_f32 v117, -v115, v116, 1.0
	v_fmac_f32_e32 v116, v117, v116
	v_div_scale_f32 v117, vcc, v112, v114, v112
	v_mul_f32_e32 v118, v117, v116
	v_fma_f32 v119, -v115, v118, v117
	v_fmac_f32_e32 v118, v119, v116
	v_fma_f32 v115, -v115, v118, v117
	v_div_fmas_f32 v115, v115, v116, v118
	v_div_fixup_f32 v112, v115, v114, v112
	ds_write2st64_b32 v154, v112, v113 offset0:137 offset1:139
	s_waitcnt vmcnt(24)
	v_lshlrev_b32_e32 v112, 16, v54
	v_and_b32_e32 v113, 0xffff0000, v54
	v_lshlrev_b32_e32 v54, 16, v55
	v_and_b32_e32 v55, 0xffff0000, v55
	v_lshlrev_b32_e32 v114, 16, v56
	v_and_b32_e32 v115, 0xffff0000, v56
	v_lshlrev_b32_e32 v56, 16, v57
	v_and_b32_e32 v57, 0xffff0000, v57
	v_lshlrev_b32_e32 v116, 16, v50
	v_and_b32_e32 v117, 0xffff0000, v50
	v_lshlrev_b32_e32 v50, 16, v51
	v_and_b32_e32 v51, 0xffff0000, v51
	v_lshlrev_b32_e32 v118, 16, v52
	v_and_b32_e32 v119, 0xffff0000, v52
	v_lshlrev_b32_e32 v52, 16, v53
	v_and_b32_e32 v53, 0xffff0000, v53
	v_and_b32_e32 v49, 0xffff0000, v49
	v_lshlrev_b32_e32 v126, 16, v38
	v_and_b32_e32 v127, 0xffff0000, v38
	v_lshlrev_b32_e32 v38, 16, v39
	v_and_b32_e32 v39, 0xffff0000, v39
	v_lshlrev_b32_e32 v128, 16, v40
	v_and_b32_e32 v129, 0xffff0000, v40
	v_lshlrev_b32_e32 v40, 16, v41
	v_and_b32_e32 v41, 0xffff0000, v41
	s_waitcnt vmcnt(20)
	v_lshlrev_b32_e32 v130, 16, v42
	v_and_b32_e32 v131, 0xffff0000, v42
	v_lshlrev_b32_e32 v42, 16, v43
	v_and_b32_e32 v43, 0xffff0000, v43
	v_lshlrev_b32_e32 v132, 16, v44
	v_and_b32_e32 v133, 0xffff0000, v44
	v_lshlrev_b32_e32 v44, 16, v45
	v_and_b32_e32 v45, 0xffff0000, v45
	v_lshlrev_b32_e32 v134, 16, v34
	v_and_b32_e32 v135, 0xffff0000, v34
	v_lshlrev_b32_e32 v34, 16, v35
	v_and_b32_e32 v35, 0xffff0000, v35
	v_lshlrev_b32_e32 v136, 16, v36
	v_and_b32_e32 v137, 0xffff0000, v36
	v_lshlrev_b32_e32 v36, 16, v37
	v_and_b32_e32 v37, 0xffff0000, v37
	v_lshlrev_b32_e32 v138, 16, v30
	v_and_b32_e32 v139, 0xffff0000, v30
	v_lshlrev_b32_e32 v140, 16, v31
	v_and_b32_e32 v141, 0xffff0000, v31
	v_lshlrev_b32_e32 v142, 16, v32
	v_and_b32_e32 v143, 0xffff0000, v32
	v_lshlrev_b32_e32 v144, 16, v33
	v_and_b32_e32 v145, 0xffff0000, v33
	v_lshlrev_b32_e32 v146, 16, v26
	v_and_b32_e32 v147, 0xffff0000, v26
	v_lshlrev_b32_e32 v148, 16, v27
	v_and_b32_e32 v149, 0xffff0000, v27
	v_lshlrev_b32_e32 v150, 16, v28
	v_and_b32_e32 v151, 0xffff0000, v28
	v_lshlrev_b32_e32 v152, 16, v29
	v_and_b32_e32 v153, 0xffff0000, v29
	ds_read_b32 v240, v217 offset:35376
	v_lshlrev_b32_e32 v245, 2, v124
	v_add_u32_e32 v245, 0xb800, v245
	v_add_u32_e32 v227, 0x8a00, v217
	s_movk_i32 s0, 0x200
	s_mov_b32 s2, 0
	v_cndmask_b32_e64 v244, v245, v221, s[44:45]
	s_waitcnt lgkmcnt(0)
	ds_read_b32 v241, v227 offset:64
	s_waitcnt vmcnt(5)
	v_mad_u64_u32 v[242:243], s[6:7], v240, s0, v[84:85]
	global_load_dwordx4 v[30:33], v[242:243], off
	global_load_dwordx4 v[26:29], v[242:243], off offset:256
	v_cvt_scalef32_pk_f32_fp4 v[196:197], v66, 1.0
	v_cvt_scalef32_pk_f32_fp4 v[198:199], v66, 1.0 op_sel:[1,0,0]
	v_cvt_scalef32_pk_f32_fp4 v[230:231], v66, 1.0 op_sel:[0,1,0]
	v_cvt_scalef32_pk_f32_fp4 v[232:233], v66, 1.0 op_sel:[1,1,0]
	v_pk_fma_f32 v[234:235], v[112:113], v[196:197], 0 op_sel_hi:[1,1,0]
	v_pk_fma_f32 v[236:237], v[54:55], v[198:199], 0 op_sel_hi:[1,1,0]
	v_pk_fma_f32 v[234:235], v[114:115], v[230:231], v[234:235]
	v_pk_fma_f32 v[236:237], v[56:57], v[232:233], v[236:237]
	v_cvt_scalef32_pk_f32_fp4 v[196:197], v67, 1.0
	v_cvt_scalef32_pk_f32_fp4 v[198:199], v67, 1.0 op_sel:[1,0,0]
	v_cvt_scalef32_pk_f32_fp4 v[230:231], v67, 1.0 op_sel:[0,1,0]
	v_cvt_scalef32_pk_f32_fp4 v[232:233], v67, 1.0 op_sel:[1,1,0]
	v_pk_fma_f32 v[234:235], v[116:117], v[196:197], v[234:235]
	v_pk_fma_f32 v[236:237], v[50:51], v[198:199], v[236:237]
	v_pk_fma_f32 v[234:235], v[118:119], v[230:231], v[234:235]
	v_pk_fma_f32 v[236:237], v[52:53], v[232:233], v[236:237]
	v_cvt_scalef32_pk_f32_fp4 v[196:197], v68, 1.0
	v_cvt_scalef32_pk_f32_fp4 v[198:199], v68, 1.0 op_sel:[1,0,0]
	v_cvt_scalef32_pk_f32_fp4 v[230:231], v68, 1.0 op_sel:[0,1,0]
	v_cvt_scalef32_pk_f32_fp4 v[232:233], v68, 1.0 op_sel:[1,1,0]
	v_pk_fma_f32 v[234:235], v[120:121], v[196:197], v[234:235]
	v_pk_fma_f32 v[236:237], v[46:47], v[198:199], v[236:237]
	v_pk_fma_f32 v[234:235], v[122:123], v[230:231], v[234:235]
	v_pk_fma_f32 v[236:237], v[48:49], v[232:233], v[236:237]
	v_cvt_scalef32_pk_f32_fp4 v[196:197], v69, 1.0
	v_cvt_scalef32_pk_f32_fp4 v[198:199], v69, 1.0 op_sel:[1,0,0]
	v_cvt_scalef32_pk_f32_fp4 v[230:231], v69, 1.0 op_sel:[0,1,0]
	v_cvt_scalef32_pk_f32_fp4 v[232:233], v69, 1.0 op_sel:[1,1,0]
	v_pk_fma_f32 v[234:235], v[126:127], v[196:197], v[234:235]
	v_pk_fma_f32 v[236:237], v[38:39], v[198:199], v[236:237]
	v_pk_fma_f32 v[234:235], v[128:129], v[230:231], v[234:235]
	v_pk_fma_f32 v[236:237], v[40:41], v[232:233], v[236:237]
	s_waitcnt vmcnt(6)
	v_cvt_scalef32_pk_f32_fp4 v[196:197], v58, 1.0
	v_cvt_scalef32_pk_f32_fp4 v[198:199], v58, 1.0 op_sel:[1,0,0]
	v_cvt_scalef32_pk_f32_fp4 v[230:231], v58, 1.0 op_sel:[0,1,0]
	v_cvt_scalef32_pk_f32_fp4 v[232:233], v58, 1.0 op_sel:[1,1,0]
	v_pk_fma_f32 v[234:235], v[130:131], v[196:197], v[234:235]
	v_pk_fma_f32 v[236:237], v[42:43], v[198:199], v[236:237]
	v_pk_fma_f32 v[234:235], v[132:133], v[230:231], v[234:235]
	v_pk_fma_f32 v[236:237], v[44:45], v[232:233], v[236:237]
	v_cvt_scalef32_pk_f32_fp4 v[196:197], v59, 1.0
	v_cvt_scalef32_pk_f32_fp4 v[198:199], v59, 1.0 op_sel:[1,0,0]
	v_cvt_scalef32_pk_f32_fp4 v[230:231], v59, 1.0 op_sel:[0,1,0]
	v_cvt_scalef32_pk_f32_fp4 v[232:233], v59, 1.0 op_sel:[1,1,0]
	v_pk_fma_f32 v[234:235], v[134:135], v[196:197], v[234:235]
	v_pk_fma_f32 v[236:237], v[34:35], v[198:199], v[236:237]
	v_pk_fma_f32 v[234:235], v[136:137], v[230:231], v[234:235]
	v_pk_fma_f32 v[236:237], v[36:37], v[232:233], v[236:237]
	v_cvt_scalef32_pk_f32_fp4 v[196:197], v60, 1.0
	v_cvt_scalef32_pk_f32_fp4 v[198:199], v60, 1.0 op_sel:[1,0,0]
	v_cvt_scalef32_pk_f32_fp4 v[230:231], v60, 1.0 op_sel:[0,1,0]
	v_cvt_scalef32_pk_f32_fp4 v[232:233], v60, 1.0 op_sel:[1,1,0]
	v_pk_fma_f32 v[234:235], v[138:139], v[196:197], v[234:235]
	v_pk_fma_f32 v[236:237], v[140:141], v[198:199], v[236:237]
	v_pk_fma_f32 v[234:235], v[142:143], v[230:231], v[234:235]
	v_pk_fma_f32 v[236:237], v[144:145], v[232:233], v[236:237]
	v_cvt_scalef32_pk_f32_fp4 v[196:197], v61, 1.0
	v_cvt_scalef32_pk_f32_fp4 v[198:199], v61, 1.0 op_sel:[1,0,0]
	v_cvt_scalef32_pk_f32_fp4 v[230:231], v61, 1.0 op_sel:[0,1,0]
	v_cvt_scalef32_pk_f32_fp4 v[232:233], v61, 1.0 op_sel:[1,1,0]
	v_pk_fma_f32 v[234:235], v[146:147], v[196:197], v[234:235]
	v_pk_fma_f32 v[236:237], v[148:149], v[198:199], v[236:237]
	v_pk_fma_f32 v[234:235], v[150:151], v[230:231], v[234:235]
	v_pk_fma_f32 v[236:237], v[152:153], v[232:233], v[236:237]
	v_add_f32_e32 v238, v236, v237
	v_add_f32_e32 v242, v234, v235
	v_add_f32_e32 v238, v242, v238
	s_nop 0
	v_add_f32_dpp v238, v238, v238 quad_perm:[1,0,3,2] row_mask:0xf bank_mask:0xf bound_ctrl:1
	s_nop 1
	v_add_f32_dpp v238, v238, v238 quad_perm:[2,3,0,1] row_mask:0xf bank_mask:0xf bound_ctrl:1
	s_nop 1
	v_add_f32_dpp v238, v238, v238 row_half_mirror row_mask:0xf bank_mask:0xf bound_ctrl:1
	s_nop 1
	v_add_f32_dpp v238, v238, v238 row_mirror row_mask:0xf bank_mask:0xf bound_ctrl:1
	ds_write_b32 v244, v238 offset:0
	s_waitcnt lgkmcnt(0)
.Lpu_loop:
	ds_read_b32 v240, v227 offset:80
	s_waitcnt vmcnt(5)
	v_mad_u64_u32 v[242:243], s[6:7], v241, s0, v[84:85]
	global_load_dwordx4 v[66:69], v[242:243], off
	global_load_dwordx4 v[58:61], v[242:243], off offset:256
	v_cvt_scalef32_pk_f32_fp4 v[196:197], v74, 1.0
	v_cvt_scalef32_pk_f32_fp4 v[198:199], v74, 1.0 op_sel:[1,0,0]
	v_cvt_scalef32_pk_f32_fp4 v[230:231], v74, 1.0 op_sel:[0,1,0]
	v_cvt_scalef32_pk_f32_fp4 v[232:233], v74, 1.0 op_sel:[1,1,0]
	v_pk_fma_f32 v[234:235], v[112:113], v[196:197], 0 op_sel_hi:[1,1,0]
	v_pk_fma_f32 v[236:237], v[54:55], v[198:199], 0 op_sel_hi:[1,1,0]
	v_pk_fma_f32 v[234:235], v[114:115], v[230:231], v[234:235]
	v_pk_fma_f32 v[236:237], v[56:57], v[232:233], v[236:237]
	v_cvt_scalef32_pk_f32_fp4 v[196:197], v75, 1.0
	v_cvt_scalef32_pk_f32_fp4 v[198:199], v75, 1.0 op_sel:[1,0,0]
	v_cvt_scalef32_pk_f32_fp4 v[230:231], v75, 1.0 op_sel:[0,1,0]
	v_cvt_scalef32_pk_f32_fp4 v[232:233], v75, 1.0 op_sel:[1,1,0]
	v_pk_fma_f32 v[234:235], v[116:117], v[196:197], v[234:235]
	v_pk_fma_f32 v[236:237], v[50:51], v[198:199], v[236:237]
	v_pk_fma_f32 v[234:235], v[118:119], v[230:231], v[234:235]
	v_pk_fma_f32 v[236:237], v[52:53], v[232:233], v[236:237]
	v_cvt_scalef32_pk_f32_fp4 v[196:197], v76, 1.0
	v_cvt_scalef32_pk_f32_fp4 v[198:199], v76, 1.0 op_sel:[1,0,0]
	v_cvt_scalef32_pk_f32_fp4 v[230:231], v76, 1.0 op_sel:[0,1,0]
	v_cvt_scalef32_pk_f32_fp4 v[232:233], v76, 1.0 op_sel:[1,1,0]
	v_pk_fma_f32 v[234:235], v[120:121], v[196:197], v[234:235]
	v_pk_fma_f32 v[236:237], v[46:47], v[198:199], v[236:237]
	v_pk_fma_f32 v[234:235], v[122:123], v[230:231], v[234:235]
	v_pk_fma_f32 v[236:237], v[48:49], v[232:233], v[236:237]
	v_cvt_scalef32_pk_f32_fp4 v[196:197], v77, 1.0
	v_cvt_scalef32_pk_f32_fp4 v[198:199], v77, 1.0 op_sel:[1,0,0]
	v_cvt_scalef32_pk_f32_fp4 v[230:231], v77, 1.0 op_sel:[0,1,0]
	v_cvt_scalef32_pk_f32_fp4 v[232:233], v77, 1.0 op_sel:[1,1,0]
	v_pk_fma_f32 v[234:235], v[126:127], v[196:197], v[234:235]
	v_pk_fma_f32 v[236:237], v[38:39], v[198:199], v[236:237]
	v_pk_fma_f32 v[234:235], v[128:129], v[230:231], v[234:235]
	v_pk_fma_f32 v[236:237], v[40:41], v[232:233], v[236:237]
	s_waitcnt vmcnt(6)
	v_cvt_scalef32_pk_f32_fp4 v[196:197], v62, 1.0
	v_cvt_scalef32_pk_f32_fp4 v[198:199], v62, 1.0 op_sel:[1,0,0]
	v_cvt_scalef32_pk_f32_fp4 v[230:231], v62, 1.0 op_sel:[0,1,0]
	v_cvt_scalef32_pk_f32_fp4 v[232:233], v62, 1.0 op_sel:[1,1,0]
	v_pk_fma_f32 v[234:235], v[130:131], v[196:197], v[234:235]
	v_pk_fma_f32 v[236:237], v[42:43], v[198:199], v[236:237]
	v_pk_fma_f32 v[234:235], v[132:133], v[230:231], v[234:235]
	v_pk_fma_f32 v[236:237], v[44:45], v[232:233], v[236:237]
	v_cvt_scalef32_pk_f32_fp4 v[196:197], v63, 1.0
	v_cvt_scalef32_pk_f32_fp4 v[198:199], v63, 1.0 op_sel:[1,0,0]
	v_cvt_scalef32_pk_f32_fp4 v[230:231], v63, 1.0 op_sel:[0,1,0]
	v_cvt_scalef32_pk_f32_fp4 v[232:233], v63, 1.0 op_sel:[1,1,0]
	v_pk_fma_f32 v[234:235], v[134:135], v[196:197], v[234:235]
	v_pk_fma_f32 v[236:237], v[34:35], v[198:199], v[236:237]
	v_pk_fma_f32 v[234:235], v[136:137], v[230:231], v[234:235]
	v_pk_fma_f32 v[236:237], v[36:37], v[232:233], v[236:237]
	v_cvt_scalef32_pk_f32_fp4 v[196:197], v64, 1.0
	v_cvt_scalef32_pk_f32_fp4 v[198:199], v64, 1.0 op_sel:[1,0,0]
	v_cvt_scalef32_pk_f32_fp4 v[230:231], v64, 1.0 op_sel:[0,1,0]
	v_cvt_scalef32_pk_f32_fp4 v[232:233], v64, 1.0 op_sel:[1,1,0]
	v_pk_fma_f32 v[234:235], v[138:139], v[196:197], v[234:235]
	v_pk_fma_f32 v[236:237], v[140:141], v[198:199], v[236:237]
	v_pk_fma_f32 v[234:235], v[142:143], v[230:231], v[234:235]
	v_pk_fma_f32 v[236:237], v[144:145], v[232:233], v[236:237]
	v_cvt_scalef32_pk_f32_fp4 v[196:197], v65, 1.0
	v_cvt_scalef32_pk_f32_fp4 v[198:199], v65, 1.0 op_sel:[1,0,0]
	v_cvt_scalef32_pk_f32_fp4 v[230:231], v65, 1.0 op_sel:[0,1,0]
	v_cvt_scalef32_pk_f32_fp4 v[232:233], v65, 1.0 op_sel:[1,1,0]
	v_pk_fma_f32 v[234:235], v[146:147], v[196:197], v[234:235]
	v_pk_fma_f32 v[236:237], v[148:149], v[198:199], v[236:237]
	v_pk_fma_f32 v[234:235], v[150:151], v[230:231], v[234:235]
	v_pk_fma_f32 v[236:237], v[152:153], v[232:233], v[236:237]
	v_add_f32_e32 v239, v236, v237
	v_add_f32_e32 v242, v234, v235
	v_add_f32_e32 v239, v242, v239
	s_nop 0
	v_add_f32_dpp v239, v239, v239 quad_perm:[1,0,3,2] row_mask:0xf bank_mask:0xf bound_ctrl:1
	s_nop 1
	v_add_f32_dpp v239, v239, v239 quad_perm:[2,3,0,1] row_mask:0xf bank_mask:0xf bound_ctrl:1
	s_nop 1
	v_add_f32_dpp v239, v239, v239 row_half_mirror row_mask:0xf bank_mask:0xf bound_ctrl:1
	s_nop 1
	v_add_f32_dpp v239, v239, v239 row_mirror row_mask:0xf bank_mask:0xf bound_ctrl:1
	ds_write_b32 v244, v239 offset:16
	s_waitcnt lgkmcnt(0)
	ds_read_b32 v241, v227 offset:96
	s_waitcnt vmcnt(5)
	v_mad_u64_u32 v[242:243], s[6:7], v240, s0, v[84:85]
	global_load_dwordx4 v[74:77], v[242:243], off
	global_load_dwordx4 v[62:65], v[242:243], off offset:256
	v_cvt_scalef32_pk_f32_fp4 v[196:197], v78, 1.0
	v_cvt_scalef32_pk_f32_fp4 v[198:199], v78, 1.0 op_sel:[1,0,0]
	v_cvt_scalef32_pk_f32_fp4 v[230:231], v78, 1.0 op_sel:[0,1,0]
	v_cvt_scalef32_pk_f32_fp4 v[232:233], v78, 1.0 op_sel:[1,1,0]
	v_pk_fma_f32 v[234:235], v[112:113], v[196:197], 0 op_sel_hi:[1,1,0]
	v_pk_fma_f32 v[236:237], v[54:55], v[198:199], 0 op_sel_hi:[1,1,0]
	v_pk_fma_f32 v[234:235], v[114:115], v[230:231], v[234:235]
	v_pk_fma_f32 v[236:237], v[56:57], v[232:233], v[236:237]
	v_cvt_scalef32_pk_f32_fp4 v[196:197], v79, 1.0
	v_cvt_scalef32_pk_f32_fp4 v[198:199], v79, 1.0 op_sel:[1,0,0]
	v_cvt_scalef32_pk_f32_fp4 v[230:231], v79, 1.0 op_sel:[0,1,0]
	v_cvt_scalef32_pk_f32_fp4 v[232:233], v79, 1.0 op_sel:[1,1,0]
	v_pk_fma_f32 v[234:235], v[116:117], v[196:197], v[234:235]
	v_pk_fma_f32 v[236:237], v[50:51], v[198:199], v[236:237]
	v_pk_fma_f32 v[234:235], v[118:119], v[230:231], v[234:235]
	v_pk_fma_f32 v[236:237], v[52:53], v[232:233], v[236:237]
	v_cvt_scalef32_pk_f32_fp4 v[196:197], v80, 1.0
	v_cvt_scalef32_pk_f32_fp4 v[198:199], v80, 1.0 op_sel:[1,0,0]
	v_cvt_scalef32_pk_f32_fp4 v[230:231], v80, 1.0 op_sel:[0,1,0]
	v_cvt_scalef32_pk_f32_fp4 v[232:233], v80, 1.0 op_sel:[1,1,0]
	v_pk_fma_f32 v[234:235], v[120:121], v[196:197], v[234:235]
	v_pk_fma_f32 v[236:237], v[46:47], v[198:199], v[236:237]
	v_pk_fma_f32 v[234:235], v[122:123], v[230:231], v[234:235]
	v_pk_fma_f32 v[236:237], v[48:49], v[232:233], v[236:237]
	v_cvt_scalef32_pk_f32_fp4 v[196:197], v81, 1.0
	v_cvt_scalef32_pk_f32_fp4 v[198:199], v81, 1.0 op_sel:[1,0,0]
	v_cvt_scalef32_pk_f32_fp4 v[230:231], v81, 1.0 op_sel:[0,1,0]
	v_cvt_scalef32_pk_f32_fp4 v[232:233], v81, 1.0 op_sel:[1,1,0]
	v_pk_fma_f32 v[234:235], v[126:127], v[196:197], v[234:235]
	v_pk_fma_f32 v[236:237], v[38:39], v[198:199], v[236:237]
	v_pk_fma_f32 v[234:235], v[128:129], v[230:231], v[234:235]
	v_pk_fma_f32 v[236:237], v[40:41], v[232:233], v[236:237]
	s_waitcnt vmcnt(6)
	v_cvt_scalef32_pk_f32_fp4 v[196:197], v70, 1.0
	v_cvt_scalef32_pk_f32_fp4 v[198:199], v70, 1.0 op_sel:[1,0,0]
	v_cvt_scalef32_pk_f32_fp4 v[230:231], v70, 1.0 op_sel:[0,1,0]
	v_cvt_scalef32_pk_f32_fp4 v[232:233], v70, 1.0 op_sel:[1,1,0]
	v_pk_fma_f32 v[234:235], v[130:131], v[196:197], v[234:235]
	v_pk_fma_f32 v[236:237], v[42:43], v[198:199], v[236:237]
	v_pk_fma_f32 v[234:235], v[132:133], v[230:231], v[234:235]
	v_pk_fma_f32 v[236:237], v[44:45], v[232:233], v[236:237]
	v_cvt_scalef32_pk_f32_fp4 v[196:197], v71, 1.0
	v_cvt_scalef32_pk_f32_fp4 v[198:199], v71, 1.0 op_sel:[1,0,0]
	v_cvt_scalef32_pk_f32_fp4 v[230:231], v71, 1.0 op_sel:[0,1,0]
	v_cvt_scalef32_pk_f32_fp4 v[232:233], v71, 1.0 op_sel:[1,1,0]
	v_pk_fma_f32 v[234:235], v[134:135], v[196:197], v[234:235]
	v_pk_fma_f32 v[236:237], v[34:35], v[198:199], v[236:237]
	v_pk_fma_f32 v[234:235], v[136:137], v[230:231], v[234:235]
	v_pk_fma_f32 v[236:237], v[36:37], v[232:233], v[236:237]
	v_cvt_scalef32_pk_f32_fp4 v[196:197], v72, 1.0
	v_cvt_scalef32_pk_f32_fp4 v[198:199], v72, 1.0 op_sel:[1,0,0]
	v_cvt_scalef32_pk_f32_fp4 v[230:231], v72, 1.0 op_sel:[0,1,0]
	v_cvt_scalef32_pk_f32_fp4 v[232:233], v72, 1.0 op_sel:[1,1,0]
	v_pk_fma_f32 v[234:235], v[138:139], v[196:197], v[234:235]
	v_pk_fma_f32 v[236:237], v[140:141], v[198:199], v[236:237]
	v_pk_fma_f32 v[234:235], v[142:143], v[230:231], v[234:235]
	v_pk_fma_f32 v[236:237], v[144:145], v[232:233], v[236:237]
	v_cvt_scalef32_pk_f32_fp4 v[196:197], v73, 1.0
	v_cvt_scalef32_pk_f32_fp4 v[198:199], v73, 1.0 op_sel:[1,0,0]
	v_cvt_scalef32_pk_f32_fp4 v[230:231], v73, 1.0 op_sel:[0,1,0]
	v_cvt_scalef32_pk_f32_fp4 v[232:233], v73, 1.0 op_sel:[1,1,0]
	v_pk_fma_f32 v[234:235], v[146:147], v[196:197], v[234:235]
	v_pk_fma_f32 v[236:237], v[148:149], v[198:199], v[236:237]
	v_pk_fma_f32 v[234:235], v[150:151], v[230:231], v[234:235]
	v_pk_fma_f32 v[236:237], v[152:153], v[232:233], v[236:237]
	v_add_f32_e32 v238, v236, v237
	v_add_f32_e32 v242, v234, v235
	v_add_f32_e32 v238, v242, v238
	s_nop 0
	v_add_f32_dpp v238, v238, v238 quad_perm:[1,0,3,2] row_mask:0xf bank_mask:0xf bound_ctrl:1
	s_nop 1
	v_add_f32_dpp v238, v238, v238 quad_perm:[2,3,0,1] row_mask:0xf bank_mask:0xf bound_ctrl:1
	s_nop 1
	v_add_f32_dpp v238, v238, v238 row_half_mirror row_mask:0xf bank_mask:0xf bound_ctrl:1
	s_nop 1
	v_add_f32_dpp v238, v238, v238 row_mirror row_mask:0xf bank_mask:0xf bound_ctrl:1
	ds_write_b32 v244, v238 offset:32
	s_waitcnt lgkmcnt(0)
	ds_read_b32 v240, v227 offset:112
	s_waitcnt vmcnt(5)
	v_mad_u64_u32 v[242:243], s[6:7], v241, s0, v[84:85]
	global_load_dwordx4 v[78:81], v[242:243], off
	global_load_dwordx4 v[70:73], v[242:243], off offset:256
	v_cvt_scalef32_pk_f32_fp4 v[196:197], v30, 1.0
	v_cvt_scalef32_pk_f32_fp4 v[198:199], v30, 1.0 op_sel:[1,0,0]
	v_cvt_scalef32_pk_f32_fp4 v[230:231], v30, 1.0 op_sel:[0,1,0]
	v_cvt_scalef32_pk_f32_fp4 v[232:233], v30, 1.0 op_sel:[1,1,0]
	v_pk_fma_f32 v[234:235], v[112:113], v[196:197], 0 op_sel_hi:[1,1,0]
	v_pk_fma_f32 v[236:237], v[54:55], v[198:199], 0 op_sel_hi:[1,1,0]
	v_pk_fma_f32 v[234:235], v[114:115], v[230:231], v[234:235]
	v_pk_fma_f32 v[236:237], v[56:57], v[232:233], v[236:237]
	v_cvt_scalef32_pk_f32_fp4 v[196:197], v31, 1.0
	v_cvt_scalef32_pk_f32_fp4 v[198:199], v31, 1.0 op_sel:[1,0,0]
	v_cvt_scalef32_pk_f32_fp4 v[230:231], v31, 1.0 op_sel:[0,1,0]
	v_cvt_scalef32_pk_f32_fp4 v[232:233], v31, 1.0 op_sel:[1,1,0]
	v_pk_fma_f32 v[234:235], v[116:117], v[196:197], v[234:235]
	v_pk_fma_f32 v[236:237], v[50:51], v[198:199], v[236:237]
	v_pk_fma_f32 v[234:235], v[118:119], v[230:231], v[234:235]
	v_pk_fma_f32 v[236:237], v[52:53], v[232:233], v[236:237]
	v_cvt_scalef32_pk_f32_fp4 v[196:197], v32, 1.0
	v_cvt_scalef32_pk_f32_fp4 v[198:199], v32, 1.0 op_sel:[1,0,0]
	v_cvt_scalef32_pk_f32_fp4 v[230:231], v32, 1.0 op_sel:[0,1,0]
	v_cvt_scalef32_pk_f32_fp4 v[232:233], v32, 1.0 op_sel:[1,1,0]
	v_pk_fma_f32 v[234:235], v[120:121], v[196:197], v[234:235]
	v_pk_fma_f32 v[236:237], v[46:47], v[198:199], v[236:237]
	v_pk_fma_f32 v[234:235], v[122:123], v[230:231], v[234:235]
	v_pk_fma_f32 v[236:237], v[48:49], v[232:233], v[236:237]
	v_cvt_scalef32_pk_f32_fp4 v[196:197], v33, 1.0
	v_cvt_scalef32_pk_f32_fp4 v[198:199], v33, 1.0 op_sel:[1,0,0]
	v_cvt_scalef32_pk_f32_fp4 v[230:231], v33, 1.0 op_sel:[0,1,0]
	v_cvt_scalef32_pk_f32_fp4 v[232:233], v33, 1.0 op_sel:[1,1,0]
	v_pk_fma_f32 v[234:235], v[126:127], v[196:197], v[234:235]
	v_pk_fma_f32 v[236:237], v[38:39], v[198:199], v[236:237]
	v_pk_fma_f32 v[234:235], v[128:129], v[230:231], v[234:235]
	v_pk_fma_f32 v[236:237], v[40:41], v[232:233], v[236:237]
	s_waitcnt vmcnt(6)
	v_cvt_scalef32_pk_f32_fp4 v[196:197], v26, 1.0
	v_cvt_scalef32_pk_f32_fp4 v[198:199], v26, 1.0 op_sel:[1,0,0]
	v_cvt_scalef32_pk_f32_fp4 v[230:231], v26, 1.0 op_sel:[0,1,0]
	v_cvt_scalef32_pk_f32_fp4 v[232:233], v26, 1.0 op_sel:[1,1,0]
	v_pk_fma_f32 v[234:235], v[130:131], v[196:197], v[234:235]
	v_pk_fma_f32 v[236:237], v[42:43], v[198:199], v[236:237]
	v_pk_fma_f32 v[234:235], v[132:133], v[230:231], v[234:235]
	v_pk_fma_f32 v[236:237], v[44:45], v[232:233], v[236:237]
	v_cvt_scalef32_pk_f32_fp4 v[196:197], v27, 1.0
	v_cvt_scalef32_pk_f32_fp4 v[198:199], v27, 1.0 op_sel:[1,0,0]
	v_cvt_scalef32_pk_f32_fp4 v[230:231], v27, 1.0 op_sel:[0,1,0]
	v_cvt_scalef32_pk_f32_fp4 v[232:233], v27, 1.0 op_sel:[1,1,0]
	v_pk_fma_f32 v[234:235], v[134:135], v[196:197], v[234:235]
	v_pk_fma_f32 v[236:237], v[34:35], v[198:199], v[236:237]
	v_pk_fma_f32 v[234:235], v[136:137], v[230:231], v[234:235]
	v_pk_fma_f32 v[236:237], v[36:37], v[232:233], v[236:237]
	v_cvt_scalef32_pk_f32_fp4 v[196:197], v28, 1.0
	v_cvt_scalef32_pk_f32_fp4 v[198:199], v28, 1.0 op_sel:[1,0,0]
	v_cvt_scalef32_pk_f32_fp4 v[230:231], v28, 1.0 op_sel:[0,1,0]
	v_cvt_scalef32_pk_f32_fp4 v[232:233], v28, 1.0 op_sel:[1,1,0]
	v_pk_fma_f32 v[234:235], v[138:139], v[196:197], v[234:235]
	v_pk_fma_f32 v[236:237], v[140:141], v[198:199], v[236:237]
	v_pk_fma_f32 v[234:235], v[142:143], v[230:231], v[234:235]
	v_pk_fma_f32 v[236:237], v[144:145], v[232:233], v[236:237]
	v_cvt_scalef32_pk_f32_fp4 v[196:197], v29, 1.0
	v_cvt_scalef32_pk_f32_fp4 v[198:199], v29, 1.0 op_sel:[1,0,0]
	v_cvt_scalef32_pk_f32_fp4 v[230:231], v29, 1.0 op_sel:[0,1,0]
	v_cvt_scalef32_pk_f32_fp4 v[232:233], v29, 1.0 op_sel:[1,1,0]
	v_pk_fma_f32 v[234:235], v[146:147], v[196:197], v[234:235]
	v_pk_fma_f32 v[236:237], v[148:149], v[198:199], v[236:237]
	v_pk_fma_f32 v[234:235], v[150:151], v[230:231], v[234:235]
	v_pk_fma_f32 v[236:237], v[152:153], v[232:233], v[236:237]
	v_add_f32_e32 v239, v236, v237
	v_add_f32_e32 v242, v234, v235
	v_add_f32_e32 v239, v242, v239
	s_nop 0
	v_add_f32_dpp v239, v239, v239 quad_perm:[1,0,3,2] row_mask:0xf bank_mask:0xf bound_ctrl:1
	s_nop 1
	v_add_f32_dpp v239, v239, v239 quad_perm:[2,3,0,1] row_mask:0xf bank_mask:0xf bound_ctrl:1
	s_nop 1
	v_add_f32_dpp v239, v239, v239 row_half_mirror row_mask:0xf bank_mask:0xf bound_ctrl:1
	s_nop 1
	v_add_f32_dpp v239, v239, v239 row_mirror row_mask:0xf bank_mask:0xf bound_ctrl:1
	ds_write_b32 v244, v239 offset:48
	s_waitcnt lgkmcnt(0)
	ds_read_b32 v241, v227 offset:128
	s_waitcnt vmcnt(5)
	v_mad_u64_u32 v[242:243], s[6:7], v240, s0, v[84:85]
	global_load_dwordx4 v[30:33], v[242:243], off
	global_load_dwordx4 v[26:29], v[242:243], off offset:256
	v_cvt_scalef32_pk_f32_fp4 v[196:197], v66, 1.0
	v_cvt_scalef32_pk_f32_fp4 v[198:199], v66, 1.0 op_sel:[1,0,0]
	v_cvt_scalef32_pk_f32_fp4 v[230:231], v66, 1.0 op_sel:[0,1,0]
	v_cvt_scalef32_pk_f32_fp4 v[232:233], v66, 1.0 op_sel:[1,1,0]
	v_pk_fma_f32 v[234:235], v[112:113], v[196:197], 0 op_sel_hi:[1,1,0]
	v_pk_fma_f32 v[236:237], v[54:55], v[198:199], 0 op_sel_hi:[1,1,0]
	v_pk_fma_f32 v[234:235], v[114:115], v[230:231], v[234:235]
	v_pk_fma_f32 v[236:237], v[56:57], v[232:233], v[236:237]
	v_cvt_scalef32_pk_f32_fp4 v[196:197], v67, 1.0
	v_cvt_scalef32_pk_f32_fp4 v[198:199], v67, 1.0 op_sel:[1,0,0]
	v_cvt_scalef32_pk_f32_fp4 v[230:231], v67, 1.0 op_sel:[0,1,0]
	v_cvt_scalef32_pk_f32_fp4 v[232:233], v67, 1.0 op_sel:[1,1,0]
	v_pk_fma_f32 v[234:235], v[116:117], v[196:197], v[234:235]
	v_pk_fma_f32 v[236:237], v[50:51], v[198:199], v[236:237]
	v_pk_fma_f32 v[234:235], v[118:119], v[230:231], v[234:235]
	v_pk_fma_f32 v[236:237], v[52:53], v[232:233], v[236:237]
	v_cvt_scalef32_pk_f32_fp4 v[196:197], v68, 1.0
	v_cvt_scalef32_pk_f32_fp4 v[198:199], v68, 1.0 op_sel:[1,0,0]
	v_cvt_scalef32_pk_f32_fp4 v[230:231], v68, 1.0 op_sel:[0,1,0]
	v_cvt_scalef32_pk_f32_fp4 v[232:233], v68, 1.0 op_sel:[1,1,0]
	v_pk_fma_f32 v[234:235], v[120:121], v[196:197], v[234:235]
	v_pk_fma_f32 v[236:237], v[46:47], v[198:199], v[236:237]
	v_pk_fma_f32 v[234:235], v[122:123], v[230:231], v[234:235]
	v_pk_fma_f32 v[236:237], v[48:49], v[232:233], v[236:237]
	v_cvt_scalef32_pk_f32_fp4 v[196:197], v69, 1.0
	v_cvt_scalef32_pk_f32_fp4 v[198:199], v69, 1.0 op_sel:[1,0,0]
	v_cvt_scalef32_pk_f32_fp4 v[230:231], v69, 1.0 op_sel:[0,1,0]
	v_cvt_scalef32_pk_f32_fp4 v[232:233], v69, 1.0 op_sel:[1,1,0]
	v_pk_fma_f32 v[234:235], v[126:127], v[196:197], v[234:235]
	v_pk_fma_f32 v[236:237], v[38:39], v[198:199], v[236:237]
	v_pk_fma_f32 v[234:235], v[128:129], v[230:231], v[234:235]
	v_pk_fma_f32 v[236:237], v[40:41], v[232:233], v[236:237]
	s_waitcnt vmcnt(6)
	v_cvt_scalef32_pk_f32_fp4 v[196:197], v58, 1.0
	v_cvt_scalef32_pk_f32_fp4 v[198:199], v58, 1.0 op_sel:[1,0,0]
	v_cvt_scalef32_pk_f32_fp4 v[230:231], v58, 1.0 op_sel:[0,1,0]
	v_cvt_scalef32_pk_f32_fp4 v[232:233], v58, 1.0 op_sel:[1,1,0]
	v_pk_fma_f32 v[234:235], v[130:131], v[196:197], v[234:235]
	v_pk_fma_f32 v[236:237], v[42:43], v[198:199], v[236:237]
	v_pk_fma_f32 v[234:235], v[132:133], v[230:231], v[234:235]
	v_pk_fma_f32 v[236:237], v[44:45], v[232:233], v[236:237]
	v_cvt_scalef32_pk_f32_fp4 v[196:197], v59, 1.0
	v_cvt_scalef32_pk_f32_fp4 v[198:199], v59, 1.0 op_sel:[1,0,0]
	v_cvt_scalef32_pk_f32_fp4 v[230:231], v59, 1.0 op_sel:[0,1,0]
	v_cvt_scalef32_pk_f32_fp4 v[232:233], v59, 1.0 op_sel:[1,1,0]
	v_pk_fma_f32 v[234:235], v[134:135], v[196:197], v[234:235]
	v_pk_fma_f32 v[236:237], v[34:35], v[198:199], v[236:237]
	v_pk_fma_f32 v[234:235], v[136:137], v[230:231], v[234:235]
	v_pk_fma_f32 v[236:237], v[36:37], v[232:233], v[236:237]
	v_cvt_scalef32_pk_f32_fp4 v[196:197], v60, 1.0
	v_cvt_scalef32_pk_f32_fp4 v[198:199], v60, 1.0 op_sel:[1,0,0]
	v_cvt_scalef32_pk_f32_fp4 v[230:231], v60, 1.0 op_sel:[0,1,0]
	v_cvt_scalef32_pk_f32_fp4 v[232:233], v60, 1.0 op_sel:[1,1,0]
	v_pk_fma_f32 v[234:235], v[138:139], v[196:197], v[234:235]
	v_pk_fma_f32 v[236:237], v[140:141], v[198:199], v[236:237]
	v_pk_fma_f32 v[234:235], v[142:143], v[230:231], v[234:235]
	v_pk_fma_f32 v[236:237], v[144:145], v[232:233], v[236:237]
	v_cvt_scalef32_pk_f32_fp4 v[196:197], v61, 1.0
	v_cvt_scalef32_pk_f32_fp4 v[198:199], v61, 1.0 op_sel:[1,0,0]
	v_cvt_scalef32_pk_f32_fp4 v[230:231], v61, 1.0 op_sel:[0,1,0]
	v_cvt_scalef32_pk_f32_fp4 v[232:233], v61, 1.0 op_sel:[1,1,0]
	v_pk_fma_f32 v[234:235], v[146:147], v[196:197], v[234:235]
	v_pk_fma_f32 v[236:237], v[148:149], v[198:199], v[236:237]
	v_pk_fma_f32 v[234:235], v[150:151], v[230:231], v[234:235]
	v_pk_fma_f32 v[236:237], v[152:153], v[232:233], v[236:237]
	v_add_f32_e32 v238, v236, v237
	v_add_f32_e32 v242, v234, v235
	v_add_f32_e32 v238, v242, v238
	s_nop 0
	v_add_f32_dpp v238, v238, v238 quad_perm:[1,0,3,2] row_mask:0xf bank_mask:0xf bound_ctrl:1
	s_nop 1
	v_add_f32_dpp v238, v238, v238 quad_perm:[2,3,0,1] row_mask:0xf bank_mask:0xf bound_ctrl:1
	s_nop 1
	v_add_f32_dpp v238, v238, v238 row_half_mirror row_mask:0xf bank_mask:0xf bound_ctrl:1
	s_nop 1
	v_add_f32_dpp v238, v238, v238 row_mirror row_mask:0xf bank_mask:0xf bound_ctrl:1
	ds_write_b32 v244, v238 offset:64
	s_waitcnt lgkmcnt(0)
	s_add_i32 s2, s2, 1
	v_add_u32_e32 v227, 64, v227
	v_add_u32_e32 v244, 64, v244
	s_cmp_lt_u32 s2, 6
	s_cbranch_scc1 .Lpu_loop
	ds_read_b32 v240, v227 offset:80
	s_waitcnt vmcnt(5)
	v_mad_u64_u32 v[242:243], s[6:7], v241, s0, v[84:85]
	global_load_dwordx4 v[66:69], v[242:243], off
	global_load_dwordx4 v[58:61], v[242:243], off offset:256
	v_cvt_scalef32_pk_f32_fp4 v[196:197], v74, 1.0
	v_cvt_scalef32_pk_f32_fp4 v[198:199], v74, 1.0 op_sel:[1,0,0]
	v_cvt_scalef32_pk_f32_fp4 v[230:231], v74, 1.0 op_sel:[0,1,0]
	v_cvt_scalef32_pk_f32_fp4 v[232:233], v74, 1.0 op_sel:[1,1,0]
	v_pk_fma_f32 v[234:235], v[112:113], v[196:197], 0 op_sel_hi:[1,1,0]
	v_pk_fma_f32 v[236:237], v[54:55], v[198:199], 0 op_sel_hi:[1,1,0]
	v_pk_fma_f32 v[234:235], v[114:115], v[230:231], v[234:235]
	v_pk_fma_f32 v[236:237], v[56:57], v[232:233], v[236:237]
	v_cvt_scalef32_pk_f32_fp4 v[196:197], v75, 1.0
	v_cvt_scalef32_pk_f32_fp4 v[198:199], v75, 1.0 op_sel:[1,0,0]
	v_cvt_scalef32_pk_f32_fp4 v[230:231], v75, 1.0 op_sel:[0,1,0]
	v_cvt_scalef32_pk_f32_fp4 v[232:233], v75, 1.0 op_sel:[1,1,0]
	v_pk_fma_f32 v[234:235], v[116:117], v[196:197], v[234:235]
	v_pk_fma_f32 v[236:237], v[50:51], v[198:199], v[236:237]
	v_pk_fma_f32 v[234:235], v[118:119], v[230:231], v[234:235]
	v_pk_fma_f32 v[236:237], v[52:53], v[232:233], v[236:237]
	v_cvt_scalef32_pk_f32_fp4 v[196:197], v76, 1.0
	v_cvt_scalef32_pk_f32_fp4 v[198:199], v76, 1.0 op_sel:[1,0,0]
	v_cvt_scalef32_pk_f32_fp4 v[230:231], v76, 1.0 op_sel:[0,1,0]
	v_cvt_scalef32_pk_f32_fp4 v[232:233], v76, 1.0 op_sel:[1,1,0]
	v_pk_fma_f32 v[234:235], v[120:121], v[196:197], v[234:235]
	v_pk_fma_f32 v[236:237], v[46:47], v[198:199], v[236:237]
	v_pk_fma_f32 v[234:235], v[122:123], v[230:231], v[234:235]
	v_pk_fma_f32 v[236:237], v[48:49], v[232:233], v[236:237]
	v_cvt_scalef32_pk_f32_fp4 v[196:197], v77, 1.0
	v_cvt_scalef32_pk_f32_fp4 v[198:199], v77, 1.0 op_sel:[1,0,0]
	v_cvt_scalef32_pk_f32_fp4 v[230:231], v77, 1.0 op_sel:[0,1,0]
	v_cvt_scalef32_pk_f32_fp4 v[232:233], v77, 1.0 op_sel:[1,1,0]
	v_pk_fma_f32 v[234:235], v[126:127], v[196:197], v[234:235]
	v_pk_fma_f32 v[236:237], v[38:39], v[198:199], v[236:237]
	v_pk_fma_f32 v[234:235], v[128:129], v[230:231], v[234:235]
	v_pk_fma_f32 v[236:237], v[40:41], v[232:233], v[236:237]
	s_waitcnt vmcnt(6)
	v_cvt_scalef32_pk_f32_fp4 v[196:197], v62, 1.0
	v_cvt_scalef32_pk_f32_fp4 v[198:199], v62, 1.0 op_sel:[1,0,0]
	v_cvt_scalef32_pk_f32_fp4 v[230:231], v62, 1.0 op_sel:[0,1,0]
	v_cvt_scalef32_pk_f32_fp4 v[232:233], v62, 1.0 op_sel:[1,1,0]
	v_pk_fma_f32 v[234:235], v[130:131], v[196:197], v[234:235]
	v_pk_fma_f32 v[236:237], v[42:43], v[198:199], v[236:237]
	v_pk_fma_f32 v[234:235], v[132:133], v[230:231], v[234:235]
	v_pk_fma_f32 v[236:237], v[44:45], v[232:233], v[236:237]
	v_cvt_scalef32_pk_f32_fp4 v[196:197], v63, 1.0
	v_cvt_scalef32_pk_f32_fp4 v[198:199], v63, 1.0 op_sel:[1,0,0]
	v_cvt_scalef32_pk_f32_fp4 v[230:231], v63, 1.0 op_sel:[0,1,0]
	v_cvt_scalef32_pk_f32_fp4 v[232:233], v63, 1.0 op_sel:[1,1,0]
	v_pk_fma_f32 v[234:235], v[134:135], v[196:197], v[234:235]
	v_pk_fma_f32 v[236:237], v[34:35], v[198:199], v[236:237]
	v_pk_fma_f32 v[234:235], v[136:137], v[230:231], v[234:235]
	v_pk_fma_f32 v[236:237], v[36:37], v[232:233], v[236:237]
	v_cvt_scalef32_pk_f32_fp4 v[196:197], v64, 1.0
	v_cvt_scalef32_pk_f32_fp4 v[198:199], v64, 1.0 op_sel:[1,0,0]
	v_cvt_scalef32_pk_f32_fp4 v[230:231], v64, 1.0 op_sel:[0,1,0]
	v_cvt_scalef32_pk_f32_fp4 v[232:233], v64, 1.0 op_sel:[1,1,0]
	v_pk_fma_f32 v[234:235], v[138:139], v[196:197], v[234:235]
	v_pk_fma_f32 v[236:237], v[140:141], v[198:199], v[236:237]
	v_pk_fma_f32 v[234:235], v[142:143], v[230:231], v[234:235]
	v_pk_fma_f32 v[236:237], v[144:145], v[232:233], v[236:237]
	v_cvt_scalef32_pk_f32_fp4 v[196:197], v65, 1.0
	v_cvt_scalef32_pk_f32_fp4 v[198:199], v65, 1.0 op_sel:[1,0,0]
	v_cvt_scalef32_pk_f32_fp4 v[230:231], v65, 1.0 op_sel:[0,1,0]
	v_cvt_scalef32_pk_f32_fp4 v[232:233], v65, 1.0 op_sel:[1,1,0]
	v_pk_fma_f32 v[234:235], v[146:147], v[196:197], v[234:235]
	v_pk_fma_f32 v[236:237], v[148:149], v[198:199], v[236:237]
	v_pk_fma_f32 v[234:235], v[150:151], v[230:231], v[234:235]
	v_pk_fma_f32 v[236:237], v[152:153], v[232:233], v[236:237]
	v_add_f32_e32 v239, v236, v237
	v_add_f32_e32 v242, v234, v235
	v_add_f32_e32 v239, v242, v239
	s_nop 0
	v_add_f32_dpp v239, v239, v239 quad_perm:[1,0,3,2] row_mask:0xf bank_mask:0xf bound_ctrl:1
	s_nop 1
	v_add_f32_dpp v239, v239, v239 quad_perm:[2,3,0,1] row_mask:0xf bank_mask:0xf bound_ctrl:1
	s_nop 1
	v_add_f32_dpp v239, v239, v239 row_half_mirror row_mask:0xf bank_mask:0xf bound_ctrl:1
	s_nop 1
	v_add_f32_dpp v239, v239, v239 row_mirror row_mask:0xf bank_mask:0xf bound_ctrl:1
	ds_write_b32 v244, v239 offset:16
	s_waitcnt lgkmcnt(0)
	ds_read_b32 v241, v227 offset:96
	s_waitcnt vmcnt(5)
	v_mad_u64_u32 v[242:243], s[6:7], v240, s0, v[84:85]
	global_load_dwordx4 v[74:77], v[242:243], off
	global_load_dwordx4 v[62:65], v[242:243], off offset:256
	v_cvt_scalef32_pk_f32_fp4 v[196:197], v78, 1.0
	v_cvt_scalef32_pk_f32_fp4 v[198:199], v78, 1.0 op_sel:[1,0,0]
	v_cvt_scalef32_pk_f32_fp4 v[230:231], v78, 1.0 op_sel:[0,1,0]
	v_cvt_scalef32_pk_f32_fp4 v[232:233], v78, 1.0 op_sel:[1,1,0]
	v_pk_fma_f32 v[234:235], v[112:113], v[196:197], 0 op_sel_hi:[1,1,0]
	v_pk_fma_f32 v[236:237], v[54:55], v[198:199], 0 op_sel_hi:[1,1,0]
	v_pk_fma_f32 v[234:235], v[114:115], v[230:231], v[234:235]
	v_pk_fma_f32 v[236:237], v[56:57], v[232:233], v[236:237]
	v_cvt_scalef32_pk_f32_fp4 v[196:197], v79, 1.0
	v_cvt_scalef32_pk_f32_fp4 v[198:199], v79, 1.0 op_sel:[1,0,0]
	v_cvt_scalef32_pk_f32_fp4 v[230:231], v79, 1.0 op_sel:[0,1,0]
	v_cvt_scalef32_pk_f32_fp4 v[232:233], v79, 1.0 op_sel:[1,1,0]
	v_pk_fma_f32 v[234:235], v[116:117], v[196:197], v[234:235]
	v_pk_fma_f32 v[236:237], v[50:51], v[198:199], v[236:237]
	v_pk_fma_f32 v[234:235], v[118:119], v[230:231], v[234:235]
	v_pk_fma_f32 v[236:237], v[52:53], v[232:233], v[236:237]
	v_cvt_scalef32_pk_f32_fp4 v[196:197], v80, 1.0
	v_cvt_scalef32_pk_f32_fp4 v[198:199], v80, 1.0 op_sel:[1,0,0]
	v_cvt_scalef32_pk_f32_fp4 v[230:231], v80, 1.0 op_sel:[0,1,0]
	v_cvt_scalef32_pk_f32_fp4 v[232:233], v80, 1.0 op_sel:[1,1,0]
	v_pk_fma_f32 v[234:235], v[120:121], v[196:197], v[234:235]
	v_pk_fma_f32 v[236:237], v[46:47], v[198:199], v[236:237]
	v_pk_fma_f32 v[234:235], v[122:123], v[230:231], v[234:235]
	v_pk_fma_f32 v[236:237], v[48:49], v[232:233], v[236:237]
	v_cvt_scalef32_pk_f32_fp4 v[196:197], v81, 1.0
	v_cvt_scalef32_pk_f32_fp4 v[198:199], v81, 1.0 op_sel:[1,0,0]
	v_cvt_scalef32_pk_f32_fp4 v[230:231], v81, 1.0 op_sel:[0,1,0]
	v_cvt_scalef32_pk_f32_fp4 v[232:233], v81, 1.0 op_sel:[1,1,0]
	v_pk_fma_f32 v[234:235], v[126:127], v[196:197], v[234:235]
	v_pk_fma_f32 v[236:237], v[38:39], v[198:199], v[236:237]
	v_pk_fma_f32 v[234:235], v[128:129], v[230:231], v[234:235]
	v_pk_fma_f32 v[236:237], v[40:41], v[232:233], v[236:237]
	s_waitcnt vmcnt(6)
	v_cvt_scalef32_pk_f32_fp4 v[196:197], v70, 1.0
	v_cvt_scalef32_pk_f32_fp4 v[198:199], v70, 1.0 op_sel:[1,0,0]
	v_cvt_scalef32_pk_f32_fp4 v[230:231], v70, 1.0 op_sel:[0,1,0]
	v_cvt_scalef32_pk_f32_fp4 v[232:233], v70, 1.0 op_sel:[1,1,0]
	v_pk_fma_f32 v[234:235], v[130:131], v[196:197], v[234:235]
	v_pk_fma_f32 v[236:237], v[42:43], v[198:199], v[236:237]
	v_pk_fma_f32 v[234:235], v[132:133], v[230:231], v[234:235]
	v_pk_fma_f32 v[236:237], v[44:45], v[232:233], v[236:237]
	v_cvt_scalef32_pk_f32_fp4 v[196:197], v71, 1.0
	v_cvt_scalef32_pk_f32_fp4 v[198:199], v71, 1.0 op_sel:[1,0,0]
	v_cvt_scalef32_pk_f32_fp4 v[230:231], v71, 1.0 op_sel:[0,1,0]
	v_cvt_scalef32_pk_f32_fp4 v[232:233], v71, 1.0 op_sel:[1,1,0]
	v_pk_fma_f32 v[234:235], v[134:135], v[196:197], v[234:235]
	v_pk_fma_f32 v[236:237], v[34:35], v[198:199], v[236:237]
	v_pk_fma_f32 v[234:235], v[136:137], v[230:231], v[234:235]
	v_pk_fma_f32 v[236:237], v[36:37], v[232:233], v[236:237]
	v_cvt_scalef32_pk_f32_fp4 v[196:197], v72, 1.0
	v_cvt_scalef32_pk_f32_fp4 v[198:199], v72, 1.0 op_sel:[1,0,0]
	v_cvt_scalef32_pk_f32_fp4 v[230:231], v72, 1.0 op_sel:[0,1,0]
	v_cvt_scalef32_pk_f32_fp4 v[232:233], v72, 1.0 op_sel:[1,1,0]
	v_pk_fma_f32 v[234:235], v[138:139], v[196:197], v[234:235]
	v_pk_fma_f32 v[236:237], v[140:141], v[198:199], v[236:237]
	v_pk_fma_f32 v[234:235], v[142:143], v[230:231], v[234:235]
	v_pk_fma_f32 v[236:237], v[144:145], v[232:233], v[236:237]
	v_cvt_scalef32_pk_f32_fp4 v[196:197], v73, 1.0
	v_cvt_scalef32_pk_f32_fp4 v[198:199], v73, 1.0 op_sel:[1,0,0]
	v_cvt_scalef32_pk_f32_fp4 v[230:231], v73, 1.0 op_sel:[0,1,0]
	v_cvt_scalef32_pk_f32_fp4 v[232:233], v73, 1.0 op_sel:[1,1,0]
	v_pk_fma_f32 v[234:235], v[146:147], v[196:197], v[234:235]
	v_pk_fma_f32 v[236:237], v[148:149], v[198:199], v[236:237]
	v_pk_fma_f32 v[234:235], v[150:151], v[230:231], v[234:235]
	v_pk_fma_f32 v[236:237], v[152:153], v[232:233], v[236:237]
	v_add_f32_e32 v238, v236, v237
	v_add_f32_e32 v242, v234, v235
	v_add_f32_e32 v238, v242, v238
	s_nop 0
	v_add_f32_dpp v238, v238, v238 quad_perm:[1,0,3,2] row_mask:0xf bank_mask:0xf bound_ctrl:1
	s_nop 1
	v_add_f32_dpp v238, v238, v238 quad_perm:[2,3,0,1] row_mask:0xf bank_mask:0xf bound_ctrl:1
	s_nop 1
	v_add_f32_dpp v238, v238, v238 row_half_mirror row_mask:0xf bank_mask:0xf bound_ctrl:1
	s_nop 1
	v_add_f32_dpp v238, v238, v238 row_mirror row_mask:0xf bank_mask:0xf bound_ctrl:1
	ds_write_b32 v244, v238 offset:32
	s_waitcnt lgkmcnt(0)
	ds_read_b32 v240, v227 offset:112
	s_waitcnt vmcnt(5)
	v_mad_u64_u32 v[242:243], s[6:7], v241, s0, v[84:85]
	global_load_dwordx4 v[78:81], v[242:243], off
	global_load_dwordx4 v[70:73], v[242:243], off offset:256
	v_cvt_scalef32_pk_f32_fp4 v[196:197], v30, 1.0
	v_cvt_scalef32_pk_f32_fp4 v[198:199], v30, 1.0 op_sel:[1,0,0]
	v_cvt_scalef32_pk_f32_fp4 v[230:231], v30, 1.0 op_sel:[0,1,0]
	v_cvt_scalef32_pk_f32_fp4 v[232:233], v30, 1.0 op_sel:[1,1,0]
	v_pk_fma_f32 v[234:235], v[112:113], v[196:197], 0 op_sel_hi:[1,1,0]
	v_pk_fma_f32 v[236:237], v[54:55], v[198:199], 0 op_sel_hi:[1,1,0]
	v_pk_fma_f32 v[234:235], v[114:115], v[230:231], v[234:235]
	v_pk_fma_f32 v[236:237], v[56:57], v[232:233], v[236:237]
	v_cvt_scalef32_pk_f32_fp4 v[196:197], v31, 1.0
	v_cvt_scalef32_pk_f32_fp4 v[198:199], v31, 1.0 op_sel:[1,0,0]
	v_cvt_scalef32_pk_f32_fp4 v[230:231], v31, 1.0 op_sel:[0,1,0]
	v_cvt_scalef32_pk_f32_fp4 v[232:233], v31, 1.0 op_sel:[1,1,0]
	v_pk_fma_f32 v[234:235], v[116:117], v[196:197], v[234:235]
	v_pk_fma_f32 v[236:237], v[50:51], v[198:199], v[236:237]
	v_pk_fma_f32 v[234:235], v[118:119], v[230:231], v[234:235]
	v_pk_fma_f32 v[236:237], v[52:53], v[232:233], v[236:237]
	v_cvt_scalef32_pk_f32_fp4 v[196:197], v32, 1.0
	v_cvt_scalef32_pk_f32_fp4 v[198:199], v32, 1.0 op_sel:[1,0,0]
	v_cvt_scalef32_pk_f32_fp4 v[230:231], v32, 1.0 op_sel:[0,1,0]
	v_cvt_scalef32_pk_f32_fp4 v[232:233], v32, 1.0 op_sel:[1,1,0]
	v_pk_fma_f32 v[234:235], v[120:121], v[196:197], v[234:235]
	v_pk_fma_f32 v[236:237], v[46:47], v[198:199], v[236:237]
	v_pk_fma_f32 v[234:235], v[122:123], v[230:231], v[234:235]
	v_pk_fma_f32 v[236:237], v[48:49], v[232:233], v[236:237]
	v_cvt_scalef32_pk_f32_fp4 v[196:197], v33, 1.0
	v_cvt_scalef32_pk_f32_fp4 v[198:199], v33, 1.0 op_sel:[1,0,0]
	v_cvt_scalef32_pk_f32_fp4 v[230:231], v33, 1.0 op_sel:[0,1,0]
	v_cvt_scalef32_pk_f32_fp4 v[232:233], v33, 1.0 op_sel:[1,1,0]
	v_pk_fma_f32 v[234:235], v[126:127], v[196:197], v[234:235]
	v_pk_fma_f32 v[236:237], v[38:39], v[198:199], v[236:237]
	v_pk_fma_f32 v[234:235], v[128:129], v[230:231], v[234:235]
	v_pk_fma_f32 v[236:237], v[40:41], v[232:233], v[236:237]
	s_waitcnt vmcnt(6)
	v_cvt_scalef32_pk_f32_fp4 v[196:197], v26, 1.0
	v_cvt_scalef32_pk_f32_fp4 v[198:199], v26, 1.0 op_sel:[1,0,0]
	v_cvt_scalef32_pk_f32_fp4 v[230:231], v26, 1.0 op_sel:[0,1,0]
	v_cvt_scalef32_pk_f32_fp4 v[232:233], v26, 1.0 op_sel:[1,1,0]
	v_pk_fma_f32 v[234:235], v[130:131], v[196:197], v[234:235]
	v_pk_fma_f32 v[236:237], v[42:43], v[198:199], v[236:237]
	v_pk_fma_f32 v[234:235], v[132:133], v[230:231], v[234:235]
	v_pk_fma_f32 v[236:237], v[44:45], v[232:233], v[236:237]
	v_cvt_scalef32_pk_f32_fp4 v[196:197], v27, 1.0
	v_cvt_scalef32_pk_f32_fp4 v[198:199], v27, 1.0 op_sel:[1,0,0]
	v_cvt_scalef32_pk_f32_fp4 v[230:231], v27, 1.0 op_sel:[0,1,0]
	v_cvt_scalef32_pk_f32_fp4 v[232:233], v27, 1.0 op_sel:[1,1,0]
	v_pk_fma_f32 v[234:235], v[134:135], v[196:197], v[234:235]
	v_pk_fma_f32 v[236:237], v[34:35], v[198:199], v[236:237]
	v_pk_fma_f32 v[234:235], v[136:137], v[230:231], v[234:235]
	v_pk_fma_f32 v[236:237], v[36:37], v[232:233], v[236:237]
	v_cvt_scalef32_pk_f32_fp4 v[196:197], v28, 1.0
	v_cvt_scalef32_pk_f32_fp4 v[198:199], v28, 1.0 op_sel:[1,0,0]
	v_cvt_scalef32_pk_f32_fp4 v[230:231], v28, 1.0 op_sel:[0,1,0]
	v_cvt_scalef32_pk_f32_fp4 v[232:233], v28, 1.0 op_sel:[1,1,0]
	v_pk_fma_f32 v[234:235], v[138:139], v[196:197], v[234:235]
	v_pk_fma_f32 v[236:237], v[140:141], v[198:199], v[236:237]
	v_pk_fma_f32 v[234:235], v[142:143], v[230:231], v[234:235]
	v_pk_fma_f32 v[236:237], v[144:145], v[232:233], v[236:237]
	v_cvt_scalef32_pk_f32_fp4 v[196:197], v29, 1.0
	v_cvt_scalef32_pk_f32_fp4 v[198:199], v29, 1.0 op_sel:[1,0,0]
	v_cvt_scalef32_pk_f32_fp4 v[230:231], v29, 1.0 op_sel:[0,1,0]
	v_cvt_scalef32_pk_f32_fp4 v[232:233], v29, 1.0 op_sel:[1,1,0]
	v_pk_fma_f32 v[234:235], v[146:147], v[196:197], v[234:235]
	v_pk_fma_f32 v[236:237], v[148:149], v[198:199], v[236:237]
	v_pk_fma_f32 v[234:235], v[150:151], v[230:231], v[234:235]
	v_pk_fma_f32 v[236:237], v[152:153], v[232:233], v[236:237]
	v_add_f32_e32 v239, v236, v237
	v_add_f32_e32 v242, v234, v235
	v_add_f32_e32 v239, v242, v239
	s_nop 0
	v_add_f32_dpp v239, v239, v239 quad_perm:[1,0,3,2] row_mask:0xf bank_mask:0xf bound_ctrl:1
	s_nop 1
	v_add_f32_dpp v239, v239, v239 quad_perm:[2,3,0,1] row_mask:0xf bank_mask:0xf bound_ctrl:1
	s_nop 1
	v_add_f32_dpp v239, v239, v239 row_half_mirror row_mask:0xf bank_mask:0xf bound_ctrl:1
	s_nop 1
	v_add_f32_dpp v239, v239, v239 row_mirror row_mask:0xf bank_mask:0xf bound_ctrl:1
	ds_write_b32 v244, v239 offset:48
	s_waitcnt lgkmcnt(0)
	s_waitcnt vmcnt(5)
	v_mad_u64_u32 v[242:243], s[6:7], v240, s0, v[84:85]
	global_load_dwordx4 v[30:33], v[242:243], off
	global_load_dwordx4 v[26:29], v[242:243], off offset:256
	v_cvt_scalef32_pk_f32_fp4 v[196:197], v66, 1.0
	v_cvt_scalef32_pk_f32_fp4 v[198:199], v66, 1.0 op_sel:[1,0,0]
	v_cvt_scalef32_pk_f32_fp4 v[230:231], v66, 1.0 op_sel:[0,1,0]
	v_cvt_scalef32_pk_f32_fp4 v[232:233], v66, 1.0 op_sel:[1,1,0]
	v_pk_fma_f32 v[234:235], v[112:113], v[196:197], 0 op_sel_hi:[1,1,0]
	v_pk_fma_f32 v[236:237], v[54:55], v[198:199], 0 op_sel_hi:[1,1,0]
	v_pk_fma_f32 v[234:235], v[114:115], v[230:231], v[234:235]
	v_pk_fma_f32 v[236:237], v[56:57], v[232:233], v[236:237]
	v_cvt_scalef32_pk_f32_fp4 v[196:197], v67, 1.0
	v_cvt_scalef32_pk_f32_fp4 v[198:199], v67, 1.0 op_sel:[1,0,0]
	v_cvt_scalef32_pk_f32_fp4 v[230:231], v67, 1.0 op_sel:[0,1,0]
	v_cvt_scalef32_pk_f32_fp4 v[232:233], v67, 1.0 op_sel:[1,1,0]
	v_pk_fma_f32 v[234:235], v[116:117], v[196:197], v[234:235]
	v_pk_fma_f32 v[236:237], v[50:51], v[198:199], v[236:237]
	v_pk_fma_f32 v[234:235], v[118:119], v[230:231], v[234:235]
	v_pk_fma_f32 v[236:237], v[52:53], v[232:233], v[236:237]
	v_cvt_scalef32_pk_f32_fp4 v[196:197], v68, 1.0
	v_cvt_scalef32_pk_f32_fp4 v[198:199], v68, 1.0 op_sel:[1,0,0]
	v_cvt_scalef32_pk_f32_fp4 v[230:231], v68, 1.0 op_sel:[0,1,0]
	v_cvt_scalef32_pk_f32_fp4 v[232:233], v68, 1.0 op_sel:[1,1,0]
	v_pk_fma_f32 v[234:235], v[120:121], v[196:197], v[234:235]
	v_pk_fma_f32 v[236:237], v[46:47], v[198:199], v[236:237]
	v_pk_fma_f32 v[234:235], v[122:123], v[230:231], v[234:235]
	v_pk_fma_f32 v[236:237], v[48:49], v[232:233], v[236:237]
	v_cvt_scalef32_pk_f32_fp4 v[196:197], v69, 1.0
	v_cvt_scalef32_pk_f32_fp4 v[198:199], v69, 1.0 op_sel:[1,0,0]
	v_cvt_scalef32_pk_f32_fp4 v[230:231], v69, 1.0 op_sel:[0,1,0]
	v_cvt_scalef32_pk_f32_fp4 v[232:233], v69, 1.0 op_sel:[1,1,0]
	v_pk_fma_f32 v[234:235], v[126:127], v[196:197], v[234:235]
	v_pk_fma_f32 v[236:237], v[38:39], v[198:199], v[236:237]
	v_pk_fma_f32 v[234:235], v[128:129], v[230:231], v[234:235]
	v_pk_fma_f32 v[236:237], v[40:41], v[232:233], v[236:237]
	s_waitcnt vmcnt(6)
	v_cvt_scalef32_pk_f32_fp4 v[196:197], v58, 1.0
	v_cvt_scalef32_pk_f32_fp4 v[198:199], v58, 1.0 op_sel:[1,0,0]
	v_cvt_scalef32_pk_f32_fp4 v[230:231], v58, 1.0 op_sel:[0,1,0]
	v_cvt_scalef32_pk_f32_fp4 v[232:233], v58, 1.0 op_sel:[1,1,0]
	v_pk_fma_f32 v[234:235], v[130:131], v[196:197], v[234:235]
	v_pk_fma_f32 v[236:237], v[42:43], v[198:199], v[236:237]
	v_pk_fma_f32 v[234:235], v[132:133], v[230:231], v[234:235]
	v_pk_fma_f32 v[236:237], v[44:45], v[232:233], v[236:237]
	v_cvt_scalef32_pk_f32_fp4 v[196:197], v59, 1.0
	v_cvt_scalef32_pk_f32_fp4 v[198:199], v59, 1.0 op_sel:[1,0,0]
	v_cvt_scalef32_pk_f32_fp4 v[230:231], v59, 1.0 op_sel:[0,1,0]
	v_cvt_scalef32_pk_f32_fp4 v[232:233], v59, 1.0 op_sel:[1,1,0]
	v_pk_fma_f32 v[234:235], v[134:135], v[196:197], v[234:235]
	v_pk_fma_f32 v[236:237], v[34:35], v[198:199], v[236:237]
	v_pk_fma_f32 v[234:235], v[136:137], v[230:231], v[234:235]
	v_pk_fma_f32 v[236:237], v[36:37], v[232:233], v[236:237]
	v_cvt_scalef32_pk_f32_fp4 v[196:197], v60, 1.0
	v_cvt_scalef32_pk_f32_fp4 v[198:199], v60, 1.0 op_sel:[1,0,0]
	v_cvt_scalef32_pk_f32_fp4 v[230:231], v60, 1.0 op_sel:[0,1,0]
	v_cvt_scalef32_pk_f32_fp4 v[232:233], v60, 1.0 op_sel:[1,1,0]
	v_pk_fma_f32 v[234:235], v[138:139], v[196:197], v[234:235]
	v_pk_fma_f32 v[236:237], v[140:141], v[198:199], v[236:237]
	v_pk_fma_f32 v[234:235], v[142:143], v[230:231], v[234:235]
	v_pk_fma_f32 v[236:237], v[144:145], v[232:233], v[236:237]
	v_cvt_scalef32_pk_f32_fp4 v[196:197], v61, 1.0
	v_cvt_scalef32_pk_f32_fp4 v[198:199], v61, 1.0 op_sel:[1,0,0]
	v_cvt_scalef32_pk_f32_fp4 v[230:231], v61, 1.0 op_sel:[0,1,0]
	v_cvt_scalef32_pk_f32_fp4 v[232:233], v61, 1.0 op_sel:[1,1,0]
	v_pk_fma_f32 v[234:235], v[146:147], v[196:197], v[234:235]
	v_pk_fma_f32 v[236:237], v[148:149], v[198:199], v[236:237]
	v_pk_fma_f32 v[234:235], v[150:151], v[230:231], v[234:235]
	v_pk_fma_f32 v[236:237], v[152:153], v[232:233], v[236:237]
	v_add_f32_e32 v238, v236, v237
	v_add_f32_e32 v242, v234, v235
	v_add_f32_e32 v238, v242, v238
	s_nop 0
	v_add_f32_dpp v238, v238, v238 quad_perm:[1,0,3,2] row_mask:0xf bank_mask:0xf bound_ctrl:1
	s_nop 1
	v_add_f32_dpp v238, v238, v238 quad_perm:[2,3,0,1] row_mask:0xf bank_mask:0xf bound_ctrl:1
	s_nop 1
	v_add_f32_dpp v238, v238, v238 row_half_mirror row_mask:0xf bank_mask:0xf bound_ctrl:1
	s_nop 1
	v_add_f32_dpp v238, v238, v238 row_mirror row_mask:0xf bank_mask:0xf bound_ctrl:1
	ds_write_b32 v244, v238 offset:64
	s_waitcnt vmcnt(5)
	v_cvt_scalef32_pk_f32_fp4 v[196:197], v74, 1.0
	v_cvt_scalef32_pk_f32_fp4 v[198:199], v74, 1.0 op_sel:[1,0,0]
	v_cvt_scalef32_pk_f32_fp4 v[230:231], v74, 1.0 op_sel:[0,1,0]
	v_cvt_scalef32_pk_f32_fp4 v[232:233], v74, 1.0 op_sel:[1,1,0]
	v_pk_fma_f32 v[234:235], v[112:113], v[196:197], 0 op_sel_hi:[1,1,0]
	v_pk_fma_f32 v[236:237], v[54:55], v[198:199], 0 op_sel_hi:[1,1,0]
	v_pk_fma_f32 v[234:235], v[114:115], v[230:231], v[234:235]
	v_pk_fma_f32 v[236:237], v[56:57], v[232:233], v[236:237]
	v_cvt_scalef32_pk_f32_fp4 v[196:197], v75, 1.0
	v_cvt_scalef32_pk_f32_fp4 v[198:199], v75, 1.0 op_sel:[1,0,0]
	v_cvt_scalef32_pk_f32_fp4 v[230:231], v75, 1.0 op_sel:[0,1,0]
	v_cvt_scalef32_pk_f32_fp4 v[232:233], v75, 1.0 op_sel:[1,1,0]
	v_pk_fma_f32 v[234:235], v[116:117], v[196:197], v[234:235]
	v_pk_fma_f32 v[236:237], v[50:51], v[198:199], v[236:237]
	v_pk_fma_f32 v[234:235], v[118:119], v[230:231], v[234:235]
	v_pk_fma_f32 v[236:237], v[52:53], v[232:233], v[236:237]
	v_cvt_scalef32_pk_f32_fp4 v[196:197], v76, 1.0
	v_cvt_scalef32_pk_f32_fp4 v[198:199], v76, 1.0 op_sel:[1,0,0]
	v_cvt_scalef32_pk_f32_fp4 v[230:231], v76, 1.0 op_sel:[0,1,0]
	v_cvt_scalef32_pk_f32_fp4 v[232:233], v76, 1.0 op_sel:[1,1,0]
	v_pk_fma_f32 v[234:235], v[120:121], v[196:197], v[234:235]
	v_pk_fma_f32 v[236:237], v[46:47], v[198:199], v[236:237]
	v_pk_fma_f32 v[234:235], v[122:123], v[230:231], v[234:235]
	v_pk_fma_f32 v[236:237], v[48:49], v[232:233], v[236:237]
	v_cvt_scalef32_pk_f32_fp4 v[196:197], v77, 1.0
	v_cvt_scalef32_pk_f32_fp4 v[198:199], v77, 1.0 op_sel:[1,0,0]
	v_cvt_scalef32_pk_f32_fp4 v[230:231], v77, 1.0 op_sel:[0,1,0]
	v_cvt_scalef32_pk_f32_fp4 v[232:233], v77, 1.0 op_sel:[1,1,0]
	v_pk_fma_f32 v[234:235], v[126:127], v[196:197], v[234:235]
	v_pk_fma_f32 v[236:237], v[38:39], v[198:199], v[236:237]
	v_pk_fma_f32 v[234:235], v[128:129], v[230:231], v[234:235]
	v_pk_fma_f32 v[236:237], v[40:41], v[232:233], v[236:237]
	s_waitcnt vmcnt(4)
	v_cvt_scalef32_pk_f32_fp4 v[196:197], v62, 1.0
	v_cvt_scalef32_pk_f32_fp4 v[198:199], v62, 1.0 op_sel:[1,0,0]
	v_cvt_scalef32_pk_f32_fp4 v[230:231], v62, 1.0 op_sel:[0,1,0]
	v_cvt_scalef32_pk_f32_fp4 v[232:233], v62, 1.0 op_sel:[1,1,0]
	v_pk_fma_f32 v[234:235], v[130:131], v[196:197], v[234:235]
	v_pk_fma_f32 v[236:237], v[42:43], v[198:199], v[236:237]
	v_pk_fma_f32 v[234:235], v[132:133], v[230:231], v[234:235]
	v_pk_fma_f32 v[236:237], v[44:45], v[232:233], v[236:237]
	v_cvt_scalef32_pk_f32_fp4 v[196:197], v63, 1.0
	v_cvt_scalef32_pk_f32_fp4 v[198:199], v63, 1.0 op_sel:[1,0,0]
	v_cvt_scalef32_pk_f32_fp4 v[230:231], v63, 1.0 op_sel:[0,1,0]
	v_cvt_scalef32_pk_f32_fp4 v[232:233], v63, 1.0 op_sel:[1,1,0]
	v_pk_fma_f32 v[234:235], v[134:135], v[196:197], v[234:235]
	v_pk_fma_f32 v[236:237], v[34:35], v[198:199], v[236:237]
	v_pk_fma_f32 v[234:235], v[136:137], v[230:231], v[234:235]
	v_pk_fma_f32 v[236:237], v[36:37], v[232:233], v[236:237]
	v_cvt_scalef32_pk_f32_fp4 v[196:197], v64, 1.0
	v_cvt_scalef32_pk_f32_fp4 v[198:199], v64, 1.0 op_sel:[1,0,0]
	v_cvt_scalef32_pk_f32_fp4 v[230:231], v64, 1.0 op_sel:[0,1,0]
	v_cvt_scalef32_pk_f32_fp4 v[232:233], v64, 1.0 op_sel:[1,1,0]
	v_pk_fma_f32 v[234:235], v[138:139], v[196:197], v[234:235]
	v_pk_fma_f32 v[236:237], v[140:141], v[198:199], v[236:237]
	v_pk_fma_f32 v[234:235], v[142:143], v[230:231], v[234:235]
	v_pk_fma_f32 v[236:237], v[144:145], v[232:233], v[236:237]
	v_cvt_scalef32_pk_f32_fp4 v[196:197], v65, 1.0
	v_cvt_scalef32_pk_f32_fp4 v[198:199], v65, 1.0 op_sel:[1,0,0]
	v_cvt_scalef32_pk_f32_fp4 v[230:231], v65, 1.0 op_sel:[0,1,0]
	v_cvt_scalef32_pk_f32_fp4 v[232:233], v65, 1.0 op_sel:[1,1,0]
	v_pk_fma_f32 v[234:235], v[146:147], v[196:197], v[234:235]
	v_pk_fma_f32 v[236:237], v[148:149], v[198:199], v[236:237]
	v_pk_fma_f32 v[234:235], v[150:151], v[230:231], v[234:235]
	v_pk_fma_f32 v[236:237], v[152:153], v[232:233], v[236:237]
	v_add_f32_e32 v239, v236, v237
	v_add_f32_e32 v242, v234, v235
	v_add_f32_e32 v239, v242, v239
	s_nop 0
	v_add_f32_dpp v239, v239, v239 quad_perm:[1,0,3,2] row_mask:0xf bank_mask:0xf bound_ctrl:1
	s_nop 1
	v_add_f32_dpp v239, v239, v239 quad_perm:[2,3,0,1] row_mask:0xf bank_mask:0xf bound_ctrl:1
	s_nop 1
	v_add_f32_dpp v239, v239, v239 row_half_mirror row_mask:0xf bank_mask:0xf bound_ctrl:1
	s_nop 1
	v_add_f32_dpp v239, v239, v239 row_mirror row_mask:0xf bank_mask:0xf bound_ctrl:1
	ds_write_b32 v244, v239 offset:80
	s_waitcnt vmcnt(3)
	v_cvt_scalef32_pk_f32_fp4 v[196:197], v78, 1.0
	v_cvt_scalef32_pk_f32_fp4 v[198:199], v78, 1.0 op_sel:[1,0,0]
	v_cvt_scalef32_pk_f32_fp4 v[230:231], v78, 1.0 op_sel:[0,1,0]
	v_cvt_scalef32_pk_f32_fp4 v[232:233], v78, 1.0 op_sel:[1,1,0]
	v_pk_fma_f32 v[234:235], v[112:113], v[196:197], 0 op_sel_hi:[1,1,0]
	v_pk_fma_f32 v[236:237], v[54:55], v[198:199], 0 op_sel_hi:[1,1,0]
	v_pk_fma_f32 v[234:235], v[114:115], v[230:231], v[234:235]
	v_pk_fma_f32 v[236:237], v[56:57], v[232:233], v[236:237]
	v_cvt_scalef32_pk_f32_fp4 v[196:197], v79, 1.0
	v_cvt_scalef32_pk_f32_fp4 v[198:199], v79, 1.0 op_sel:[1,0,0]
	v_cvt_scalef32_pk_f32_fp4 v[230:231], v79, 1.0 op_sel:[0,1,0]
	v_cvt_scalef32_pk_f32_fp4 v[232:233], v79, 1.0 op_sel:[1,1,0]
	v_pk_fma_f32 v[234:235], v[116:117], v[196:197], v[234:235]
	v_pk_fma_f32 v[236:237], v[50:51], v[198:199], v[236:237]
	v_pk_fma_f32 v[234:235], v[118:119], v[230:231], v[234:235]
	v_pk_fma_f32 v[236:237], v[52:53], v[232:233], v[236:237]
	v_cvt_scalef32_pk_f32_fp4 v[196:197], v80, 1.0
	v_cvt_scalef32_pk_f32_fp4 v[198:199], v80, 1.0 op_sel:[1,0,0]
	v_cvt_scalef32_pk_f32_fp4 v[230:231], v80, 1.0 op_sel:[0,1,0]
	v_cvt_scalef32_pk_f32_fp4 v[232:233], v80, 1.0 op_sel:[1,1,0]
	v_pk_fma_f32 v[234:235], v[120:121], v[196:197], v[234:235]
	v_pk_fma_f32 v[236:237], v[46:47], v[198:199], v[236:237]
	v_pk_fma_f32 v[234:235], v[122:123], v[230:231], v[234:235]
	v_pk_fma_f32 v[236:237], v[48:49], v[232:233], v[236:237]
	v_cvt_scalef32_pk_f32_fp4 v[196:197], v81, 1.0
	v_cvt_scalef32_pk_f32_fp4 v[198:199], v81, 1.0 op_sel:[1,0,0]
	v_cvt_scalef32_pk_f32_fp4 v[230:231], v81, 1.0 op_sel:[0,1,0]
	v_cvt_scalef32_pk_f32_fp4 v[232:233], v81, 1.0 op_sel:[1,1,0]
	v_pk_fma_f32 v[234:235], v[126:127], v[196:197], v[234:235]
	v_pk_fma_f32 v[236:237], v[38:39], v[198:199], v[236:237]
	v_pk_fma_f32 v[234:235], v[128:129], v[230:231], v[234:235]
	v_pk_fma_f32 v[236:237], v[40:41], v[232:233], v[236:237]
	s_waitcnt vmcnt(2)
	v_cvt_scalef32_pk_f32_fp4 v[196:197], v70, 1.0
	v_cvt_scalef32_pk_f32_fp4 v[198:199], v70, 1.0 op_sel:[1,0,0]
	v_cvt_scalef32_pk_f32_fp4 v[230:231], v70, 1.0 op_sel:[0,1,0]
	v_cvt_scalef32_pk_f32_fp4 v[232:233], v70, 1.0 op_sel:[1,1,0]
	v_pk_fma_f32 v[234:235], v[130:131], v[196:197], v[234:235]
	v_pk_fma_f32 v[236:237], v[42:43], v[198:199], v[236:237]
	v_pk_fma_f32 v[234:235], v[132:133], v[230:231], v[234:235]
	v_pk_fma_f32 v[236:237], v[44:45], v[232:233], v[236:237]
	v_cvt_scalef32_pk_f32_fp4 v[196:197], v71, 1.0
	v_cvt_scalef32_pk_f32_fp4 v[198:199], v71, 1.0 op_sel:[1,0,0]
	v_cvt_scalef32_pk_f32_fp4 v[230:231], v71, 1.0 op_sel:[0,1,0]
	v_cvt_scalef32_pk_f32_fp4 v[232:233], v71, 1.0 op_sel:[1,1,0]
	v_pk_fma_f32 v[234:235], v[134:135], v[196:197], v[234:235]
	v_pk_fma_f32 v[236:237], v[34:35], v[198:199], v[236:237]
	v_pk_fma_f32 v[234:235], v[136:137], v[230:231], v[234:235]
	v_pk_fma_f32 v[236:237], v[36:37], v[232:233], v[236:237]
	v_cvt_scalef32_pk_f32_fp4 v[196:197], v72, 1.0
	v_cvt_scalef32_pk_f32_fp4 v[198:199], v72, 1.0 op_sel:[1,0,0]
	v_cvt_scalef32_pk_f32_fp4 v[230:231], v72, 1.0 op_sel:[0,1,0]
	v_cvt_scalef32_pk_f32_fp4 v[232:233], v72, 1.0 op_sel:[1,1,0]
	v_pk_fma_f32 v[234:235], v[138:139], v[196:197], v[234:235]
	v_pk_fma_f32 v[236:237], v[140:141], v[198:199], v[236:237]
	v_pk_fma_f32 v[234:235], v[142:143], v[230:231], v[234:235]
	v_pk_fma_f32 v[236:237], v[144:145], v[232:233], v[236:237]
	v_cvt_scalef32_pk_f32_fp4 v[196:197], v73, 1.0
	v_cvt_scalef32_pk_f32_fp4 v[198:199], v73, 1.0 op_sel:[1,0,0]
	v_cvt_scalef32_pk_f32_fp4 v[230:231], v73, 1.0 op_sel:[0,1,0]
	v_cvt_scalef32_pk_f32_fp4 v[232:233], v73, 1.0 op_sel:[1,1,0]
	v_pk_fma_f32 v[234:235], v[146:147], v[196:197], v[234:235]
	v_pk_fma_f32 v[236:237], v[148:149], v[198:199], v[236:237]
	v_pk_fma_f32 v[234:235], v[150:151], v[230:231], v[234:235]
	v_pk_fma_f32 v[236:237], v[152:153], v[232:233], v[236:237]
	v_add_f32_e32 v238, v236, v237
	v_add_f32_e32 v242, v234, v235
	v_add_f32_e32 v238, v242, v238
	s_nop 0
	v_add_f32_dpp v238, v238, v238 quad_perm:[1,0,3,2] row_mask:0xf bank_mask:0xf bound_ctrl:1
	s_nop 1
	v_add_f32_dpp v238, v238, v238 quad_perm:[2,3,0,1] row_mask:0xf bank_mask:0xf bound_ctrl:1
	s_nop 1
	v_add_f32_dpp v238, v238, v238 row_half_mirror row_mask:0xf bank_mask:0xf bound_ctrl:1
	s_nop 1
	v_add_f32_dpp v238, v238, v238 row_mirror row_mask:0xf bank_mask:0xf bound_ctrl:1
	ds_write_b32 v244, v238 offset:96
	s_waitcnt vmcnt(1)
	v_cvt_scalef32_pk_f32_fp4 v[196:197], v30, 1.0
	v_cvt_scalef32_pk_f32_fp4 v[198:199], v30, 1.0 op_sel:[1,0,0]
	v_cvt_scalef32_pk_f32_fp4 v[230:231], v30, 1.0 op_sel:[0,1,0]
	v_cvt_scalef32_pk_f32_fp4 v[232:233], v30, 1.0 op_sel:[1,1,0]
	v_pk_fma_f32 v[234:235], v[112:113], v[196:197], 0 op_sel_hi:[1,1,0]
	v_pk_fma_f32 v[236:237], v[54:55], v[198:199], 0 op_sel_hi:[1,1,0]
	v_pk_fma_f32 v[234:235], v[114:115], v[230:231], v[234:235]
	v_pk_fma_f32 v[236:237], v[56:57], v[232:233], v[236:237]
	v_cvt_scalef32_pk_f32_fp4 v[196:197], v31, 1.0
	v_cvt_scalef32_pk_f32_fp4 v[198:199], v31, 1.0 op_sel:[1,0,0]
	v_cvt_scalef32_pk_f32_fp4 v[230:231], v31, 1.0 op_sel:[0,1,0]
	v_cvt_scalef32_pk_f32_fp4 v[232:233], v31, 1.0 op_sel:[1,1,0]
	v_pk_fma_f32 v[234:235], v[116:117], v[196:197], v[234:235]
	v_pk_fma_f32 v[236:237], v[50:51], v[198:199], v[236:237]
	v_pk_fma_f32 v[234:235], v[118:119], v[230:231], v[234:235]
	v_pk_fma_f32 v[236:237], v[52:53], v[232:233], v[236:237]
	v_cvt_scalef32_pk_f32_fp4 v[196:197], v32, 1.0
	v_cvt_scalef32_pk_f32_fp4 v[198:199], v32, 1.0 op_sel:[1,0,0]
	v_cvt_scalef32_pk_f32_fp4 v[230:231], v32, 1.0 op_sel:[0,1,0]
	v_cvt_scalef32_pk_f32_fp4 v[232:233], v32, 1.0 op_sel:[1,1,0]
	v_pk_fma_f32 v[234:235], v[120:121], v[196:197], v[234:235]
	v_pk_fma_f32 v[236:237], v[46:47], v[198:199], v[236:237]
	v_pk_fma_f32 v[234:235], v[122:123], v[230:231], v[234:235]
	v_pk_fma_f32 v[236:237], v[48:49], v[232:233], v[236:237]
	v_cvt_scalef32_pk_f32_fp4 v[196:197], v33, 1.0
	v_cvt_scalef32_pk_f32_fp4 v[198:199], v33, 1.0 op_sel:[1,0,0]
	v_cvt_scalef32_pk_f32_fp4 v[230:231], v33, 1.0 op_sel:[0,1,0]
	v_cvt_scalef32_pk_f32_fp4 v[232:233], v33, 1.0 op_sel:[1,1,0]
	v_pk_fma_f32 v[234:235], v[126:127], v[196:197], v[234:235]
	v_pk_fma_f32 v[236:237], v[38:39], v[198:199], v[236:237]
	v_pk_fma_f32 v[234:235], v[128:129], v[230:231], v[234:235]
	v_pk_fma_f32 v[236:237], v[40:41], v[232:233], v[236:237]
	s_waitcnt vmcnt(0)
	v_cvt_scalef32_pk_f32_fp4 v[196:197], v26, 1.0
	v_cvt_scalef32_pk_f32_fp4 v[198:199], v26, 1.0 op_sel:[1,0,0]
	v_cvt_scalef32_pk_f32_fp4 v[230:231], v26, 1.0 op_sel:[0,1,0]
	v_cvt_scalef32_pk_f32_fp4 v[232:233], v26, 1.0 op_sel:[1,1,0]
	v_pk_fma_f32 v[234:235], v[130:131], v[196:197], v[234:235]
	v_pk_fma_f32 v[236:237], v[42:43], v[198:199], v[236:237]
	v_pk_fma_f32 v[234:235], v[132:133], v[230:231], v[234:235]
	v_pk_fma_f32 v[236:237], v[44:45], v[232:233], v[236:237]
	v_cvt_scalef32_pk_f32_fp4 v[196:197], v27, 1.0
	v_cvt_scalef32_pk_f32_fp4 v[198:199], v27, 1.0 op_sel:[1,0,0]
	v_cvt_scalef32_pk_f32_fp4 v[230:231], v27, 1.0 op_sel:[0,1,0]
	v_cvt_scalef32_pk_f32_fp4 v[232:233], v27, 1.0 op_sel:[1,1,0]
	v_pk_fma_f32 v[234:235], v[134:135], v[196:197], v[234:235]
	v_pk_fma_f32 v[236:237], v[34:35], v[198:199], v[236:237]
	v_pk_fma_f32 v[234:235], v[136:137], v[230:231], v[234:235]
	v_pk_fma_f32 v[236:237], v[36:37], v[232:233], v[236:237]
	v_cvt_scalef32_pk_f32_fp4 v[196:197], v28, 1.0
	v_cvt_scalef32_pk_f32_fp4 v[198:199], v28, 1.0 op_sel:[1,0,0]
	v_cvt_scalef32_pk_f32_fp4 v[230:231], v28, 1.0 op_sel:[0,1,0]
	v_cvt_scalef32_pk_f32_fp4 v[232:233], v28, 1.0 op_sel:[1,1,0]
	v_pk_fma_f32 v[234:235], v[138:139], v[196:197], v[234:235]
	v_pk_fma_f32 v[236:237], v[140:141], v[198:199], v[236:237]
	v_pk_fma_f32 v[234:235], v[142:143], v[230:231], v[234:235]
	v_pk_fma_f32 v[236:237], v[144:145], v[232:233], v[236:237]
	v_cvt_scalef32_pk_f32_fp4 v[196:197], v29, 1.0
	v_cvt_scalef32_pk_f32_fp4 v[198:199], v29, 1.0 op_sel:[1,0,0]
	v_cvt_scalef32_pk_f32_fp4 v[230:231], v29, 1.0 op_sel:[0,1,0]
	v_cvt_scalef32_pk_f32_fp4 v[232:233], v29, 1.0 op_sel:[1,1,0]
	v_pk_fma_f32 v[234:235], v[146:147], v[196:197], v[234:235]
	v_pk_fma_f32 v[236:237], v[148:149], v[198:199], v[236:237]
	v_pk_fma_f32 v[234:235], v[150:151], v[230:231], v[234:235]
	v_pk_fma_f32 v[236:237], v[152:153], v[232:233], v[236:237]
	v_add_f32_e32 v239, v236, v237
	v_add_f32_e32 v242, v234, v235
	v_add_f32_e32 v239, v242, v239
	s_nop 0
	v_add_f32_dpp v239, v239, v239 quad_perm:[1,0,3,2] row_mask:0xf bank_mask:0xf bound_ctrl:1
	s_nop 1
	v_add_f32_dpp v239, v239, v239 quad_perm:[2,3,0,1] row_mask:0xf bank_mask:0xf bound_ctrl:1
	s_nop 1
	v_add_f32_dpp v239, v239, v239 row_half_mirror row_mask:0xf bank_mask:0xf bound_ctrl:1
	s_nop 1
	v_add_f32_dpp v239, v239, v239 row_mirror row_mask:0xf bank_mask:0xf bound_ctrl:1
	ds_write_b32 v244, v239 offset:112

.LBB0_186:
	s_andn2_saveexec_b64 s[6:7], s[6:7]
	v_mul_f32_e32 v28, v26, v26
	v_fmamk_f32 v29, v28, 0xba1345e1, v171
	v_fmaak_f32 v29, v28, v29, 0xbcdac9b8
	v_fmaak_f32 v29, v28, v29, 0x3de703be
	v_fmaak_f32 v29, v28, v29, 0xbec09330
	v_fmaak_f32 v28, v28, v29, 0x3e0375d0
	v_fma_f32 v28, |v26|, v28, |v26|
	s_or_b64 exec, exec, s[6:7]
	ds_read_b32 v29, v154 offset:35072
	s_brev_b32 s0, -2
	v_bfi_b32 v26, s0, v28, v26
	v_mul_f32_e32 v27, 0.5, v27
	v_add_f32_e32 v26, 1.0, v26
	v_mul_f32_e32 v26, v27, v26
	v_mul_f32_e32 v26, 0x3d353d2b, v26
	s_waitcnt vmcnt(2)
	v_mov_b32_e32 v64, 0
	s_waitcnt lgkmcnt(0)
	v_mul_f32_e32 v26, v29, v26
	s_mov_b32 s2, -4
	v_mov_b32_e32 v131, v222
	v_mov_b32_e32 v132, v223
	v_mov_b32_e32 v65, v64
	v_mov_b32_e32 v62, v64
	v_mov_b32_e32 v63, v64
	v_mov_b32_e32 v60, v64
	v_mov_b32_e32 v61, v64
	v_mov_b32_e32 v58, v64
	v_mov_b32_e32 v59, v64
	v_mov_b32_e32 v56, v64
	v_mov_b32_e32 v57, v64
	v_mov_b32_e32 v54, v64
	v_mov_b32_e32 v55, v64
	v_mov_b32_e32 v52, v64
	v_mov_b32_e32 v53, v64
	v_mov_b32_e32 v50, v64
	v_mov_b32_e32 v51, v64
	v_mov_b32_e32 v48, v64
	v_mov_b32_e32 v49, v64
	v_mov_b32_e32 v46, v64
	v_mov_b32_e32 v47, v64
	v_mov_b32_e32 v44, v64
	v_mov_b32_e32 v45, v64
	v_mov_b32_e32 v42, v64
	v_mov_b32_e32 v43, v64
	v_mov_b32_e32 v40, v64
	v_mov_b32_e32 v41, v64
	v_mov_b32_e32 v38, v64
	v_mov_b32_e32 v39, v64
	v_mov_b32_e32 v36, v64
	v_mov_b32_e32 v37, v64
	v_mov_b32_e32 v34, v64
	v_mov_b32_e32 v35, v64
	v_mov_b32_e32 v66, v64
	v_mov_b32_e32 v67, v64
	v_mov_b32_e32 v68, v64
	v_mov_b32_e32 v69, v64
	s_waitcnt vmcnt(0)
	v_mov_b32_e32 v70, v64
	v_mov_b32_e32 v71, v64
	v_mov_b32_e32 v72, v64
	v_mov_b32_e32 v73, v64
	v_mov_b32_e32 v74, v64
	v_mov_b32_e32 v75, v64
	v_mov_b32_e32 v76, v64
	v_mov_b32_e32 v77, v64
	v_mov_b32_e32 v78, v64
	v_mov_b32_e32 v79, v64
	v_mov_b32_e32 v80, v64
	v_mov_b32_e32 v81, v64
	v_mov_b32_e32 v112, v64
	v_mov_b32_e32 v113, v64
	v_mov_b32_e32 v114, v64
	v_mov_b32_e32 v115, v64
	v_mov_b32_e32 v116, v64
	v_mov_b32_e32 v117, v64
	v_mov_b32_e32 v118, v64
	v_mov_b32_e32 v119, v64
	v_mov_b32_e32 v120, v64
	v_mov_b32_e32 v121, v64
	v_mov_b32_e32 v122, v64
	v_mov_b32_e32 v123, v64
	v_mov_b32_e32 v126, v64
	v_mov_b32_e32 v127, v64
	v_mov_b32_e32 v128, v64
	v_mov_b32_e32 v129, v64
	ds_write_b32 v154, v26 offset:35072
	ds_read_b32 v30, v217 offset:35376
	ds_read_b32 v142, v217 offset:35392
	ds_read_b32 v150, v217 offset:35408
	ds_read_b32 v236, v217 offset:35424
	ds_read_b32 v250, v217 offset:35440
	s_movk_i32 s0, 0x200
	s_waitcnt lgkmcnt(0)
	v_mad_u64_u32 v[248:249], vcc, v30, s0, v[86:87]
	global_load_dwordx4 v[30:33], v[248:249], off
	global_load_dwordx4 v[26:29], v[248:249], off offset:256
	v_mad_u64_u32 v[248:249], vcc, v142, s0, v[86:87]
	global_load_dwordx4 v[142:145], v[248:249], off
	global_load_dwordx4 v[146:149], v[248:249], off offset:256
	v_mad_u64_u32 v[248:249], vcc, v150, s0, v[86:87]
	global_load_dwordx4 v[150:153], v[248:249], off
	global_load_dwordx4 v[232:235], v[248:249], off offset:256
	v_mad_u64_u32 v[248:249], vcc, v236, s0, v[86:87]
	global_load_dwordx4 v[236:239], v[248:249], off
	global_load_dwordx4 v[240:243], v[248:249], off offset:256
	v_add_u32_e32 v131, 0x8a80, v217
	v_mov_b32_e32 v132, v223
	s_mov_b32 s2, 0
.Lpv_loop:
	v_mad_u64_u32 v[248:249], vcc, v250, s0, v[86:87]
	global_load_dwordx4 v[244:247], v[248:249], off
	global_load_dwordx4 v[228:231], v[248:249], off offset:256
	ds_read_b32 v227, v131 offset:0
	ds_read_b32 v130, v132 offset:0
	s_waitcnt vmcnt(15)
	v_cvt_scalef32_pk_f32_fp4 v[134:135], v10, 1.0
	v_cvt_scalef32_pk_f32_fp4 v[136:137], v10, 1.0 op_sel:[1,0,0]
	v_cvt_scalef32_pk_f32_fp4 v[138:139], v10, 1.0 op_sel:[0,1,0]
	v_cvt_scalef32_pk_f32_fp4 v[140:141], v10, 1.0 op_sel:[1,1,0]
	s_waitcnt lgkmcnt(0)
	v_pk_fma_f32 v[128:129], v[130:131], v[134:135], v[128:129] op_sel_hi:[0,1,1]
	v_pk_fma_f32 v[126:127], v[130:131], v[136:137], v[126:127] op_sel_hi:[0,1,1]
	v_pk_fma_f32 v[122:123], v[130:131], v[138:139], v[122:123] op_sel_hi:[0,1,1]
	v_pk_fma_f32 v[120:121], v[130:131], v[140:141], v[120:121] op_sel_hi:[0,1,1]
	v_cvt_scalef32_pk_f32_fp4 v[134:135], v11, 1.0
	v_cvt_scalef32_pk_f32_fp4 v[136:137], v11, 1.0 op_sel:[1,0,0]
	v_cvt_scalef32_pk_f32_fp4 v[138:139], v11, 1.0 op_sel:[0,1,0]
	v_cvt_scalef32_pk_f32_fp4 v[140:141], v11, 1.0 op_sel:[1,1,0]
	v_pk_fma_f32 v[118:119], v[130:131], v[134:135], v[118:119] op_sel_hi:[0,1,1]
	v_pk_fma_f32 v[116:117], v[130:131], v[136:137], v[116:117] op_sel_hi:[0,1,1]
	v_pk_fma_f32 v[114:115], v[130:131], v[138:139], v[114:115] op_sel_hi:[0,1,1]
	v_pk_fma_f32 v[112:113], v[130:131], v[140:141], v[112:113] op_sel_hi:[0,1,1]
	v_cvt_scalef32_pk_f32_fp4 v[134:135], v12, 1.0
	v_cvt_scalef32_pk_f32_fp4 v[136:137], v12, 1.0 op_sel:[1,0,0]
	v_cvt_scalef32_pk_f32_fp4 v[138:139], v12, 1.0 op_sel:[0,1,0]
	v_cvt_scalef32_pk_f32_fp4 v[140:141], v12, 1.0 op_sel:[1,1,0]
	v_pk_fma_f32 v[80:81], v[130:131], v[134:135], v[80:81] op_sel_hi:[0,1,1]
	v_pk_fma_f32 v[78:79], v[130:131], v[136:137], v[78:79] op_sel_hi:[0,1,1]
	v_pk_fma_f32 v[76:77], v[130:131], v[138:139], v[76:77] op_sel_hi:[0,1,1]
	v_pk_fma_f32 v[74:75], v[130:131], v[140:141], v[74:75] op_sel_hi:[0,1,1]
	v_cvt_scalef32_pk_f32_fp4 v[134:135], v13, 1.0
	v_cvt_scalef32_pk_f32_fp4 v[136:137], v13, 1.0 op_sel:[1,0,0]
	v_cvt_scalef32_pk_f32_fp4 v[138:139], v13, 1.0 op_sel:[0,1,0]
	v_cvt_scalef32_pk_f32_fp4 v[140:141], v13, 1.0 op_sel:[1,1,0]
	v_pk_fma_f32 v[72:73], v[130:131], v[134:135], v[72:73] op_sel_hi:[0,1,1]
	v_pk_fma_f32 v[70:71], v[130:131], v[136:137], v[70:71] op_sel_hi:[0,1,1]
	v_pk_fma_f32 v[68:69], v[130:131], v[138:139], v[68:69] op_sel_hi:[0,1,1]
	v_pk_fma_f32 v[66:67], v[130:131], v[140:141], v[66:67] op_sel_hi:[0,1,1]
	s_waitcnt vmcnt(14)
	v_cvt_scalef32_pk_f32_fp4 v[134:135], v2, 1.0
	v_cvt_scalef32_pk_f32_fp4 v[136:137], v2, 1.0 op_sel:[1,0,0]
	v_cvt_scalef32_pk_f32_fp4 v[138:139], v2, 1.0 op_sel:[0,1,0]
	v_cvt_scalef32_pk_f32_fp4 v[140:141], v2, 1.0 op_sel:[1,1,0]
	v_pk_fma_f32 v[34:35], v[130:131], v[134:135], v[34:35] op_sel_hi:[0,1,1]
	v_pk_fma_f32 v[36:37], v[130:131], v[136:137], v[36:37] op_sel_hi:[0,1,1]
	v_pk_fma_f32 v[38:39], v[130:131], v[138:139], v[38:39] op_sel_hi:[0,1,1]
	v_pk_fma_f32 v[40:41], v[130:131], v[140:141], v[40:41] op_sel_hi:[0,1,1]
	v_cvt_scalef32_pk_f32_fp4 v[134:135], v3, 1.0
	v_cvt_scalef32_pk_f32_fp4 v[136:137], v3, 1.0 op_sel:[1,0,0]
	v_cvt_scalef32_pk_f32_fp4 v[138:139], v3, 1.0 op_sel:[0,1,0]
	v_cvt_scalef32_pk_f32_fp4 v[140:141], v3, 1.0 op_sel:[1,1,0]
	v_pk_fma_f32 v[42:43], v[130:131], v[134:135], v[42:43] op_sel_hi:[0,1,1]
	v_pk_fma_f32 v[44:45], v[130:131], v[136:137], v[44:45] op_sel_hi:[0,1,1]
	v_pk_fma_f32 v[46:47], v[130:131], v[138:139], v[46:47] op_sel_hi:[0,1,1]
	v_pk_fma_f32 v[48:49], v[130:131], v[140:141], v[48:49] op_sel_hi:[0,1,1]
	v_cvt_scalef32_pk_f32_fp4 v[134:135], v4, 1.0
	v_cvt_scalef32_pk_f32_fp4 v[136:137], v4, 1.0 op_sel:[1,0,0]
	v_cvt_scalef32_pk_f32_fp4 v[138:139], v4, 1.0 op_sel:[0,1,0]
	v_cvt_scalef32_pk_f32_fp4 v[140:141], v4, 1.0 op_sel:[1,1,0]
	v_pk_fma_f32 v[50:51], v[130:131], v[134:135], v[50:51] op_sel_hi:[0,1,1]
	v_pk_fma_f32 v[52:53], v[130:131], v[136:137], v[52:53] op_sel_hi:[0,1,1]
	v_pk_fma_f32 v[54:55], v[130:131], v[138:139], v[54:55] op_sel_hi:[0,1,1]
	v_pk_fma_f32 v[56:57], v[130:131], v[140:141], v[56:57] op_sel_hi:[0,1,1]
	v_cvt_scalef32_pk_f32_fp4 v[134:135], v5, 1.0
	v_cvt_scalef32_pk_f32_fp4 v[136:137], v5, 1.0 op_sel:[1,0,0]
	v_cvt_scalef32_pk_f32_fp4 v[138:139], v5, 1.0 op_sel:[0,1,0]
	v_cvt_scalef32_pk_f32_fp4 v[140:141], v5, 1.0 op_sel:[1,1,0]
	v_pk_fma_f32 v[58:59], v[130:131], v[134:135], v[58:59] op_sel_hi:[0,1,1]
	v_pk_fma_f32 v[60:61], v[130:131], v[136:137], v[60:61] op_sel_hi:[0,1,1]
	v_pk_fma_f32 v[62:63], v[130:131], v[138:139], v[62:63] op_sel_hi:[0,1,1]
	v_pk_fma_f32 v[64:65], v[130:131], v[140:141], v[64:65] op_sel_hi:[0,1,1]
	v_mad_u64_u32 v[248:249], vcc, v227, s0, v[86:87]
	global_load_dwordx4 v[10:13], v[248:249], off
	global_load_dwordx4 v[2:5], v[248:249], off offset:256
	ds_read_b32 v250, v131 offset:16
	ds_read_b32 v130, v132 offset:16
	s_waitcnt vmcnt(15)
	v_cvt_scalef32_pk_f32_fp4 v[134:135], v14, 1.0
	v_cvt_scalef32_pk_f32_fp4 v[136:137], v14, 1.0 op_sel:[1,0,0]
	v_cvt_scalef32_pk_f32_fp4 v[138:139], v14, 1.0 op_sel:[0,1,0]
	v_cvt_scalef32_pk_f32_fp4 v[140:141], v14, 1.0 op_sel:[1,1,0]
	s_waitcnt lgkmcnt(0)
	v_pk_fma_f32 v[128:129], v[130:131], v[134:135], v[128:129] op_sel_hi:[0,1,1]
	v_pk_fma_f32 v[126:127], v[130:131], v[136:137], v[126:127] op_sel_hi:[0,1,1]
	v_pk_fma_f32 v[122:123], v[130:131], v[138:139], v[122:123] op_sel_hi:[0,1,1]
	v_pk_fma_f32 v[120:121], v[130:131], v[140:141], v[120:121] op_sel_hi:[0,1,1]
	v_cvt_scalef32_pk_f32_fp4 v[134:135], v15, 1.0
	v_cvt_scalef32_pk_f32_fp4 v[136:137], v15, 1.0 op_sel:[1,0,0]
	v_cvt_scalef32_pk_f32_fp4 v[138:139], v15, 1.0 op_sel:[0,1,0]
	v_cvt_scalef32_pk_f32_fp4 v[140:141], v15, 1.0 op_sel:[1,1,0]
	v_pk_fma_f32 v[118:119], v[130:131], v[134:135], v[118:119] op_sel_hi:[0,1,1]
	v_pk_fma_f32 v[116:117], v[130:131], v[136:137], v[116:117] op_sel_hi:[0,1,1]
	v_pk_fma_f32 v[114:115], v[130:131], v[138:139], v[114:115] op_sel_hi:[0,1,1]
	v_pk_fma_f32 v[112:113], v[130:131], v[140:141], v[112:113] op_sel_hi:[0,1,1]
	v_cvt_scalef32_pk_f32_fp4 v[134:135], v16, 1.0
	v_cvt_scalef32_pk_f32_fp4 v[136:137], v16, 1.0 op_sel:[1,0,0]
	v_cvt_scalef32_pk_f32_fp4 v[138:139], v16, 1.0 op_sel:[0,1,0]
	v_cvt_scalef32_pk_f32_fp4 v[140:141], v16, 1.0 op_sel:[1,1,0]
	v_pk_fma_f32 v[80:81], v[130:131], v[134:135], v[80:81] op_sel_hi:[0,1,1]
	v_pk_fma_f32 v[78:79], v[130:131], v[136:137], v[78:79] op_sel_hi:[0,1,1]
	v_pk_fma_f32 v[76:77], v[130:131], v[138:139], v[76:77] op_sel_hi:[0,1,1]
	v_pk_fma_f32 v[74:75], v[130:131], v[140:141], v[74:75] op_sel_hi:[0,1,1]
	v_cvt_scalef32_pk_f32_fp4 v[134:135], v17, 1.0
	v_cvt_scalef32_pk_f32_fp4 v[136:137], v17, 1.0 op_sel:[1,0,0]
	v_cvt_scalef32_pk_f32_fp4 v[138:139], v17, 1.0 op_sel:[0,1,0]
	v_cvt_scalef32_pk_f32_fp4 v[140:141], v17, 1.0 op_sel:[1,1,0]
	v_pk_fma_f32 v[72:73], v[130:131], v[134:135], v[72:73] op_sel_hi:[0,1,1]
	v_pk_fma_f32 v[70:71], v[130:131], v[136:137], v[70:71] op_sel_hi:[0,1,1]
	v_pk_fma_f32 v[68:69], v[130:131], v[138:139], v[68:69] op_sel_hi:[0,1,1]
	v_pk_fma_f32 v[66:67], v[130:131], v[140:141], v[66:67] op_sel_hi:[0,1,1]
	s_waitcnt vmcnt(14)
	v_cvt_scalef32_pk_f32_fp4 v[134:135], v6, 1.0
	v_cvt_scalef32_pk_f32_fp4 v[136:137], v6, 1.0 op_sel:[1,0,0]
	v_cvt_scalef32_pk_f32_fp4 v[138:139], v6, 1.0 op_sel:[0,1,0]
	v_cvt_scalef32_pk_f32_fp4 v[140:141], v6, 1.0 op_sel:[1,1,0]
	v_pk_fma_f32 v[34:35], v[130:131], v[134:135], v[34:35] op_sel_hi:[0,1,1]
	v_pk_fma_f32 v[36:37], v[130:131], v[136:137], v[36:37] op_sel_hi:[0,1,1]
	v_pk_fma_f32 v[38:39], v[130:131], v[138:139], v[38:39] op_sel_hi:[0,1,1]
	v_pk_fma_f32 v[40:41], v[130:131], v[140:141], v[40:41] op_sel_hi:[0,1,1]
	v_cvt_scalef32_pk_f32_fp4 v[134:135], v7, 1.0
	v_cvt_scalef32_pk_f32_fp4 v[136:137], v7, 1.0 op_sel:[1,0,0]
	v_cvt_scalef32_pk_f32_fp4 v[138:139], v7, 1.0 op_sel:[0,1,0]
	v_cvt_scalef32_pk_f32_fp4 v[140:141], v7, 1.0 op_sel:[1,1,0]
	v_pk_fma_f32 v[42:43], v[130:131], v[134:135], v[42:43] op_sel_hi:[0,1,1]
	v_pk_fma_f32 v[44:45], v[130:131], v[136:137], v[44:45] op_sel_hi:[0,1,1]
	v_pk_fma_f32 v[46:47], v[130:131], v[138:139], v[46:47] op_sel_hi:[0,1,1]
	v_pk_fma_f32 v[48:49], v[130:131], v[140:141], v[48:49] op_sel_hi:[0,1,1]
	v_cvt_scalef32_pk_f32_fp4 v[134:135], v8, 1.0
	v_cvt_scalef32_pk_f32_fp4 v[136:137], v8, 1.0 op_sel:[1,0,0]
	v_cvt_scalef32_pk_f32_fp4 v[138:139], v8, 1.0 op_sel:[0,1,0]
	v_cvt_scalef32_pk_f32_fp4 v[140:141], v8, 1.0 op_sel:[1,1,0]
	v_pk_fma_f32 v[50:51], v[130:131], v[134:135], v[50:51] op_sel_hi:[0,1,1]
	v_pk_fma_f32 v[52:53], v[130:131], v[136:137], v[52:53] op_sel_hi:[0,1,1]
	v_pk_fma_f32 v[54:55], v[130:131], v[138:139], v[54:55] op_sel_hi:[0,1,1]
	v_pk_fma_f32 v[56:57], v[130:131], v[140:141], v[56:57] op_sel_hi:[0,1,1]
	v_cvt_scalef32_pk_f32_fp4 v[134:135], v9, 1.0
	v_cvt_scalef32_pk_f32_fp4 v[136:137], v9, 1.0 op_sel:[1,0,0]
	v_cvt_scalef32_pk_f32_fp4 v[138:139], v9, 1.0 op_sel:[0,1,0]
	v_cvt_scalef32_pk_f32_fp4 v[140:141], v9, 1.0 op_sel:[1,1,0]
	v_pk_fma_f32 v[58:59], v[130:131], v[134:135], v[58:59] op_sel_hi:[0,1,1]
	v_pk_fma_f32 v[60:61], v[130:131], v[136:137], v[60:61] op_sel_hi:[0,1,1]
	v_pk_fma_f32 v[62:63], v[130:131], v[138:139], v[62:63] op_sel_hi:[0,1,1]
	v_pk_fma_f32 v[64:65], v[130:131], v[140:141], v[64:65] op_sel_hi:[0,1,1]
	v_mad_u64_u32 v[248:249], vcc, v250, s0, v[86:87]
	global_load_dwordx4 v[14:17], v[248:249], off
	global_load_dwordx4 v[6:9], v[248:249], off offset:256
	ds_read_b32 v227, v131 offset:32
	ds_read_b32 v130, v132 offset:32
	s_waitcnt vmcnt(15)
	v_cvt_scalef32_pk_f32_fp4 v[134:135], v22, 1.0
	v_cvt_scalef32_pk_f32_fp4 v[136:137], v22, 1.0 op_sel:[1,0,0]
	v_cvt_scalef32_pk_f32_fp4 v[138:139], v22, 1.0 op_sel:[0,1,0]
	v_cvt_scalef32_pk_f32_fp4 v[140:141], v22, 1.0 op_sel:[1,1,0]
	s_waitcnt lgkmcnt(0)
	v_pk_fma_f32 v[128:129], v[130:131], v[134:135], v[128:129] op_sel_hi:[0,1,1]
	v_pk_fma_f32 v[126:127], v[130:131], v[136:137], v[126:127] op_sel_hi:[0,1,1]
	v_pk_fma_f32 v[122:123], v[130:131], v[138:139], v[122:123] op_sel_hi:[0,1,1]
	v_pk_fma_f32 v[120:121], v[130:131], v[140:141], v[120:121] op_sel_hi:[0,1,1]
	v_cvt_scalef32_pk_f32_fp4 v[134:135], v23, 1.0
	v_cvt_scalef32_pk_f32_fp4 v[136:137], v23, 1.0 op_sel:[1,0,0]
	v_cvt_scalef32_pk_f32_fp4 v[138:139], v23, 1.0 op_sel:[0,1,0]
	v_cvt_scalef32_pk_f32_fp4 v[140:141], v23, 1.0 op_sel:[1,1,0]
	v_pk_fma_f32 v[118:119], v[130:131], v[134:135], v[118:119] op_sel_hi:[0,1,1]
	v_pk_fma_f32 v[116:117], v[130:131], v[136:137], v[116:117] op_sel_hi:[0,1,1]
	v_pk_fma_f32 v[114:115], v[130:131], v[138:139], v[114:115] op_sel_hi:[0,1,1]
	v_pk_fma_f32 v[112:113], v[130:131], v[140:141], v[112:113] op_sel_hi:[0,1,1]
	v_cvt_scalef32_pk_f32_fp4 v[134:135], v24, 1.0
	v_cvt_scalef32_pk_f32_fp4 v[136:137], v24, 1.0 op_sel:[1,0,0]
	v_cvt_scalef32_pk_f32_fp4 v[138:139], v24, 1.0 op_sel:[0,1,0]
	v_cvt_scalef32_pk_f32_fp4 v[140:141], v24, 1.0 op_sel:[1,1,0]
	v_pk_fma_f32 v[80:81], v[130:131], v[134:135], v[80:81] op_sel_hi:[0,1,1]
	v_pk_fma_f32 v[78:79], v[130:131], v[136:137], v[78:79] op_sel_hi:[0,1,1]
	v_pk_fma_f32 v[76:77], v[130:131], v[138:139], v[76:77] op_sel_hi:[0,1,1]
	v_pk_fma_f32 v[74:75], v[130:131], v[140:141], v[74:75] op_sel_hi:[0,1,1]
	v_cvt_scalef32_pk_f32_fp4 v[134:135], v25, 1.0
	v_cvt_scalef32_pk_f32_fp4 v[136:137], v25, 1.0 op_sel:[1,0,0]
	v_cvt_scalef32_pk_f32_fp4 v[138:139], v25, 1.0 op_sel:[0,1,0]
	v_cvt_scalef32_pk_f32_fp4 v[140:141], v25, 1.0 op_sel:[1,1,0]
	v_pk_fma_f32 v[72:73], v[130:131], v[134:135], v[72:73] op_sel_hi:[0,1,1]
	v_pk_fma_f32 v[70:71], v[130:131], v[136:137], v[70:71] op_sel_hi:[0,1,1]
	v_pk_fma_f32 v[68:69], v[130:131], v[138:139], v[68:69] op_sel_hi:[0,1,1]
	v_pk_fma_f32 v[66:67], v[130:131], v[140:141], v[66:67] op_sel_hi:[0,1,1]
	s_waitcnt vmcnt(14)
	v_cvt_scalef32_pk_f32_fp4 v[134:135], v18, 1.0
	v_cvt_scalef32_pk_f32_fp4 v[136:137], v18, 1.0 op_sel:[1,0,0]
	v_cvt_scalef32_pk_f32_fp4 v[138:139], v18, 1.0 op_sel:[0,1,0]
	v_cvt_scalef32_pk_f32_fp4 v[140:141], v18, 1.0 op_sel:[1,1,0]
	v_pk_fma_f32 v[34:35], v[130:131], v[134:135], v[34:35] op_sel_hi:[0,1,1]
	v_pk_fma_f32 v[36:37], v[130:131], v[136:137], v[36:37] op_sel_hi:[0,1,1]
	v_pk_fma_f32 v[38:39], v[130:131], v[138:139], v[38:39] op_sel_hi:[0,1,1]
	v_pk_fma_f32 v[40:41], v[130:131], v[140:141], v[40:41] op_sel_hi:[0,1,1]
	v_cvt_scalef32_pk_f32_fp4 v[134:135], v19, 1.0
	v_cvt_scalef32_pk_f32_fp4 v[136:137], v19, 1.0 op_sel:[1,0,0]
	v_cvt_scalef32_pk_f32_fp4 v[138:139], v19, 1.0 op_sel:[0,1,0]
	v_cvt_scalef32_pk_f32_fp4 v[140:141], v19, 1.0 op_sel:[1,1,0]
	v_pk_fma_f32 v[42:43], v[130:131], v[134:135], v[42:43] op_sel_hi:[0,1,1]
	v_pk_fma_f32 v[44:45], v[130:131], v[136:137], v[44:45] op_sel_hi:[0,1,1]
	v_pk_fma_f32 v[46:47], v[130:131], v[138:139], v[46:47] op_sel_hi:[0,1,1]
	v_pk_fma_f32 v[48:49], v[130:131], v[140:141], v[48:49] op_sel_hi:[0,1,1]
	v_cvt_scalef32_pk_f32_fp4 v[134:135], v20, 1.0
	v_cvt_scalef32_pk_f32_fp4 v[136:137], v20, 1.0 op_sel:[1,0,0]
	v_cvt_scalef32_pk_f32_fp4 v[138:139], v20, 1.0 op_sel:[0,1,0]
	v_cvt_scalef32_pk_f32_fp4 v[140:141], v20, 1.0 op_sel:[1,1,0]
	v_pk_fma_f32 v[50:51], v[130:131], v[134:135], v[50:51] op_sel_hi:[0,1,1]
	v_pk_fma_f32 v[52:53], v[130:131], v[136:137], v[52:53] op_sel_hi:[0,1,1]
	v_pk_fma_f32 v[54:55], v[130:131], v[138:139], v[54:55] op_sel_hi:[0,1,1]
	v_pk_fma_f32 v[56:57], v[130:131], v[140:141], v[56:57] op_sel_hi:[0,1,1]
	v_cvt_scalef32_pk_f32_fp4 v[134:135], v21, 1.0
	v_cvt_scalef32_pk_f32_fp4 v[136:137], v21, 1.0 op_sel:[1,0,0]
	v_cvt_scalef32_pk_f32_fp4 v[138:139], v21, 1.0 op_sel:[0,1,0]
	v_cvt_scalef32_pk_f32_fp4 v[140:141], v21, 1.0 op_sel:[1,1,0]
	v_pk_fma_f32 v[58:59], v[130:131], v[134:135], v[58:59] op_sel_hi:[0,1,1]
	v_pk_fma_f32 v[60:61], v[130:131], v[136:137], v[60:61] op_sel_hi:[0,1,1]
	v_pk_fma_f32 v[62:63], v[130:131], v[138:139], v[62:63] op_sel_hi:[0,1,1]
	v_pk_fma_f32 v[64:65], v[130:131], v[140:141], v[64:65] op_sel_hi:[0,1,1]
	v_mad_u64_u32 v[248:249], vcc, v227, s0, v[86:87]
	global_load_dwordx4 v[22:25], v[248:249], off
	global_load_dwordx4 v[18:21], v[248:249], off offset:256
	ds_read_b32 v250, v131 offset:48
	ds_read_b32 v130, v132 offset:48
	s_waitcnt vmcnt(15)
	v_cvt_scalef32_pk_f32_fp4 v[134:135], v30, 1.0
	v_cvt_scalef32_pk_f32_fp4 v[136:137], v30, 1.0 op_sel:[1,0,0]
	v_cvt_scalef32_pk_f32_fp4 v[138:139], v30, 1.0 op_sel:[0,1,0]
	v_cvt_scalef32_pk_f32_fp4 v[140:141], v30, 1.0 op_sel:[1,1,0]
	s_waitcnt lgkmcnt(0)
	v_pk_fma_f32 v[128:129], v[130:131], v[134:135], v[128:129] op_sel_hi:[0,1,1]
	v_pk_fma_f32 v[126:127], v[130:131], v[136:137], v[126:127] op_sel_hi:[0,1,1]
	v_pk_fma_f32 v[122:123], v[130:131], v[138:139], v[122:123] op_sel_hi:[0,1,1]
	v_pk_fma_f32 v[120:121], v[130:131], v[140:141], v[120:121] op_sel_hi:[0,1,1]
	v_cvt_scalef32_pk_f32_fp4 v[134:135], v31, 1.0
	v_cvt_scalef32_pk_f32_fp4 v[136:137], v31, 1.0 op_sel:[1,0,0]
	v_cvt_scalef32_pk_f32_fp4 v[138:139], v31, 1.0 op_sel:[0,1,0]
	v_cvt_scalef32_pk_f32_fp4 v[140:141], v31, 1.0 op_sel:[1,1,0]
	v_pk_fma_f32 v[118:119], v[130:131], v[134:135], v[118:119] op_sel_hi:[0,1,1]
	v_pk_fma_f32 v[116:117], v[130:131], v[136:137], v[116:117] op_sel_hi:[0,1,1]
	v_pk_fma_f32 v[114:115], v[130:131], v[138:139], v[114:115] op_sel_hi:[0,1,1]
	v_pk_fma_f32 v[112:113], v[130:131], v[140:141], v[112:113] op_sel_hi:[0,1,1]
	v_cvt_scalef32_pk_f32_fp4 v[134:135], v32, 1.0
	v_cvt_scalef32_pk_f32_fp4 v[136:137], v32, 1.0 op_sel:[1,0,0]
	v_cvt_scalef32_pk_f32_fp4 v[138:139], v32, 1.0 op_sel:[0,1,0]
	v_cvt_scalef32_pk_f32_fp4 v[140:141], v32, 1.0 op_sel:[1,1,0]
	v_pk_fma_f32 v[80:81], v[130:131], v[134:135], v[80:81] op_sel_hi:[0,1,1]
	v_pk_fma_f32 v[78:79], v[130:131], v[136:137], v[78:79] op_sel_hi:[0,1,1]
	v_pk_fma_f32 v[76:77], v[130:131], v[138:139], v[76:77] op_sel_hi:[0,1,1]
	v_pk_fma_f32 v[74:75], v[130:131], v[140:141], v[74:75] op_sel_hi:[0,1,1]
	v_cvt_scalef32_pk_f32_fp4 v[134:135], v33, 1.0
	v_cvt_scalef32_pk_f32_fp4 v[136:137], v33, 1.0 op_sel:[1,0,0]
	v_cvt_scalef32_pk_f32_fp4 v[138:139], v33, 1.0 op_sel:[0,1,0]
	v_cvt_scalef32_pk_f32_fp4 v[140:141], v33, 1.0 op_sel:[1,1,0]
	v_pk_fma_f32 v[72:73], v[130:131], v[134:135], v[72:73] op_sel_hi:[0,1,1]
	v_pk_fma_f32 v[70:71], v[130:131], v[136:137], v[70:71] op_sel_hi:[0,1,1]
	v_pk_fma_f32 v[68:69], v[130:131], v[138:139], v[68:69] op_sel_hi:[0,1,1]
	v_pk_fma_f32 v[66:67], v[130:131], v[140:141], v[66:67] op_sel_hi:[0,1,1]
	s_waitcnt vmcnt(14)
	v_cvt_scalef32_pk_f32_fp4 v[134:135], v26, 1.0
	v_cvt_scalef32_pk_f32_fp4 v[136:137], v26, 1.0 op_sel:[1,0,0]
	v_cvt_scalef32_pk_f32_fp4 v[138:139], v26, 1.0 op_sel:[0,1,0]
	v_cvt_scalef32_pk_f32_fp4 v[140:141], v26, 1.0 op_sel:[1,1,0]
	v_pk_fma_f32 v[34:35], v[130:131], v[134:135], v[34:35] op_sel_hi:[0,1,1]
	v_pk_fma_f32 v[36:37], v[130:131], v[136:137], v[36:37] op_sel_hi:[0,1,1]
	v_pk_fma_f32 v[38:39], v[130:131], v[138:139], v[38:39] op_sel_hi:[0,1,1]
	v_pk_fma_f32 v[40:41], v[130:131], v[140:141], v[40:41] op_sel_hi:[0,1,1]
	v_cvt_scalef32_pk_f32_fp4 v[134:135], v27, 1.0
	v_cvt_scalef32_pk_f32_fp4 v[136:137], v27, 1.0 op_sel:[1,0,0]
	v_cvt_scalef32_pk_f32_fp4 v[138:139], v27, 1.0 op_sel:[0,1,0]
	v_cvt_scalef32_pk_f32_fp4 v[140:141], v27, 1.0 op_sel:[1,1,0]
	v_pk_fma_f32 v[42:43], v[130:131], v[134:135], v[42:43] op_sel_hi:[0,1,1]
	v_pk_fma_f32 v[44:45], v[130:131], v[136:137], v[44:45] op_sel_hi:[0,1,1]
	v_pk_fma_f32 v[46:47], v[130:131], v[138:139], v[46:47] op_sel_hi:[0,1,1]
	v_pk_fma_f32 v[48:49], v[130:131], v[140:141], v[48:49] op_sel_hi:[0,1,1]
	v_cvt_scalef32_pk_f32_fp4 v[134:135], v28, 1.0
	v_cvt_scalef32_pk_f32_fp4 v[136:137], v28, 1.0 op_sel:[1,0,0]
	v_cvt_scalef32_pk_f32_fp4 v[138:139], v28, 1.0 op_sel:[0,1,0]
	v_cvt_scalef32_pk_f32_fp4 v[140:141], v28, 1.0 op_sel:[1,1,0]
	v_pk_fma_f32 v[50:51], v[130:131], v[134:135], v[50:51] op_sel_hi:[0,1,1]
	v_pk_fma_f32 v[52:53], v[130:131], v[136:137], v[52:53] op_sel_hi:[0,1,1]
	v_pk_fma_f32 v[54:55], v[130:131], v[138:139], v[54:55] op_sel_hi:[0,1,1]
	v_pk_fma_f32 v[56:57], v[130:131], v[140:141], v[56:57] op_sel_hi:[0,1,1]
	v_cvt_scalef32_pk_f32_fp4 v[134:135], v29, 1.0
	v_cvt_scalef32_pk_f32_fp4 v[136:137], v29, 1.0 op_sel:[1,0,0]
	v_cvt_scalef32_pk_f32_fp4 v[138:139], v29, 1.0 op_sel:[0,1,0]
	v_cvt_scalef32_pk_f32_fp4 v[140:141], v29, 1.0 op_sel:[1,1,0]
	v_pk_fma_f32 v[58:59], v[130:131], v[134:135], v[58:59] op_sel_hi:[0,1,1]
	v_pk_fma_f32 v[60:61], v[130:131], v[136:137], v[60:61] op_sel_hi:[0,1,1]
	v_pk_fma_f32 v[62:63], v[130:131], v[138:139], v[62:63] op_sel_hi:[0,1,1]
	v_pk_fma_f32 v[64:65], v[130:131], v[140:141], v[64:65] op_sel_hi:[0,1,1]
	v_mad_u64_u32 v[248:249], vcc, v250, s0, v[86:87]
	global_load_dwordx4 v[30:33], v[248:249], off
	global_load_dwordx4 v[26:29], v[248:249], off offset:256
	ds_read_b32 v227, v131 offset:64
	ds_read_b32 v130, v132 offset:64
	s_waitcnt vmcnt(15)
	v_cvt_scalef32_pk_f32_fp4 v[134:135], v142, 1.0
	v_cvt_scalef32_pk_f32_fp4 v[136:137], v142, 1.0 op_sel:[1,0,0]
	v_cvt_scalef32_pk_f32_fp4 v[138:139], v142, 1.0 op_sel:[0,1,0]
	v_cvt_scalef32_pk_f32_fp4 v[140:141], v142, 1.0 op_sel:[1,1,0]
	s_waitcnt lgkmcnt(0)
	v_pk_fma_f32 v[128:129], v[130:131], v[134:135], v[128:129] op_sel_hi:[0,1,1]
	v_pk_fma_f32 v[126:127], v[130:131], v[136:137], v[126:127] op_sel_hi:[0,1,1]
	v_pk_fma_f32 v[122:123], v[130:131], v[138:139], v[122:123] op_sel_hi:[0,1,1]
	v_pk_fma_f32 v[120:121], v[130:131], v[140:141], v[120:121] op_sel_hi:[0,1,1]
	v_cvt_scalef32_pk_f32_fp4 v[134:135], v143, 1.0
	v_cvt_scalef32_pk_f32_fp4 v[136:137], v143, 1.0 op_sel:[1,0,0]
	v_cvt_scalef32_pk_f32_fp4 v[138:139], v143, 1.0 op_sel:[0,1,0]
	v_cvt_scalef32_pk_f32_fp4 v[140:141], v143, 1.0 op_sel:[1,1,0]
	v_pk_fma_f32 v[118:119], v[130:131], v[134:135], v[118:119] op_sel_hi:[0,1,1]
	v_pk_fma_f32 v[116:117], v[130:131], v[136:137], v[116:117] op_sel_hi:[0,1,1]
	v_pk_fma_f32 v[114:115], v[130:131], v[138:139], v[114:115] op_sel_hi:[0,1,1]
	v_pk_fma_f32 v[112:113], v[130:131], v[140:141], v[112:113] op_sel_hi:[0,1,1]
	v_cvt_scalef32_pk_f32_fp4 v[134:135], v144, 1.0
	v_cvt_scalef32_pk_f32_fp4 v[136:137], v144, 1.0 op_sel:[1,0,0]
	v_cvt_scalef32_pk_f32_fp4 v[138:139], v144, 1.0 op_sel:[0,1,0]
	v_cvt_scalef32_pk_f32_fp4 v[140:141], v144, 1.0 op_sel:[1,1,0]
	v_pk_fma_f32 v[80:81], v[130:131], v[134:135], v[80:81] op_sel_hi:[0,1,1]
	v_pk_fma_f32 v[78:79], v[130:131], v[136:137], v[78:79] op_sel_hi:[0,1,1]
	v_pk_fma_f32 v[76:77], v[130:131], v[138:139], v[76:77] op_sel_hi:[0,1,1]
	v_pk_fma_f32 v[74:75], v[130:131], v[140:141], v[74:75] op_sel_hi:[0,1,1]
	v_cvt_scalef32_pk_f32_fp4 v[134:135], v145, 1.0
	v_cvt_scalef32_pk_f32_fp4 v[136:137], v145, 1.0 op_sel:[1,0,0]
	v_cvt_scalef32_pk_f32_fp4 v[138:139], v145, 1.0 op_sel:[0,1,0]
	v_cvt_scalef32_pk_f32_fp4 v[140:141], v145, 1.0 op_sel:[1,1,0]
	v_pk_fma_f32 v[72:73], v[130:131], v[134:135], v[72:73] op_sel_hi:[0,1,1]
	v_pk_fma_f32 v[70:71], v[130:131], v[136:137], v[70:71] op_sel_hi:[0,1,1]
	v_pk_fma_f32 v[68:69], v[130:131], v[138:139], v[68:69] op_sel_hi:[0,1,1]
	v_pk_fma_f32 v[66:67], v[130:131], v[140:141], v[66:67] op_sel_hi:[0,1,1]
	s_waitcnt vmcnt(14)
	v_cvt_scalef32_pk_f32_fp4 v[134:135], v146, 1.0
	v_cvt_scalef32_pk_f32_fp4 v[136:137], v146, 1.0 op_sel:[1,0,0]
	v_cvt_scalef32_pk_f32_fp4 v[138:139], v146, 1.0 op_sel:[0,1,0]
	v_cvt_scalef32_pk_f32_fp4 v[140:141], v146, 1.0 op_sel:[1,1,0]
	v_pk_fma_f32 v[34:35], v[130:131], v[134:135], v[34:35] op_sel_hi:[0,1,1]
	v_pk_fma_f32 v[36:37], v[130:131], v[136:137], v[36:37] op_sel_hi:[0,1,1]
	v_pk_fma_f32 v[38:39], v[130:131], v[138:139], v[38:39] op_sel_hi:[0,1,1]
	v_pk_fma_f32 v[40:41], v[130:131], v[140:141], v[40:41] op_sel_hi:[0,1,1]
	v_cvt_scalef32_pk_f32_fp4 v[134:135], v147, 1.0
	v_cvt_scalef32_pk_f32_fp4 v[136:137], v147, 1.0 op_sel:[1,0,0]
	v_cvt_scalef32_pk_f32_fp4 v[138:139], v147, 1.0 op_sel:[0,1,0]
	v_cvt_scalef32_pk_f32_fp4 v[140:141], v147, 1.0 op_sel:[1,1,0]
	v_pk_fma_f32 v[42:43], v[130:131], v[134:135], v[42:43] op_sel_hi:[0,1,1]
	v_pk_fma_f32 v[44:45], v[130:131], v[136:137], v[44:45] op_sel_hi:[0,1,1]
	v_pk_fma_f32 v[46:47], v[130:131], v[138:139], v[46:47] op_sel_hi:[0,1,1]
	v_pk_fma_f32 v[48:49], v[130:131], v[140:141], v[48:49] op_sel_hi:[0,1,1]
	v_cvt_scalef32_pk_f32_fp4 v[134:135], v148, 1.0
	v_cvt_scalef32_pk_f32_fp4 v[136:137], v148, 1.0 op_sel:[1,0,0]
	v_cvt_scalef32_pk_f32_fp4 v[138:139], v148, 1.0 op_sel:[0,1,0]
	v_cvt_scalef32_pk_f32_fp4 v[140:141], v148, 1.0 op_sel:[1,1,0]
	v_pk_fma_f32 v[50:51], v[130:131], v[134:135], v[50:51] op_sel_hi:[0,1,1]
	v_pk_fma_f32 v[52:53], v[130:131], v[136:137], v[52:53] op_sel_hi:[0,1,1]
	v_pk_fma_f32 v[54:55], v[130:131], v[138:139], v[54:55] op_sel_hi:[0,1,1]
	v_pk_fma_f32 v[56:57], v[130:131], v[140:141], v[56:57] op_sel_hi:[0,1,1]
	v_cvt_scalef32_pk_f32_fp4 v[134:135], v149, 1.0
	v_cvt_scalef32_pk_f32_fp4 v[136:137], v149, 1.0 op_sel:[1,0,0]
	v_cvt_scalef32_pk_f32_fp4 v[138:139], v149, 1.0 op_sel:[0,1,0]
	v_cvt_scalef32_pk_f32_fp4 v[140:141], v149, 1.0 op_sel:[1,1,0]
	v_pk_fma_f32 v[58:59], v[130:131], v[134:135], v[58:59] op_sel_hi:[0,1,1]
	v_pk_fma_f32 v[60:61], v[130:131], v[136:137], v[60:61] op_sel_hi:[0,1,1]
	v_pk_fma_f32 v[62:63], v[130:131], v[138:139], v[62:63] op_sel_hi:[0,1,1]
	v_pk_fma_f32 v[64:65], v[130:131], v[140:141], v[64:65] op_sel_hi:[0,1,1]
	v_mad_u64_u32 v[248:249], vcc, v227, s0, v[86:87]
	global_load_dwordx4 v[142:145], v[248:249], off
	global_load_dwordx4 v[146:149], v[248:249], off offset:256
	ds_read_b32 v250, v131 offset:80
	ds_read_b32 v130, v132 offset:80
	s_waitcnt vmcnt(15)
	v_cvt_scalef32_pk_f32_fp4 v[134:135], v150, 1.0
	v_cvt_scalef32_pk_f32_fp4 v[136:137], v150, 1.0 op_sel:[1,0,0]
	v_cvt_scalef32_pk_f32_fp4 v[138:139], v150, 1.0 op_sel:[0,1,0]
	v_cvt_scalef32_pk_f32_fp4 v[140:141], v150, 1.0 op_sel:[1,1,0]
	s_waitcnt lgkmcnt(0)
	v_pk_fma_f32 v[128:129], v[130:131], v[134:135], v[128:129] op_sel_hi:[0,1,1]
	v_pk_fma_f32 v[126:127], v[130:131], v[136:137], v[126:127] op_sel_hi:[0,1,1]
	v_pk_fma_f32 v[122:123], v[130:131], v[138:139], v[122:123] op_sel_hi:[0,1,1]
	v_pk_fma_f32 v[120:121], v[130:131], v[140:141], v[120:121] op_sel_hi:[0,1,1]
	v_cvt_scalef32_pk_f32_fp4 v[134:135], v151, 1.0
	v_cvt_scalef32_pk_f32_fp4 v[136:137], v151, 1.0 op_sel:[1,0,0]
	v_cvt_scalef32_pk_f32_fp4 v[138:139], v151, 1.0 op_sel:[0,1,0]
	v_cvt_scalef32_pk_f32_fp4 v[140:141], v151, 1.0 op_sel:[1,1,0]
	v_pk_fma_f32 v[118:119], v[130:131], v[134:135], v[118:119] op_sel_hi:[0,1,1]
	v_pk_fma_f32 v[116:117], v[130:131], v[136:137], v[116:117] op_sel_hi:[0,1,1]
	v_pk_fma_f32 v[114:115], v[130:131], v[138:139], v[114:115] op_sel_hi:[0,1,1]
	v_pk_fma_f32 v[112:113], v[130:131], v[140:141], v[112:113] op_sel_hi:[0,1,1]
	v_cvt_scalef32_pk_f32_fp4 v[134:135], v152, 1.0
	v_cvt_scalef32_pk_f32_fp4 v[136:137], v152, 1.0 op_sel:[1,0,0]
	v_cvt_scalef32_pk_f32_fp4 v[138:139], v152, 1.0 op_sel:[0,1,0]
	v_cvt_scalef32_pk_f32_fp4 v[140:141], v152, 1.0 op_sel:[1,1,0]
	v_pk_fma_f32 v[80:81], v[130:131], v[134:135], v[80:81] op_sel_hi:[0,1,1]
	v_pk_fma_f32 v[78:79], v[130:131], v[136:137], v[78:79] op_sel_hi:[0,1,1]
	v_pk_fma_f32 v[76:77], v[130:131], v[138:139], v[76:77] op_sel_hi:[0,1,1]
	v_pk_fma_f32 v[74:75], v[130:131], v[140:141], v[74:75] op_sel_hi:[0,1,1]
	v_cvt_scalef32_pk_f32_fp4 v[134:135], v153, 1.0
	v_cvt_scalef32_pk_f32_fp4 v[136:137], v153, 1.0 op_sel:[1,0,0]
	v_cvt_scalef32_pk_f32_fp4 v[138:139], v153, 1.0 op_sel:[0,1,0]
	v_cvt_scalef32_pk_f32_fp4 v[140:141], v153, 1.0 op_sel:[1,1,0]
	v_pk_fma_f32 v[72:73], v[130:131], v[134:135], v[72:73] op_sel_hi:[0,1,1]
	v_pk_fma_f32 v[70:71], v[130:131], v[136:137], v[70:71] op_sel_hi:[0,1,1]
	v_pk_fma_f32 v[68:69], v[130:131], v[138:139], v[68:69] op_sel_hi:[0,1,1]
	v_pk_fma_f32 v[66:67], v[130:131], v[140:141], v[66:67] op_sel_hi:[0,1,1]
	s_waitcnt vmcnt(14)
	v_cvt_scalef32_pk_f32_fp4 v[134:135], v232, 1.0
	v_cvt_scalef32_pk_f32_fp4 v[136:137], v232, 1.0 op_sel:[1,0,0]
	v_cvt_scalef32_pk_f32_fp4 v[138:139], v232, 1.0 op_sel:[0,1,0]
	v_cvt_scalef32_pk_f32_fp4 v[140:141], v232, 1.0 op_sel:[1,1,0]
	v_pk_fma_f32 v[34:35], v[130:131], v[134:135], v[34:35] op_sel_hi:[0,1,1]
	v_pk_fma_f32 v[36:37], v[130:131], v[136:137], v[36:37] op_sel_hi:[0,1,1]
	v_pk_fma_f32 v[38:39], v[130:131], v[138:139], v[38:39] op_sel_hi:[0,1,1]
	v_pk_fma_f32 v[40:41], v[130:131], v[140:141], v[40:41] op_sel_hi:[0,1,1]
	v_cvt_scalef32_pk_f32_fp4 v[134:135], v233, 1.0
	v_cvt_scalef32_pk_f32_fp4 v[136:137], v233, 1.0 op_sel:[1,0,0]
	v_cvt_scalef32_pk_f32_fp4 v[138:139], v233, 1.0 op_sel:[0,1,0]
	v_cvt_scalef32_pk_f32_fp4 v[140:141], v233, 1.0 op_sel:[1,1,0]
	v_pk_fma_f32 v[42:43], v[130:131], v[134:135], v[42:43] op_sel_hi:[0,1,1]
	v_pk_fma_f32 v[44:45], v[130:131], v[136:137], v[44:45] op_sel_hi:[0,1,1]
	v_pk_fma_f32 v[46:47], v[130:131], v[138:139], v[46:47] op_sel_hi:[0,1,1]
	v_pk_fma_f32 v[48:49], v[130:131], v[140:141], v[48:49] op_sel_hi:[0,1,1]
	v_cvt_scalef32_pk_f32_fp4 v[134:135], v234, 1.0
	v_cvt_scalef32_pk_f32_fp4 v[136:137], v234, 1.0 op_sel:[1,0,0]
	v_cvt_scalef32_pk_f32_fp4 v[138:139], v234, 1.0 op_sel:[0,1,0]
	v_cvt_scalef32_pk_f32_fp4 v[140:141], v234, 1.0 op_sel:[1,1,0]
	v_pk_fma_f32 v[50:51], v[130:131], v[134:135], v[50:51] op_sel_hi:[0,1,1]
	v_pk_fma_f32 v[52:53], v[130:131], v[136:137], v[52:53] op_sel_hi:[0,1,1]
	v_pk_fma_f32 v[54:55], v[130:131], v[138:139], v[54:55] op_sel_hi:[0,1,1]
	v_pk_fma_f32 v[56:57], v[130:131], v[140:141], v[56:57] op_sel_hi:[0,1,1]
	v_cvt_scalef32_pk_f32_fp4 v[134:135], v235, 1.0
	v_cvt_scalef32_pk_f32_fp4 v[136:137], v235, 1.0 op_sel:[1,0,0]
	v_cvt_scalef32_pk_f32_fp4 v[138:139], v235, 1.0 op_sel:[0,1,0]
	v_cvt_scalef32_pk_f32_fp4 v[140:141], v235, 1.0 op_sel:[1,1,0]
	v_pk_fma_f32 v[58:59], v[130:131], v[134:135], v[58:59] op_sel_hi:[0,1,1]
	v_pk_fma_f32 v[60:61], v[130:131], v[136:137], v[60:61] op_sel_hi:[0,1,1]
	v_pk_fma_f32 v[62:63], v[130:131], v[138:139], v[62:63] op_sel_hi:[0,1,1]
	v_pk_fma_f32 v[64:65], v[130:131], v[140:141], v[64:65] op_sel_hi:[0,1,1]
	v_mad_u64_u32 v[248:249], vcc, v250, s0, v[86:87]
	global_load_dwordx4 v[150:153], v[248:249], off
	global_load_dwordx4 v[232:235], v[248:249], off offset:256
	ds_read_b32 v227, v131 offset:96
	ds_read_b32 v130, v132 offset:96
	s_waitcnt vmcnt(15)
	v_cvt_scalef32_pk_f32_fp4 v[134:135], v236, 1.0
	v_cvt_scalef32_pk_f32_fp4 v[136:137], v236, 1.0 op_sel:[1,0,0]
	v_cvt_scalef32_pk_f32_fp4 v[138:139], v236, 1.0 op_sel:[0,1,0]
	v_cvt_scalef32_pk_f32_fp4 v[140:141], v236, 1.0 op_sel:[1,1,0]
	s_waitcnt lgkmcnt(0)
	v_pk_fma_f32 v[128:129], v[130:131], v[134:135], v[128:129] op_sel_hi:[0,1,1]
	v_pk_fma_f32 v[126:127], v[130:131], v[136:137], v[126:127] op_sel_hi:[0,1,1]
	v_pk_fma_f32 v[122:123], v[130:131], v[138:139], v[122:123] op_sel_hi:[0,1,1]
	v_pk_fma_f32 v[120:121], v[130:131], v[140:141], v[120:121] op_sel_hi:[0,1,1]
	v_cvt_scalef32_pk_f32_fp4 v[134:135], v237, 1.0
	v_cvt_scalef32_pk_f32_fp4 v[136:137], v237, 1.0 op_sel:[1,0,0]
	v_cvt_scalef32_pk_f32_fp4 v[138:139], v237, 1.0 op_sel:[0,1,0]
	v_cvt_scalef32_pk_f32_fp4 v[140:141], v237, 1.0 op_sel:[1,1,0]
	v_pk_fma_f32 v[118:119], v[130:131], v[134:135], v[118:119] op_sel_hi:[0,1,1]
	v_pk_fma_f32 v[116:117], v[130:131], v[136:137], v[116:117] op_sel_hi:[0,1,1]
	v_pk_fma_f32 v[114:115], v[130:131], v[138:139], v[114:115] op_sel_hi:[0,1,1]
	v_pk_fma_f32 v[112:113], v[130:131], v[140:141], v[112:113] op_sel_hi:[0,1,1]
	v_cvt_scalef32_pk_f32_fp4 v[134:135], v238, 1.0
	v_cvt_scalef32_pk_f32_fp4 v[136:137], v238, 1.0 op_sel:[1,0,0]
	v_cvt_scalef32_pk_f32_fp4 v[138:139], v238, 1.0 op_sel:[0,1,0]
	v_cvt_scalef32_pk_f32_fp4 v[140:141], v238, 1.0 op_sel:[1,1,0]
	v_pk_fma_f32 v[80:81], v[130:131], v[134:135], v[80:81] op_sel_hi:[0,1,1]
	v_pk_fma_f32 v[78:79], v[130:131], v[136:137], v[78:79] op_sel_hi:[0,1,1]
	v_pk_fma_f32 v[76:77], v[130:131], v[138:139], v[76:77] op_sel_hi:[0,1,1]
	v_pk_fma_f32 v[74:75], v[130:131], v[140:141], v[74:75] op_sel_hi:[0,1,1]
	v_cvt_scalef32_pk_f32_fp4 v[134:135], v239, 1.0
	v_cvt_scalef32_pk_f32_fp4 v[136:137], v239, 1.0 op_sel:[1,0,0]
	v_cvt_scalef32_pk_f32_fp4 v[138:139], v239, 1.0 op_sel:[0,1,0]
	v_cvt_scalef32_pk_f32_fp4 v[140:141], v239, 1.0 op_sel:[1,1,0]
	v_pk_fma_f32 v[72:73], v[130:131], v[134:135], v[72:73] op_sel_hi:[0,1,1]
	v_pk_fma_f32 v[70:71], v[130:131], v[136:137], v[70:71] op_sel_hi:[0,1,1]
	v_pk_fma_f32 v[68:69], v[130:131], v[138:139], v[68:69] op_sel_hi:[0,1,1]
	v_pk_fma_f32 v[66:67], v[130:131], v[140:141], v[66:67] op_sel_hi:[0,1,1]
	s_waitcnt vmcnt(14)
	v_cvt_scalef32_pk_f32_fp4 v[134:135], v240, 1.0
	v_cvt_scalef32_pk_f32_fp4 v[136:137], v240, 1.0 op_sel:[1,0,0]
	v_cvt_scalef32_pk_f32_fp4 v[138:139], v240, 1.0 op_sel:[0,1,0]
	v_cvt_scalef32_pk_f32_fp4 v[140:141], v240, 1.0 op_sel:[1,1,0]
	v_pk_fma_f32 v[34:35], v[130:131], v[134:135], v[34:35] op_sel_hi:[0,1,1]
	v_pk_fma_f32 v[36:37], v[130:131], v[136:137], v[36:37] op_sel_hi:[0,1,1]
	v_pk_fma_f32 v[38:39], v[130:131], v[138:139], v[38:39] op_sel_hi:[0,1,1]
	v_pk_fma_f32 v[40:41], v[130:131], v[140:141], v[40:41] op_sel_hi:[0,1,1]
	v_cvt_scalef32_pk_f32_fp4 v[134:135], v241, 1.0
	v_cvt_scalef32_pk_f32_fp4 v[136:137], v241, 1.0 op_sel:[1,0,0]
	v_cvt_scalef32_pk_f32_fp4 v[138:139], v241, 1.0 op_sel:[0,1,0]
	v_cvt_scalef32_pk_f32_fp4 v[140:141], v241, 1.0 op_sel:[1,1,0]
	v_pk_fma_f32 v[42:43], v[130:131], v[134:135], v[42:43] op_sel_hi:[0,1,1]
	v_pk_fma_f32 v[44:45], v[130:131], v[136:137], v[44:45] op_sel_hi:[0,1,1]
	v_pk_fma_f32 v[46:47], v[130:131], v[138:139], v[46:47] op_sel_hi:[0,1,1]
	v_pk_fma_f32 v[48:49], v[130:131], v[140:141], v[48:49] op_sel_hi:[0,1,1]
	v_cvt_scalef32_pk_f32_fp4 v[134:135], v242, 1.0
	v_cvt_scalef32_pk_f32_fp4 v[136:137], v242, 1.0 op_sel:[1,0,0]
	v_cvt_scalef32_pk_f32_fp4 v[138:139], v242, 1.0 op_sel:[0,1,0]
	v_cvt_scalef32_pk_f32_fp4 v[140:141], v242, 1.0 op_sel:[1,1,0]
	v_pk_fma_f32 v[50:51], v[130:131], v[134:135], v[50:51] op_sel_hi:[0,1,1]
	v_pk_fma_f32 v[52:53], v[130:131], v[136:137], v[52:53] op_sel_hi:[0,1,1]
	v_pk_fma_f32 v[54:55], v[130:131], v[138:139], v[54:55] op_sel_hi:[0,1,1]
	v_pk_fma_f32 v[56:57], v[130:131], v[140:141], v[56:57] op_sel_hi:[0,1,1]
	v_cvt_scalef32_pk_f32_fp4 v[134:135], v243, 1.0
	v_cvt_scalef32_pk_f32_fp4 v[136:137], v243, 1.0 op_sel:[1,0,0]
	v_cvt_scalef32_pk_f32_fp4 v[138:139], v243, 1.0 op_sel:[0,1,0]
	v_cvt_scalef32_pk_f32_fp4 v[140:141], v243, 1.0 op_sel:[1,1,0]
	v_pk_fma_f32 v[58:59], v[130:131], v[134:135], v[58:59] op_sel_hi:[0,1,1]
	v_pk_fma_f32 v[60:61], v[130:131], v[136:137], v[60:61] op_sel_hi:[0,1,1]
	v_pk_fma_f32 v[62:63], v[130:131], v[138:139], v[62:63] op_sel_hi:[0,1,1]
	v_pk_fma_f32 v[64:65], v[130:131], v[140:141], v[64:65] op_sel_hi:[0,1,1]
	v_mad_u64_u32 v[248:249], vcc, v227, s0, v[86:87]
	global_load_dwordx4 v[236:239], v[248:249], off
	global_load_dwordx4 v[240:243], v[248:249], off offset:256
	ds_read_b32 v250, v131 offset:112
	ds_read_b32 v130, v132 offset:112
	s_waitcnt vmcnt(15)
	v_cvt_scalef32_pk_f32_fp4 v[134:135], v244, 1.0
	v_cvt_scalef32_pk_f32_fp4 v[136:137], v244, 1.0 op_sel:[1,0,0]
	v_cvt_scalef32_pk_f32_fp4 v[138:139], v244, 1.0 op_sel:[0,1,0]
	v_cvt_scalef32_pk_f32_fp4 v[140:141], v244, 1.0 op_sel:[1,1,0]
	s_waitcnt lgkmcnt(0)
	v_pk_fma_f32 v[128:129], v[130:131], v[134:135], v[128:129] op_sel_hi:[0,1,1]
	v_pk_fma_f32 v[126:127], v[130:131], v[136:137], v[126:127] op_sel_hi:[0,1,1]
	v_pk_fma_f32 v[122:123], v[130:131], v[138:139], v[122:123] op_sel_hi:[0,1,1]
	v_pk_fma_f32 v[120:121], v[130:131], v[140:141], v[120:121] op_sel_hi:[0,1,1]
	v_cvt_scalef32_pk_f32_fp4 v[134:135], v245, 1.0
	v_cvt_scalef32_pk_f32_fp4 v[136:137], v245, 1.0 op_sel:[1,0,0]
	v_cvt_scalef32_pk_f32_fp4 v[138:139], v245, 1.0 op_sel:[0,1,0]
	v_cvt_scalef32_pk_f32_fp4 v[140:141], v245, 1.0 op_sel:[1,1,0]
	v_pk_fma_f32 v[118:119], v[130:131], v[134:135], v[118:119] op_sel_hi:[0,1,1]
	v_pk_fma_f32 v[116:117], v[130:131], v[136:137], v[116:117] op_sel_hi:[0,1,1]
	v_pk_fma_f32 v[114:115], v[130:131], v[138:139], v[114:115] op_sel_hi:[0,1,1]
	v_pk_fma_f32 v[112:113], v[130:131], v[140:141], v[112:113] op_sel_hi:[0,1,1]
	v_cvt_scalef32_pk_f32_fp4 v[134:135], v246, 1.0
	v_cvt_scalef32_pk_f32_fp4 v[136:137], v246, 1.0 op_sel:[1,0,0]
	v_cvt_scalef32_pk_f32_fp4 v[138:139], v246, 1.0 op_sel:[0,1,0]
	v_cvt_scalef32_pk_f32_fp4 v[140:141], v246, 1.0 op_sel:[1,1,0]
	v_pk_fma_f32 v[80:81], v[130:131], v[134:135], v[80:81] op_sel_hi:[0,1,1]
	v_pk_fma_f32 v[78:79], v[130:131], v[136:137], v[78:79] op_sel_hi:[0,1,1]
	v_pk_fma_f32 v[76:77], v[130:131], v[138:139], v[76:77] op_sel_hi:[0,1,1]
	v_pk_fma_f32 v[74:75], v[130:131], v[140:141], v[74:75] op_sel_hi:[0,1,1]
	v_cvt_scalef32_pk_f32_fp4 v[134:135], v247, 1.0
	v_cvt_scalef32_pk_f32_fp4 v[136:137], v247, 1.0 op_sel:[1,0,0]
	v_cvt_scalef32_pk_f32_fp4 v[138:139], v247, 1.0 op_sel:[0,1,0]
	v_cvt_scalef32_pk_f32_fp4 v[140:141], v247, 1.0 op_sel:[1,1,0]
	v_pk_fma_f32 v[72:73], v[130:131], v[134:135], v[72:73] op_sel_hi:[0,1,1]
	v_pk_fma_f32 v[70:71], v[130:131], v[136:137], v[70:71] op_sel_hi:[0,1,1]
	v_pk_fma_f32 v[68:69], v[130:131], v[138:139], v[68:69] op_sel_hi:[0,1,1]
	v_pk_fma_f32 v[66:67], v[130:131], v[140:141], v[66:67] op_sel_hi:[0,1,1]
	s_waitcnt vmcnt(14)
	v_cvt_scalef32_pk_f32_fp4 v[134:135], v228, 1.0
	v_cvt_scalef32_pk_f32_fp4 v[136:137], v228, 1.0 op_sel:[1,0,0]
	v_cvt_scalef32_pk_f32_fp4 v[138:139], v228, 1.0 op_sel:[0,1,0]
	v_cvt_scalef32_pk_f32_fp4 v[140:141], v228, 1.0 op_sel:[1,1,0]
	v_pk_fma_f32 v[34:35], v[130:131], v[134:135], v[34:35] op_sel_hi:[0,1,1]
	v_pk_fma_f32 v[36:37], v[130:131], v[136:137], v[36:37] op_sel_hi:[0,1,1]
	v_pk_fma_f32 v[38:39], v[130:131], v[138:139], v[38:39] op_sel_hi:[0,1,1]
	v_pk_fma_f32 v[40:41], v[130:131], v[140:141], v[40:41] op_sel_hi:[0,1,1]
	v_cvt_scalef32_pk_f32_fp4 v[134:135], v229, 1.0
	v_cvt_scalef32_pk_f32_fp4 v[136:137], v229, 1.0 op_sel:[1,0,0]
	v_cvt_scalef32_pk_f32_fp4 v[138:139], v229, 1.0 op_sel:[0,1,0]
	v_cvt_scalef32_pk_f32_fp4 v[140:141], v229, 1.0 op_sel:[1,1,0]
	v_pk_fma_f32 v[42:43], v[130:131], v[134:135], v[42:43] op_sel_hi:[0,1,1]
	v_pk_fma_f32 v[44:45], v[130:131], v[136:137], v[44:45] op_sel_hi:[0,1,1]
	v_pk_fma_f32 v[46:47], v[130:131], v[138:139], v[46:47] op_sel_hi:[0,1,1]
	v_pk_fma_f32 v[48:49], v[130:131], v[140:141], v[48:49] op_sel_hi:[0,1,1]
	v_cvt_scalef32_pk_f32_fp4 v[134:135], v230, 1.0
	v_cvt_scalef32_pk_f32_fp4 v[136:137], v230, 1.0 op_sel:[1,0,0]
	v_cvt_scalef32_pk_f32_fp4 v[138:139], v230, 1.0 op_sel:[0,1,0]
	v_cvt_scalef32_pk_f32_fp4 v[140:141], v230, 1.0 op_sel:[1,1,0]
	v_pk_fma_f32 v[50:51], v[130:131], v[134:135], v[50:51] op_sel_hi:[0,1,1]
	v_pk_fma_f32 v[52:53], v[130:131], v[136:137], v[52:53] op_sel_hi:[0,1,1]
	v_pk_fma_f32 v[54:55], v[130:131], v[138:139], v[54:55] op_sel_hi:[0,1,1]
	v_pk_fma_f32 v[56:57], v[130:131], v[140:141], v[56:57] op_sel_hi:[0,1,1]
	v_cvt_scalef32_pk_f32_fp4 v[134:135], v231, 1.0
	v_cvt_scalef32_pk_f32_fp4 v[136:137], v231, 1.0 op_sel:[1,0,0]
	v_cvt_scalef32_pk_f32_fp4 v[138:139], v231, 1.0 op_sel:[0,1,0]
	v_cvt_scalef32_pk_f32_fp4 v[140:141], v231, 1.0 op_sel:[1,1,0]
	v_pk_fma_f32 v[58:59], v[130:131], v[134:135], v[58:59] op_sel_hi:[0,1,1]
	v_pk_fma_f32 v[60:61], v[130:131], v[136:137], v[60:61] op_sel_hi:[0,1,1]
	v_pk_fma_f32 v[62:63], v[130:131], v[138:139], v[62:63] op_sel_hi:[0,1,1]
	v_pk_fma_f32 v[64:65], v[130:131], v[140:141], v[64:65] op_sel_hi:[0,1,1]
	s_add_i32 s2, s2, 8
	v_add_u32_e32 v131, 0x80, v131
	v_add_u32_e32 v132, 0x80, v132
	s_cmp_lt_u32 s2, 24
	s_cbranch_scc1 .Lpv_loop
	v_mad_u64_u32 v[248:249], vcc, v250, s0, v[86:87]
	global_load_dwordx4 v[244:247], v[248:249], off
	global_load_dwordx4 v[228:231], v[248:249], off offset:256
	ds_read_b32 v130, v132 offset:0
	s_waitcnt vmcnt(15)
	v_cvt_scalef32_pk_f32_fp4 v[134:135], v10, 1.0
	v_cvt_scalef32_pk_f32_fp4 v[136:137], v10, 1.0 op_sel:[1,0,0]
	v_cvt_scalef32_pk_f32_fp4 v[138:139], v10, 1.0 op_sel:[0,1,0]
	v_cvt_scalef32_pk_f32_fp4 v[140:141], v10, 1.0 op_sel:[1,1,0]
	s_waitcnt lgkmcnt(0)
	v_pk_fma_f32 v[128:129], v[130:131], v[134:135], v[128:129] op_sel_hi:[0,1,1]
	v_pk_fma_f32 v[126:127], v[130:131], v[136:137], v[126:127] op_sel_hi:[0,1,1]
	v_pk_fma_f32 v[122:123], v[130:131], v[138:139], v[122:123] op_sel_hi:[0,1,1]
	v_pk_fma_f32 v[120:121], v[130:131], v[140:141], v[120:121] op_sel_hi:[0,1,1]
	v_cvt_scalef32_pk_f32_fp4 v[134:135], v11, 1.0
	v_cvt_scalef32_pk_f32_fp4 v[136:137], v11, 1.0 op_sel:[1,0,0]
	v_cvt_scalef32_pk_f32_fp4 v[138:139], v11, 1.0 op_sel:[0,1,0]
	v_cvt_scalef32_pk_f32_fp4 v[140:141], v11, 1.0 op_sel:[1,1,0]
	v_pk_fma_f32 v[118:119], v[130:131], v[134:135], v[118:119] op_sel_hi:[0,1,1]
	v_pk_fma_f32 v[116:117], v[130:131], v[136:137], v[116:117] op_sel_hi:[0,1,1]
	v_pk_fma_f32 v[114:115], v[130:131], v[138:139], v[114:115] op_sel_hi:[0,1,1]
	v_pk_fma_f32 v[112:113], v[130:131], v[140:141], v[112:113] op_sel_hi:[0,1,1]
	v_cvt_scalef32_pk_f32_fp4 v[134:135], v12, 1.0
	v_cvt_scalef32_pk_f32_fp4 v[136:137], v12, 1.0 op_sel:[1,0,0]
	v_cvt_scalef32_pk_f32_fp4 v[138:139], v12, 1.0 op_sel:[0,1,0]
	v_cvt_scalef32_pk_f32_fp4 v[140:141], v12, 1.0 op_sel:[1,1,0]
	v_pk_fma_f32 v[80:81], v[130:131], v[134:135], v[80:81] op_sel_hi:[0,1,1]
	v_pk_fma_f32 v[78:79], v[130:131], v[136:137], v[78:79] op_sel_hi:[0,1,1]
	v_pk_fma_f32 v[76:77], v[130:131], v[138:139], v[76:77] op_sel_hi:[0,1,1]
	v_pk_fma_f32 v[74:75], v[130:131], v[140:141], v[74:75] op_sel_hi:[0,1,1]
	v_cvt_scalef32_pk_f32_fp4 v[134:135], v13, 1.0
	v_cvt_scalef32_pk_f32_fp4 v[136:137], v13, 1.0 op_sel:[1,0,0]
	v_cvt_scalef32_pk_f32_fp4 v[138:139], v13, 1.0 op_sel:[0,1,0]
	v_cvt_scalef32_pk_f32_fp4 v[140:141], v13, 1.0 op_sel:[1,1,0]
	v_pk_fma_f32 v[72:73], v[130:131], v[134:135], v[72:73] op_sel_hi:[0,1,1]
	v_pk_fma_f32 v[70:71], v[130:131], v[136:137], v[70:71] op_sel_hi:[0,1,1]
	v_pk_fma_f32 v[68:69], v[130:131], v[138:139], v[68:69] op_sel_hi:[0,1,1]
	v_pk_fma_f32 v[66:67], v[130:131], v[140:141], v[66:67] op_sel_hi:[0,1,1]
	s_waitcnt vmcnt(14)
	v_cvt_scalef32_pk_f32_fp4 v[134:135], v2, 1.0
	v_cvt_scalef32_pk_f32_fp4 v[136:137], v2, 1.0 op_sel:[1,0,0]
	v_cvt_scalef32_pk_f32_fp4 v[138:139], v2, 1.0 op_sel:[0,1,0]
	v_cvt_scalef32_pk_f32_fp4 v[140:141], v2, 1.0 op_sel:[1,1,0]
	v_pk_fma_f32 v[34:35], v[130:131], v[134:135], v[34:35] op_sel_hi:[0,1,1]
	v_pk_fma_f32 v[36:37], v[130:131], v[136:137], v[36:37] op_sel_hi:[0,1,1]
	v_pk_fma_f32 v[38:39], v[130:131], v[138:139], v[38:39] op_sel_hi:[0,1,1]
	v_pk_fma_f32 v[40:41], v[130:131], v[140:141], v[40:41] op_sel_hi:[0,1,1]
	v_cvt_scalef32_pk_f32_fp4 v[134:135], v3, 1.0
	v_cvt_scalef32_pk_f32_fp4 v[136:137], v3, 1.0 op_sel:[1,0,0]
	v_cvt_scalef32_pk_f32_fp4 v[138:139], v3, 1.0 op_sel:[0,1,0]
	v_cvt_scalef32_pk_f32_fp4 v[140:141], v3, 1.0 op_sel:[1,1,0]
	v_pk_fma_f32 v[42:43], v[130:131], v[134:135], v[42:43] op_sel_hi:[0,1,1]
	v_pk_fma_f32 v[44:45], v[130:131], v[136:137], v[44:45] op_sel_hi:[0,1,1]
	v_pk_fma_f32 v[46:47], v[130:131], v[138:139], v[46:47] op_sel_hi:[0,1,1]
	v_pk_fma_f32 v[48:49], v[130:131], v[140:141], v[48:49] op_sel_hi:[0,1,1]
	v_cvt_scalef32_pk_f32_fp4 v[134:135], v4, 1.0
	v_cvt_scalef32_pk_f32_fp4 v[136:137], v4, 1.0 op_sel:[1,0,0]
	v_cvt_scalef32_pk_f32_fp4 v[138:139], v4, 1.0 op_sel:[0,1,0]
	v_cvt_scalef32_pk_f32_fp4 v[140:141], v4, 1.0 op_sel:[1,1,0]
	v_pk_fma_f32 v[50:51], v[130:131], v[134:135], v[50:51] op_sel_hi:[0,1,1]
	v_pk_fma_f32 v[52:53], v[130:131], v[136:137], v[52:53] op_sel_hi:[0,1,1]
	v_pk_fma_f32 v[54:55], v[130:131], v[138:139], v[54:55] op_sel_hi:[0,1,1]
	v_pk_fma_f32 v[56:57], v[130:131], v[140:141], v[56:57] op_sel_hi:[0,1,1]
	v_cvt_scalef32_pk_f32_fp4 v[134:135], v5, 1.0
	v_cvt_scalef32_pk_f32_fp4 v[136:137], v5, 1.0 op_sel:[1,0,0]
	v_cvt_scalef32_pk_f32_fp4 v[138:139], v5, 1.0 op_sel:[0,1,0]
	v_cvt_scalef32_pk_f32_fp4 v[140:141], v5, 1.0 op_sel:[1,1,0]
	v_pk_fma_f32 v[58:59], v[130:131], v[134:135], v[58:59] op_sel_hi:[0,1,1]
	v_pk_fma_f32 v[60:61], v[130:131], v[136:137], v[60:61] op_sel_hi:[0,1,1]
	v_pk_fma_f32 v[62:63], v[130:131], v[138:139], v[62:63] op_sel_hi:[0,1,1]
	v_pk_fma_f32 v[64:65], v[130:131], v[140:141], v[64:65] op_sel_hi:[0,1,1]
	ds_read_b32 v130, v132 offset:16
	s_waitcnt vmcnt(13)
	v_cvt_scalef32_pk_f32_fp4 v[134:135], v14, 1.0
	v_cvt_scalef32_pk_f32_fp4 v[136:137], v14, 1.0 op_sel:[1,0,0]
	v_cvt_scalef32_pk_f32_fp4 v[138:139], v14, 1.0 op_sel:[0,1,0]
	v_cvt_scalef32_pk_f32_fp4 v[140:141], v14, 1.0 op_sel:[1,1,0]
	s_waitcnt lgkmcnt(0)
	v_pk_fma_f32 v[128:129], v[130:131], v[134:135], v[128:129] op_sel_hi:[0,1,1]
	v_pk_fma_f32 v[126:127], v[130:131], v[136:137], v[126:127] op_sel_hi:[0,1,1]
	v_pk_fma_f32 v[122:123], v[130:131], v[138:139], v[122:123] op_sel_hi:[0,1,1]
	v_pk_fma_f32 v[120:121], v[130:131], v[140:141], v[120:121] op_sel_hi:[0,1,1]
	v_cvt_scalef32_pk_f32_fp4 v[134:135], v15, 1.0
	v_cvt_scalef32_pk_f32_fp4 v[136:137], v15, 1.0 op_sel:[1,0,0]
	v_cvt_scalef32_pk_f32_fp4 v[138:139], v15, 1.0 op_sel:[0,1,0]
	v_cvt_scalef32_pk_f32_fp4 v[140:141], v15, 1.0 op_sel:[1,1,0]
	v_pk_fma_f32 v[118:119], v[130:131], v[134:135], v[118:119] op_sel_hi:[0,1,1]
	v_pk_fma_f32 v[116:117], v[130:131], v[136:137], v[116:117] op_sel_hi:[0,1,1]
	v_pk_fma_f32 v[114:115], v[130:131], v[138:139], v[114:115] op_sel_hi:[0,1,1]
	v_pk_fma_f32 v[112:113], v[130:131], v[140:141], v[112:113] op_sel_hi:[0,1,1]
	v_cvt_scalef32_pk_f32_fp4 v[134:135], v16, 1.0
	v_cvt_scalef32_pk_f32_fp4 v[136:137], v16, 1.0 op_sel:[1,0,0]
	v_cvt_scalef32_pk_f32_fp4 v[138:139], v16, 1.0 op_sel:[0,1,0]
	v_cvt_scalef32_pk_f32_fp4 v[140:141], v16, 1.0 op_sel:[1,1,0]
	v_pk_fma_f32 v[80:81], v[130:131], v[134:135], v[80:81] op_sel_hi:[0,1,1]
	v_pk_fma_f32 v[78:79], v[130:131], v[136:137], v[78:79] op_sel_hi:[0,1,1]
	v_pk_fma_f32 v[76:77], v[130:131], v[138:139], v[76:77] op_sel_hi:[0,1,1]
	v_pk_fma_f32 v[74:75], v[130:131], v[140:141], v[74:75] op_sel_hi:[0,1,1]
	v_cvt_scalef32_pk_f32_fp4 v[134:135], v17, 1.0
	v_cvt_scalef32_pk_f32_fp4 v[136:137], v17, 1.0 op_sel:[1,0,0]
	v_cvt_scalef32_pk_f32_fp4 v[138:139], v17, 1.0 op_sel:[0,1,0]
	v_cvt_scalef32_pk_f32_fp4 v[140:141], v17, 1.0 op_sel:[1,1,0]
	v_pk_fma_f32 v[72:73], v[130:131], v[134:135], v[72:73] op_sel_hi:[0,1,1]
	v_pk_fma_f32 v[70:71], v[130:131], v[136:137], v[70:71] op_sel_hi:[0,1,1]
	v_pk_fma_f32 v[68:69], v[130:131], v[138:139], v[68:69] op_sel_hi:[0,1,1]
	v_pk_fma_f32 v[66:67], v[130:131], v[140:141], v[66:67] op_sel_hi:[0,1,1]
	s_waitcnt vmcnt(12)
	v_cvt_scalef32_pk_f32_fp4 v[134:135], v6, 1.0
	v_cvt_scalef32_pk_f32_fp4 v[136:137], v6, 1.0 op_sel:[1,0,0]
	v_cvt_scalef32_pk_f32_fp4 v[138:139], v6, 1.0 op_sel:[0,1,0]
	v_cvt_scalef32_pk_f32_fp4 v[140:141], v6, 1.0 op_sel:[1,1,0]
	v_pk_fma_f32 v[34:35], v[130:131], v[134:135], v[34:35] op_sel_hi:[0,1,1]
	v_pk_fma_f32 v[36:37], v[130:131], v[136:137], v[36:37] op_sel_hi:[0,1,1]
	v_pk_fma_f32 v[38:39], v[130:131], v[138:139], v[38:39] op_sel_hi:[0,1,1]
	v_pk_fma_f32 v[40:41], v[130:131], v[140:141], v[40:41] op_sel_hi:[0,1,1]
	v_cvt_scalef32_pk_f32_fp4 v[134:135], v7, 1.0
	v_cvt_scalef32_pk_f32_fp4 v[136:137], v7, 1.0 op_sel:[1,0,0]
	v_cvt_scalef32_pk_f32_fp4 v[138:139], v7, 1.0 op_sel:[0,1,0]
	v_cvt_scalef32_pk_f32_fp4 v[140:141], v7, 1.0 op_sel:[1,1,0]
	v_pk_fma_f32 v[42:43], v[130:131], v[134:135], v[42:43] op_sel_hi:[0,1,1]
	v_pk_fma_f32 v[44:45], v[130:131], v[136:137], v[44:45] op_sel_hi:[0,1,1]
	v_pk_fma_f32 v[46:47], v[130:131], v[138:139], v[46:47] op_sel_hi:[0,1,1]
	v_pk_fma_f32 v[48:49], v[130:131], v[140:141], v[48:49] op_sel_hi:[0,1,1]
	v_cvt_scalef32_pk_f32_fp4 v[134:135], v8, 1.0
	v_cvt_scalef32_pk_f32_fp4 v[136:137], v8, 1.0 op_sel:[1,0,0]
	v_cvt_scalef32_pk_f32_fp4 v[138:139], v8, 1.0 op_sel:[0,1,0]
	v_cvt_scalef32_pk_f32_fp4 v[140:141], v8, 1.0 op_sel:[1,1,0]
	v_pk_fma_f32 v[50:51], v[130:131], v[134:135], v[50:51] op_sel_hi:[0,1,1]
	v_pk_fma_f32 v[52:53], v[130:131], v[136:137], v[52:53] op_sel_hi:[0,1,1]
	v_pk_fma_f32 v[54:55], v[130:131], v[138:139], v[54:55] op_sel_hi:[0,1,1]
	v_pk_fma_f32 v[56:57], v[130:131], v[140:141], v[56:57] op_sel_hi:[0,1,1]
	v_cvt_scalef32_pk_f32_fp4 v[134:135], v9, 1.0
	v_cvt_scalef32_pk_f32_fp4 v[136:137], v9, 1.0 op_sel:[1,0,0]
	v_cvt_scalef32_pk_f32_fp4 v[138:139], v9, 1.0 op_sel:[0,1,0]
	v_cvt_scalef32_pk_f32_fp4 v[140:141], v9, 1.0 op_sel:[1,1,0]
	v_pk_fma_f32 v[58:59], v[130:131], v[134:135], v[58:59] op_sel_hi:[0,1,1]
	v_pk_fma_f32 v[60:61], v[130:131], v[136:137], v[60:61] op_sel_hi:[0,1,1]
	v_pk_fma_f32 v[62:63], v[130:131], v[138:139], v[62:63] op_sel_hi:[0,1,1]
	v_pk_fma_f32 v[64:65], v[130:131], v[140:141], v[64:65] op_sel_hi:[0,1,1]
	ds_read_b32 v130, v132 offset:32
	s_waitcnt vmcnt(11)
	v_cvt_scalef32_pk_f32_fp4 v[134:135], v22, 1.0
	v_cvt_scalef32_pk_f32_fp4 v[136:137], v22, 1.0 op_sel:[1,0,0]
	v_cvt_scalef32_pk_f32_fp4 v[138:139], v22, 1.0 op_sel:[0,1,0]
	v_cvt_scalef32_pk_f32_fp4 v[140:141], v22, 1.0 op_sel:[1,1,0]
	s_waitcnt lgkmcnt(0)
	v_pk_fma_f32 v[128:129], v[130:131], v[134:135], v[128:129] op_sel_hi:[0,1,1]
	v_pk_fma_f32 v[126:127], v[130:131], v[136:137], v[126:127] op_sel_hi:[0,1,1]
	v_pk_fma_f32 v[122:123], v[130:131], v[138:139], v[122:123] op_sel_hi:[0,1,1]
	v_pk_fma_f32 v[120:121], v[130:131], v[140:141], v[120:121] op_sel_hi:[0,1,1]
	v_cvt_scalef32_pk_f32_fp4 v[134:135], v23, 1.0
	v_cvt_scalef32_pk_f32_fp4 v[136:137], v23, 1.0 op_sel:[1,0,0]
	v_cvt_scalef32_pk_f32_fp4 v[138:139], v23, 1.0 op_sel:[0,1,0]
	v_cvt_scalef32_pk_f32_fp4 v[140:141], v23, 1.0 op_sel:[1,1,0]
	v_pk_fma_f32 v[118:119], v[130:131], v[134:135], v[118:119] op_sel_hi:[0,1,1]
	v_pk_fma_f32 v[116:117], v[130:131], v[136:137], v[116:117] op_sel_hi:[0,1,1]
	v_pk_fma_f32 v[114:115], v[130:131], v[138:139], v[114:115] op_sel_hi:[0,1,1]
	v_pk_fma_f32 v[112:113], v[130:131], v[140:141], v[112:113] op_sel_hi:[0,1,1]
	v_cvt_scalef32_pk_f32_fp4 v[134:135], v24, 1.0
	v_cvt_scalef32_pk_f32_fp4 v[136:137], v24, 1.0 op_sel:[1,0,0]
	v_cvt_scalef32_pk_f32_fp4 v[138:139], v24, 1.0 op_sel:[0,1,0]
	v_cvt_scalef32_pk_f32_fp4 v[140:141], v24, 1.0 op_sel:[1,1,0]
	v_pk_fma_f32 v[80:81], v[130:131], v[134:135], v[80:81] op_sel_hi:[0,1,1]
	v_pk_fma_f32 v[78:79], v[130:131], v[136:137], v[78:79] op_sel_hi:[0,1,1]
	v_pk_fma_f32 v[76:77], v[130:131], v[138:139], v[76:77] op_sel_hi:[0,1,1]
	v_pk_fma_f32 v[74:75], v[130:131], v[140:141], v[74:75] op_sel_hi:[0,1,1]
	v_cvt_scalef32_pk_f32_fp4 v[134:135], v25, 1.0
	v_cvt_scalef32_pk_f32_fp4 v[136:137], v25, 1.0 op_sel:[1,0,0]
	v_cvt_scalef32_pk_f32_fp4 v[138:139], v25, 1.0 op_sel:[0,1,0]
	v_cvt_scalef32_pk_f32_fp4 v[140:141], v25, 1.0 op_sel:[1,1,0]
	v_pk_fma_f32 v[72:73], v[130:131], v[134:135], v[72:73] op_sel_hi:[0,1,1]
	v_pk_fma_f32 v[70:71], v[130:131], v[136:137], v[70:71] op_sel_hi:[0,1,1]
	v_pk_fma_f32 v[68:69], v[130:131], v[138:139], v[68:69] op_sel_hi:[0,1,1]
	v_pk_fma_f32 v[66:67], v[130:131], v[140:141], v[66:67] op_sel_hi:[0,1,1]
	s_waitcnt vmcnt(10)
	v_cvt_scalef32_pk_f32_fp4 v[134:135], v18, 1.0
	v_cvt_scalef32_pk_f32_fp4 v[136:137], v18, 1.0 op_sel:[1,0,0]
	v_cvt_scalef32_pk_f32_fp4 v[138:139], v18, 1.0 op_sel:[0,1,0]
	v_cvt_scalef32_pk_f32_fp4 v[140:141], v18, 1.0 op_sel:[1,1,0]
	v_pk_fma_f32 v[34:35], v[130:131], v[134:135], v[34:35] op_sel_hi:[0,1,1]
	v_pk_fma_f32 v[36:37], v[130:131], v[136:137], v[36:37] op_sel_hi:[0,1,1]
	v_pk_fma_f32 v[38:39], v[130:131], v[138:139], v[38:39] op_sel_hi:[0,1,1]
	v_pk_fma_f32 v[40:41], v[130:131], v[140:141], v[40:41] op_sel_hi:[0,1,1]
	v_cvt_scalef32_pk_f32_fp4 v[134:135], v19, 1.0
	v_cvt_scalef32_pk_f32_fp4 v[136:137], v19, 1.0 op_sel:[1,0,0]
	v_cvt_scalef32_pk_f32_fp4 v[138:139], v19, 1.0 op_sel:[0,1,0]
	v_cvt_scalef32_pk_f32_fp4 v[140:141], v19, 1.0 op_sel:[1,1,0]
	v_pk_fma_f32 v[42:43], v[130:131], v[134:135], v[42:43] op_sel_hi:[0,1,1]
	v_pk_fma_f32 v[44:45], v[130:131], v[136:137], v[44:45] op_sel_hi:[0,1,1]
	v_pk_fma_f32 v[46:47], v[130:131], v[138:139], v[46:47] op_sel_hi:[0,1,1]
	v_pk_fma_f32 v[48:49], v[130:131], v[140:141], v[48:49] op_sel_hi:[0,1,1]
	v_cvt_scalef32_pk_f32_fp4 v[134:135], v20, 1.0
	v_cvt_scalef32_pk_f32_fp4 v[136:137], v20, 1.0 op_sel:[1,0,0]
	v_cvt_scalef32_pk_f32_fp4 v[138:139], v20, 1.0 op_sel:[0,1,0]
	v_cvt_scalef32_pk_f32_fp4 v[140:141], v20, 1.0 op_sel:[1,1,0]
	v_pk_fma_f32 v[50:51], v[130:131], v[134:135], v[50:51] op_sel_hi:[0,1,1]
	v_pk_fma_f32 v[52:53], v[130:131], v[136:137], v[52:53] op_sel_hi:[0,1,1]
	v_pk_fma_f32 v[54:55], v[130:131], v[138:139], v[54:55] op_sel_hi:[0,1,1]
	v_pk_fma_f32 v[56:57], v[130:131], v[140:141], v[56:57] op_sel_hi:[0,1,1]
	v_cvt_scalef32_pk_f32_fp4 v[134:135], v21, 1.0
	v_cvt_scalef32_pk_f32_fp4 v[136:137], v21, 1.0 op_sel:[1,0,0]
	v_cvt_scalef32_pk_f32_fp4 v[138:139], v21, 1.0 op_sel:[0,1,0]
	v_cvt_scalef32_pk_f32_fp4 v[140:141], v21, 1.0 op_sel:[1,1,0]
	v_pk_fma_f32 v[58:59], v[130:131], v[134:135], v[58:59] op_sel_hi:[0,1,1]
	v_pk_fma_f32 v[60:61], v[130:131], v[136:137], v[60:61] op_sel_hi:[0,1,1]
	v_pk_fma_f32 v[62:63], v[130:131], v[138:139], v[62:63] op_sel_hi:[0,1,1]
	v_pk_fma_f32 v[64:65], v[130:131], v[140:141], v[64:65] op_sel_hi:[0,1,1]
	ds_read_b32 v130, v132 offset:48
	s_waitcnt vmcnt(9)
	v_cvt_scalef32_pk_f32_fp4 v[134:135], v30, 1.0
	v_cvt_scalef32_pk_f32_fp4 v[136:137], v30, 1.0 op_sel:[1,0,0]
	v_cvt_scalef32_pk_f32_fp4 v[138:139], v30, 1.0 op_sel:[0,1,0]
	v_cvt_scalef32_pk_f32_fp4 v[140:141], v30, 1.0 op_sel:[1,1,0]
	s_waitcnt lgkmcnt(0)
	v_pk_fma_f32 v[128:129], v[130:131], v[134:135], v[128:129] op_sel_hi:[0,1,1]
	v_pk_fma_f32 v[126:127], v[130:131], v[136:137], v[126:127] op_sel_hi:[0,1,1]
	v_pk_fma_f32 v[122:123], v[130:131], v[138:139], v[122:123] op_sel_hi:[0,1,1]
	v_pk_fma_f32 v[120:121], v[130:131], v[140:141], v[120:121] op_sel_hi:[0,1,1]
	v_cvt_scalef32_pk_f32_fp4 v[134:135], v31, 1.0
	v_cvt_scalef32_pk_f32_fp4 v[136:137], v31, 1.0 op_sel:[1,0,0]
	v_cvt_scalef32_pk_f32_fp4 v[138:139], v31, 1.0 op_sel:[0,1,0]
	v_cvt_scalef32_pk_f32_fp4 v[140:141], v31, 1.0 op_sel:[1,1,0]
	v_pk_fma_f32 v[118:119], v[130:131], v[134:135], v[118:119] op_sel_hi:[0,1,1]
	v_pk_fma_f32 v[116:117], v[130:131], v[136:137], v[116:117] op_sel_hi:[0,1,1]
	v_pk_fma_f32 v[114:115], v[130:131], v[138:139], v[114:115] op_sel_hi:[0,1,1]
	v_pk_fma_f32 v[112:113], v[130:131], v[140:141], v[112:113] op_sel_hi:[0,1,1]
	v_cvt_scalef32_pk_f32_fp4 v[134:135], v32, 1.0
	v_cvt_scalef32_pk_f32_fp4 v[136:137], v32, 1.0 op_sel:[1,0,0]
	v_cvt_scalef32_pk_f32_fp4 v[138:139], v32, 1.0 op_sel:[0,1,0]
	v_cvt_scalef32_pk_f32_fp4 v[140:141], v32, 1.0 op_sel:[1,1,0]
	v_pk_fma_f32 v[80:81], v[130:131], v[134:135], v[80:81] op_sel_hi:[0,1,1]
	v_pk_fma_f32 v[78:79], v[130:131], v[136:137], v[78:79] op_sel_hi:[0,1,1]
	v_pk_fma_f32 v[76:77], v[130:131], v[138:139], v[76:77] op_sel_hi:[0,1,1]
	v_pk_fma_f32 v[74:75], v[130:131], v[140:141], v[74:75] op_sel_hi:[0,1,1]
	v_cvt_scalef32_pk_f32_fp4 v[134:135], v33, 1.0
	v_cvt_scalef32_pk_f32_fp4 v[136:137], v33, 1.0 op_sel:[1,0,0]
	v_cvt_scalef32_pk_f32_fp4 v[138:139], v33, 1.0 op_sel:[0,1,0]
	v_cvt_scalef32_pk_f32_fp4 v[140:141], v33, 1.0 op_sel:[1,1,0]
	v_pk_fma_f32 v[72:73], v[130:131], v[134:135], v[72:73] op_sel_hi:[0,1,1]
	v_pk_fma_f32 v[70:71], v[130:131], v[136:137], v[70:71] op_sel_hi:[0,1,1]
	v_pk_fma_f32 v[68:69], v[130:131], v[138:139], v[68:69] op_sel_hi:[0,1,1]
	v_pk_fma_f32 v[66:67], v[130:131], v[140:141], v[66:67] op_sel_hi:[0,1,1]
	s_waitcnt vmcnt(8)
	v_cvt_scalef32_pk_f32_fp4 v[134:135], v26, 1.0
	v_cvt_scalef32_pk_f32_fp4 v[136:137], v26, 1.0 op_sel:[1,0,0]
	v_cvt_scalef32_pk_f32_fp4 v[138:139], v26, 1.0 op_sel:[0,1,0]
	v_cvt_scalef32_pk_f32_fp4 v[140:141], v26, 1.0 op_sel:[1,1,0]
	v_pk_fma_f32 v[34:35], v[130:131], v[134:135], v[34:35] op_sel_hi:[0,1,1]
	v_pk_fma_f32 v[36:37], v[130:131], v[136:137], v[36:37] op_sel_hi:[0,1,1]
	v_pk_fma_f32 v[38:39], v[130:131], v[138:139], v[38:39] op_sel_hi:[0,1,1]
	v_pk_fma_f32 v[40:41], v[130:131], v[140:141], v[40:41] op_sel_hi:[0,1,1]
	v_cvt_scalef32_pk_f32_fp4 v[134:135], v27, 1.0
	v_cvt_scalef32_pk_f32_fp4 v[136:137], v27, 1.0 op_sel:[1,0,0]
	v_cvt_scalef32_pk_f32_fp4 v[138:139], v27, 1.0 op_sel:[0,1,0]
	v_cvt_scalef32_pk_f32_fp4 v[140:141], v27, 1.0 op_sel:[1,1,0]
	v_pk_fma_f32 v[42:43], v[130:131], v[134:135], v[42:43] op_sel_hi:[0,1,1]
	v_pk_fma_f32 v[44:45], v[130:131], v[136:137], v[44:45] op_sel_hi:[0,1,1]
	v_pk_fma_f32 v[46:47], v[130:131], v[138:139], v[46:47] op_sel_hi:[0,1,1]
	v_pk_fma_f32 v[48:49], v[130:131], v[140:141], v[48:49] op_sel_hi:[0,1,1]
	v_cvt_scalef32_pk_f32_fp4 v[134:135], v28, 1.0
	v_cvt_scalef32_pk_f32_fp4 v[136:137], v28, 1.0 op_sel:[1,0,0]
	v_cvt_scalef32_pk_f32_fp4 v[138:139], v28, 1.0 op_sel:[0,1,0]
	v_cvt_scalef32_pk_f32_fp4 v[140:141], v28, 1.0 op_sel:[1,1,0]
	v_pk_fma_f32 v[50:51], v[130:131], v[134:135], v[50:51] op_sel_hi:[0,1,1]
	v_pk_fma_f32 v[52:53], v[130:131], v[136:137], v[52:53] op_sel_hi:[0,1,1]
	v_pk_fma_f32 v[54:55], v[130:131], v[138:139], v[54:55] op_sel_hi:[0,1,1]
	v_pk_fma_f32 v[56:57], v[130:131], v[140:141], v[56:57] op_sel_hi:[0,1,1]
	v_cvt_scalef32_pk_f32_fp4 v[134:135], v29, 1.0
	v_cvt_scalef32_pk_f32_fp4 v[136:137], v29, 1.0 op_sel:[1,0,0]
	v_cvt_scalef32_pk_f32_fp4 v[138:139], v29, 1.0 op_sel:[0,1,0]
	v_cvt_scalef32_pk_f32_fp4 v[140:141], v29, 1.0 op_sel:[1,1,0]
	v_pk_fma_f32 v[58:59], v[130:131], v[134:135], v[58:59] op_sel_hi:[0,1,1]
	v_pk_fma_f32 v[60:61], v[130:131], v[136:137], v[60:61] op_sel_hi:[0,1,1]
	v_pk_fma_f32 v[62:63], v[130:131], v[138:139], v[62:63] op_sel_hi:[0,1,1]
	v_pk_fma_f32 v[64:65], v[130:131], v[140:141], v[64:65] op_sel_hi:[0,1,1]
	ds_read_b32 v130, v132 offset:64
	s_waitcnt vmcnt(7)
	v_cvt_scalef32_pk_f32_fp4 v[134:135], v142, 1.0
	v_cvt_scalef32_pk_f32_fp4 v[136:137], v142, 1.0 op_sel:[1,0,0]
	v_cvt_scalef32_pk_f32_fp4 v[138:139], v142, 1.0 op_sel:[0,1,0]
	v_cvt_scalef32_pk_f32_fp4 v[140:141], v142, 1.0 op_sel:[1,1,0]
	s_waitcnt lgkmcnt(0)
	v_pk_fma_f32 v[128:129], v[130:131], v[134:135], v[128:129] op_sel_hi:[0,1,1]
	v_pk_fma_f32 v[126:127], v[130:131], v[136:137], v[126:127] op_sel_hi:[0,1,1]
	v_pk_fma_f32 v[122:123], v[130:131], v[138:139], v[122:123] op_sel_hi:[0,1,1]
	v_pk_fma_f32 v[120:121], v[130:131], v[140:141], v[120:121] op_sel_hi:[0,1,1]
	v_cvt_scalef32_pk_f32_fp4 v[134:135], v143, 1.0
	v_cvt_scalef32_pk_f32_fp4 v[136:137], v143, 1.0 op_sel:[1,0,0]
	v_cvt_scalef32_pk_f32_fp4 v[138:139], v143, 1.0 op_sel:[0,1,0]
	v_cvt_scalef32_pk_f32_fp4 v[140:141], v143, 1.0 op_sel:[1,1,0]
	v_pk_fma_f32 v[118:119], v[130:131], v[134:135], v[118:119] op_sel_hi:[0,1,1]
	v_pk_fma_f32 v[116:117], v[130:131], v[136:137], v[116:117] op_sel_hi:[0,1,1]
	v_pk_fma_f32 v[114:115], v[130:131], v[138:139], v[114:115] op_sel_hi:[0,1,1]
	v_pk_fma_f32 v[112:113], v[130:131], v[140:141], v[112:113] op_sel_hi:[0,1,1]
	v_cvt_scalef32_pk_f32_fp4 v[134:135], v144, 1.0
	v_cvt_scalef32_pk_f32_fp4 v[136:137], v144, 1.0 op_sel:[1,0,0]
	v_cvt_scalef32_pk_f32_fp4 v[138:139], v144, 1.0 op_sel:[0,1,0]
	v_cvt_scalef32_pk_f32_fp4 v[140:141], v144, 1.0 op_sel:[1,1,0]
	v_pk_fma_f32 v[80:81], v[130:131], v[134:135], v[80:81] op_sel_hi:[0,1,1]
	v_pk_fma_f32 v[78:79], v[130:131], v[136:137], v[78:79] op_sel_hi:[0,1,1]
	v_pk_fma_f32 v[76:77], v[130:131], v[138:139], v[76:77] op_sel_hi:[0,1,1]
	v_pk_fma_f32 v[74:75], v[130:131], v[140:141], v[74:75] op_sel_hi:[0,1,1]
	v_cvt_scalef32_pk_f32_fp4 v[134:135], v145, 1.0
	v_cvt_scalef32_pk_f32_fp4 v[136:137], v145, 1.0 op_sel:[1,0,0]
	v_cvt_scalef32_pk_f32_fp4 v[138:139], v145, 1.0 op_sel:[0,1,0]
	v_cvt_scalef32_pk_f32_fp4 v[140:141], v145, 1.0 op_sel:[1,1,0]
	v_pk_fma_f32 v[72:73], v[130:131], v[134:135], v[72:73] op_sel_hi:[0,1,1]
	v_pk_fma_f32 v[70:71], v[130:131], v[136:137], v[70:71] op_sel_hi:[0,1,1]
	v_pk_fma_f32 v[68:69], v[130:131], v[138:139], v[68:69] op_sel_hi:[0,1,1]
	v_pk_fma_f32 v[66:67], v[130:131], v[140:141], v[66:67] op_sel_hi:[0,1,1]
	s_waitcnt vmcnt(6)
	v_cvt_scalef32_pk_f32_fp4 v[134:135], v146, 1.0
	v_cvt_scalef32_pk_f32_fp4 v[136:137], v146, 1.0 op_sel:[1,0,0]
	v_cvt_scalef32_pk_f32_fp4 v[138:139], v146, 1.0 op_sel:[0,1,0]
	v_cvt_scalef32_pk_f32_fp4 v[140:141], v146, 1.0 op_sel:[1,1,0]
	v_pk_fma_f32 v[34:35], v[130:131], v[134:135], v[34:35] op_sel_hi:[0,1,1]
	v_pk_fma_f32 v[36:37], v[130:131], v[136:137], v[36:37] op_sel_hi:[0,1,1]
	v_pk_fma_f32 v[38:39], v[130:131], v[138:139], v[38:39] op_sel_hi:[0,1,1]
	v_pk_fma_f32 v[40:41], v[130:131], v[140:141], v[40:41] op_sel_hi:[0,1,1]
	v_cvt_scalef32_pk_f32_fp4 v[134:135], v147, 1.0
	v_cvt_scalef32_pk_f32_fp4 v[136:137], v147, 1.0 op_sel:[1,0,0]
	v_cvt_scalef32_pk_f32_fp4 v[138:139], v147, 1.0 op_sel:[0,1,0]
	v_cvt_scalef32_pk_f32_fp4 v[140:141], v147, 1.0 op_sel:[1,1,0]
	v_pk_fma_f32 v[42:43], v[130:131], v[134:135], v[42:43] op_sel_hi:[0,1,1]
	v_pk_fma_f32 v[44:45], v[130:131], v[136:137], v[44:45] op_sel_hi:[0,1,1]
	v_pk_fma_f32 v[46:47], v[130:131], v[138:139], v[46:47] op_sel_hi:[0,1,1]
	v_pk_fma_f32 v[48:49], v[130:131], v[140:141], v[48:49] op_sel_hi:[0,1,1]
	v_cvt_scalef32_pk_f32_fp4 v[134:135], v148, 1.0
	v_cvt_scalef32_pk_f32_fp4 v[136:137], v148, 1.0 op_sel:[1,0,0]
	v_cvt_scalef32_pk_f32_fp4 v[138:139], v148, 1.0 op_sel:[0,1,0]
	v_cvt_scalef32_pk_f32_fp4 v[140:141], v148, 1.0 op_sel:[1,1,0]
	v_pk_fma_f32 v[50:51], v[130:131], v[134:135], v[50:51] op_sel_hi:[0,1,1]
	v_pk_fma_f32 v[52:53], v[130:131], v[136:137], v[52:53] op_sel_hi:[0,1,1]
	v_pk_fma_f32 v[54:55], v[130:131], v[138:139], v[54:55] op_sel_hi:[0,1,1]
	v_pk_fma_f32 v[56:57], v[130:131], v[140:141], v[56:57] op_sel_hi:[0,1,1]
	v_cvt_scalef32_pk_f32_fp4 v[134:135], v149, 1.0
	v_cvt_scalef32_pk_f32_fp4 v[136:137], v149, 1.0 op_sel:[1,0,0]
	v_cvt_scalef32_pk_f32_fp4 v[138:139], v149, 1.0 op_sel:[0,1,0]
	v_cvt_scalef32_pk_f32_fp4 v[140:141], v149, 1.0 op_sel:[1,1,0]
	v_pk_fma_f32 v[58:59], v[130:131], v[134:135], v[58:59] op_sel_hi:[0,1,1]
	v_pk_fma_f32 v[60:61], v[130:131], v[136:137], v[60:61] op_sel_hi:[0,1,1]
	v_pk_fma_f32 v[62:63], v[130:131], v[138:139], v[62:63] op_sel_hi:[0,1,1]
	v_pk_fma_f32 v[64:65], v[130:131], v[140:141], v[64:65] op_sel_hi:[0,1,1]
	ds_read_b32 v130, v132 offset:80
	s_waitcnt vmcnt(5)
	v_cvt_scalef32_pk_f32_fp4 v[134:135], v150, 1.0
	v_cvt_scalef32_pk_f32_fp4 v[136:137], v150, 1.0 op_sel:[1,0,0]
	v_cvt_scalef32_pk_f32_fp4 v[138:139], v150, 1.0 op_sel:[0,1,0]
	v_cvt_scalef32_pk_f32_fp4 v[140:141], v150, 1.0 op_sel:[1,1,0]
	s_waitcnt lgkmcnt(0)
	v_pk_fma_f32 v[128:129], v[130:131], v[134:135], v[128:129] op_sel_hi:[0,1,1]
	v_pk_fma_f32 v[126:127], v[130:131], v[136:137], v[126:127] op_sel_hi:[0,1,1]
	v_pk_fma_f32 v[122:123], v[130:131], v[138:139], v[122:123] op_sel_hi:[0,1,1]
	v_pk_fma_f32 v[120:121], v[130:131], v[140:141], v[120:121] op_sel_hi:[0,1,1]
	v_cvt_scalef32_pk_f32_fp4 v[134:135], v151, 1.0
	v_cvt_scalef32_pk_f32_fp4 v[136:137], v151, 1.0 op_sel:[1,0,0]
	v_cvt_scalef32_pk_f32_fp4 v[138:139], v151, 1.0 op_sel:[0,1,0]
	v_cvt_scalef32_pk_f32_fp4 v[140:141], v151, 1.0 op_sel:[1,1,0]
	v_pk_fma_f32 v[118:119], v[130:131], v[134:135], v[118:119] op_sel_hi:[0,1,1]
	v_pk_fma_f32 v[116:117], v[130:131], v[136:137], v[116:117] op_sel_hi:[0,1,1]
	v_pk_fma_f32 v[114:115], v[130:131], v[138:139], v[114:115] op_sel_hi:[0,1,1]
	v_pk_fma_f32 v[112:113], v[130:131], v[140:141], v[112:113] op_sel_hi:[0,1,1]
	v_cvt_scalef32_pk_f32_fp4 v[134:135], v152, 1.0
	v_cvt_scalef32_pk_f32_fp4 v[136:137], v152, 1.0 op_sel:[1,0,0]
	v_cvt_scalef32_pk_f32_fp4 v[138:139], v152, 1.0 op_sel:[0,1,0]
	v_cvt_scalef32_pk_f32_fp4 v[140:141], v152, 1.0 op_sel:[1,1,0]
	v_pk_fma_f32 v[80:81], v[130:131], v[134:135], v[80:81] op_sel_hi:[0,1,1]
	v_pk_fma_f32 v[78:79], v[130:131], v[136:137], v[78:79] op_sel_hi:[0,1,1]
	v_pk_fma_f32 v[76:77], v[130:131], v[138:139], v[76:77] op_sel_hi:[0,1,1]
	v_pk_fma_f32 v[74:75], v[130:131], v[140:141], v[74:75] op_sel_hi:[0,1,1]
	v_cvt_scalef32_pk_f32_fp4 v[134:135], v153, 1.0
	v_cvt_scalef32_pk_f32_fp4 v[136:137], v153, 1.0 op_sel:[1,0,0]
	v_cvt_scalef32_pk_f32_fp4 v[138:139], v153, 1.0 op_sel:[0,1,0]
	v_cvt_scalef32_pk_f32_fp4 v[140:141], v153, 1.0 op_sel:[1,1,0]
	v_pk_fma_f32 v[72:73], v[130:131], v[134:135], v[72:73] op_sel_hi:[0,1,1]
	v_pk_fma_f32 v[70:71], v[130:131], v[136:137], v[70:71] op_sel_hi:[0,1,1]
	v_pk_fma_f32 v[68:69], v[130:131], v[138:139], v[68:69] op_sel_hi:[0,1,1]
	v_pk_fma_f32 v[66:67], v[130:131], v[140:141], v[66:67] op_sel_hi:[0,1,1]
	s_waitcnt vmcnt(4)
	v_cvt_scalef32_pk_f32_fp4 v[134:135], v232, 1.0
	v_cvt_scalef32_pk_f32_fp4 v[136:137], v232, 1.0 op_sel:[1,0,0]
	v_cvt_scalef32_pk_f32_fp4 v[138:139], v232, 1.0 op_sel:[0,1,0]
	v_cvt_scalef32_pk_f32_fp4 v[140:141], v232, 1.0 op_sel:[1,1,0]
	v_pk_fma_f32 v[34:35], v[130:131], v[134:135], v[34:35] op_sel_hi:[0,1,1]
	v_pk_fma_f32 v[36:37], v[130:131], v[136:137], v[36:37] op_sel_hi:[0,1,1]
	v_pk_fma_f32 v[38:39], v[130:131], v[138:139], v[38:39] op_sel_hi:[0,1,1]
	v_pk_fma_f32 v[40:41], v[130:131], v[140:141], v[40:41] op_sel_hi:[0,1,1]
	v_cvt_scalef32_pk_f32_fp4 v[134:135], v233, 1.0
	v_cvt_scalef32_pk_f32_fp4 v[136:137], v233, 1.0 op_sel:[1,0,0]
	v_cvt_scalef32_pk_f32_fp4 v[138:139], v233, 1.0 op_sel:[0,1,0]
	v_cvt_scalef32_pk_f32_fp4 v[140:141], v233, 1.0 op_sel:[1,1,0]
	v_pk_fma_f32 v[42:43], v[130:131], v[134:135], v[42:43] op_sel_hi:[0,1,1]
	v_pk_fma_f32 v[44:45], v[130:131], v[136:137], v[44:45] op_sel_hi:[0,1,1]
	v_pk_fma_f32 v[46:47], v[130:131], v[138:139], v[46:47] op_sel_hi:[0,1,1]
	v_pk_fma_f32 v[48:49], v[130:131], v[140:141], v[48:49] op_sel_hi:[0,1,1]
	v_cvt_scalef32_pk_f32_fp4 v[134:135], v234, 1.0
	v_cvt_scalef32_pk_f32_fp4 v[136:137], v234, 1.0 op_sel:[1,0,0]
	v_cvt_scalef32_pk_f32_fp4 v[138:139], v234, 1.0 op_sel:[0,1,0]
	v_cvt_scalef32_pk_f32_fp4 v[140:141], v234, 1.0 op_sel:[1,1,0]
	v_pk_fma_f32 v[50:51], v[130:131], v[134:135], v[50:51] op_sel_hi:[0,1,1]
	v_pk_fma_f32 v[52:53], v[130:131], v[136:137], v[52:53] op_sel_hi:[0,1,1]
	v_pk_fma_f32 v[54:55], v[130:131], v[138:139], v[54:55] op_sel_hi:[0,1,1]
	v_pk_fma_f32 v[56:57], v[130:131], v[140:141], v[56:57] op_sel_hi:[0,1,1]
	v_cvt_scalef32_pk_f32_fp4 v[134:135], v235, 1.0
	v_cvt_scalef32_pk_f32_fp4 v[136:137], v235, 1.0 op_sel:[1,0,0]
	v_cvt_scalef32_pk_f32_fp4 v[138:139], v235, 1.0 op_sel:[0,1,0]
	v_cvt_scalef32_pk_f32_fp4 v[140:141], v235, 1.0 op_sel:[1,1,0]
	v_pk_fma_f32 v[58:59], v[130:131], v[134:135], v[58:59] op_sel_hi:[0,1,1]
	v_pk_fma_f32 v[60:61], v[130:131], v[136:137], v[60:61] op_sel_hi:[0,1,1]
	v_pk_fma_f32 v[62:63], v[130:131], v[138:139], v[62:63] op_sel_hi:[0,1,1]
	v_pk_fma_f32 v[64:65], v[130:131], v[140:141], v[64:65] op_sel_hi:[0,1,1]
	ds_read_b32 v130, v132 offset:96
	s_waitcnt vmcnt(3)
	v_cvt_scalef32_pk_f32_fp4 v[134:135], v236, 1.0
	v_cvt_scalef32_pk_f32_fp4 v[136:137], v236, 1.0 op_sel:[1,0,0]
	v_cvt_scalef32_pk_f32_fp4 v[138:139], v236, 1.0 op_sel:[0,1,0]
	v_cvt_scalef32_pk_f32_fp4 v[140:141], v236, 1.0 op_sel:[1,1,0]
	s_waitcnt lgkmcnt(0)
	v_pk_fma_f32 v[128:129], v[130:131], v[134:135], v[128:129] op_sel_hi:[0,1,1]
	v_pk_fma_f32 v[126:127], v[130:131], v[136:137], v[126:127] op_sel_hi:[0,1,1]
	v_pk_fma_f32 v[122:123], v[130:131], v[138:139], v[122:123] op_sel_hi:[0,1,1]
	v_pk_fma_f32 v[120:121], v[130:131], v[140:141], v[120:121] op_sel_hi:[0,1,1]
	v_cvt_scalef32_pk_f32_fp4 v[134:135], v237, 1.0
	v_cvt_scalef32_pk_f32_fp4 v[136:137], v237, 1.0 op_sel:[1,0,0]
	v_cvt_scalef32_pk_f32_fp4 v[138:139], v237, 1.0 op_sel:[0,1,0]
	v_cvt_scalef32_pk_f32_fp4 v[140:141], v237, 1.0 op_sel:[1,1,0]
	v_pk_fma_f32 v[118:119], v[130:131], v[134:135], v[118:119] op_sel_hi:[0,1,1]
	v_pk_fma_f32 v[116:117], v[130:131], v[136:137], v[116:117] op_sel_hi:[0,1,1]
	v_pk_fma_f32 v[114:115], v[130:131], v[138:139], v[114:115] op_sel_hi:[0,1,1]
	v_pk_fma_f32 v[112:113], v[130:131], v[140:141], v[112:113] op_sel_hi:[0,1,1]
	v_cvt_scalef32_pk_f32_fp4 v[134:135], v238, 1.0
	v_cvt_scalef32_pk_f32_fp4 v[136:137], v238, 1.0 op_sel:[1,0,0]
	v_cvt_scalef32_pk_f32_fp4 v[138:139], v238, 1.0 op_sel:[0,1,0]
	v_cvt_scalef32_pk_f32_fp4 v[140:141], v238, 1.0 op_sel:[1,1,0]
	v_pk_fma_f32 v[80:81], v[130:131], v[134:135], v[80:81] op_sel_hi:[0,1,1]
	v_pk_fma_f32 v[78:79], v[130:131], v[136:137], v[78:79] op_sel_hi:[0,1,1]
	v_pk_fma_f32 v[76:77], v[130:131], v[138:139], v[76:77] op_sel_hi:[0,1,1]
	v_pk_fma_f32 v[74:75], v[130:131], v[140:141], v[74:75] op_sel_hi:[0,1,1]
	v_cvt_scalef32_pk_f32_fp4 v[134:135], v239, 1.0
	v_cvt_scalef32_pk_f32_fp4 v[136:137], v239, 1.0 op_sel:[1,0,0]
	v_cvt_scalef32_pk_f32_fp4 v[138:139], v239, 1.0 op_sel:[0,1,0]
	v_cvt_scalef32_pk_f32_fp4 v[140:141], v239, 1.0 op_sel:[1,1,0]
	v_pk_fma_f32 v[72:73], v[130:131], v[134:135], v[72:73] op_sel_hi:[0,1,1]
	v_pk_fma_f32 v[70:71], v[130:131], v[136:137], v[70:71] op_sel_hi:[0,1,1]
	v_pk_fma_f32 v[68:69], v[130:131], v[138:139], v[68:69] op_sel_hi:[0,1,1]
	v_pk_fma_f32 v[66:67], v[130:131], v[140:141], v[66:67] op_sel_hi:[0,1,1]
	s_waitcnt vmcnt(2)
	v_cvt_scalef32_pk_f32_fp4 v[134:135], v240, 1.0
	v_cvt_scalef32_pk_f32_fp4 v[136:137], v240, 1.0 op_sel:[1,0,0]
	v_cvt_scalef32_pk_f32_fp4 v[138:139], v240, 1.0 op_sel:[0,1,0]
	v_cvt_scalef32_pk_f32_fp4 v[140:141], v240, 1.0 op_sel:[1,1,0]
	v_pk_fma_f32 v[34:35], v[130:131], v[134:135], v[34:35] op_sel_hi:[0,1,1]
	v_pk_fma_f32 v[36:37], v[130:131], v[136:137], v[36:37] op_sel_hi:[0,1,1]
	v_pk_fma_f32 v[38:39], v[130:131], v[138:139], v[38:39] op_sel_hi:[0,1,1]
	v_pk_fma_f32 v[40:41], v[130:131], v[140:141], v[40:41] op_sel_hi:[0,1,1]
	v_cvt_scalef32_pk_f32_fp4 v[134:135], v241, 1.0
	v_cvt_scalef32_pk_f32_fp4 v[136:137], v241, 1.0 op_sel:[1,0,0]
	v_cvt_scalef32_pk_f32_fp4 v[138:139], v241, 1.0 op_sel:[0,1,0]
	v_cvt_scalef32_pk_f32_fp4 v[140:141], v241, 1.0 op_sel:[1,1,0]
	v_pk_fma_f32 v[42:43], v[130:131], v[134:135], v[42:43] op_sel_hi:[0,1,1]
	v_pk_fma_f32 v[44:45], v[130:131], v[136:137], v[44:45] op_sel_hi:[0,1,1]
	v_pk_fma_f32 v[46:47], v[130:131], v[138:139], v[46:47] op_sel_hi:[0,1,1]
	v_pk_fma_f32 v[48:49], v[130:131], v[140:141], v[48:49] op_sel_hi:[0,1,1]
	v_cvt_scalef32_pk_f32_fp4 v[134:135], v242, 1.0
	v_cvt_scalef32_pk_f32_fp4 v[136:137], v242, 1.0 op_sel:[1,0,0]
	v_cvt_scalef32_pk_f32_fp4 v[138:139], v242, 1.0 op_sel:[0,1,0]
	v_cvt_scalef32_pk_f32_fp4 v[140:141], v242, 1.0 op_sel:[1,1,0]
	v_pk_fma_f32 v[50:51], v[130:131], v[134:135], v[50:51] op_sel_hi:[0,1,1]
	v_pk_fma_f32 v[52:53], v[130:131], v[136:137], v[52:53] op_sel_hi:[0,1,1]
	v_pk_fma_f32 v[54:55], v[130:131], v[138:139], v[54:55] op_sel_hi:[0,1,1]
	v_pk_fma_f32 v[56:57], v[130:131], v[140:141], v[56:57] op_sel_hi:[0,1,1]
	v_cvt_scalef32_pk_f32_fp4 v[134:135], v243, 1.0
	v_cvt_scalef32_pk_f32_fp4 v[136:137], v243, 1.0 op_sel:[1,0,0]
	v_cvt_scalef32_pk_f32_fp4 v[138:139], v243, 1.0 op_sel:[0,1,0]
	v_cvt_scalef32_pk_f32_fp4 v[140:141], v243, 1.0 op_sel:[1,1,0]
	v_pk_fma_f32 v[58:59], v[130:131], v[134:135], v[58:59] op_sel_hi:[0,1,1]
	v_pk_fma_f32 v[60:61], v[130:131], v[136:137], v[60:61] op_sel_hi:[0,1,1]
	v_pk_fma_f32 v[62:63], v[130:131], v[138:139], v[62:63] op_sel_hi:[0,1,1]
	v_pk_fma_f32 v[64:65], v[130:131], v[140:141], v[64:65] op_sel_hi:[0,1,1]
	ds_read_b32 v130, v132 offset:112
	s_waitcnt vmcnt(1)
	v_cvt_scalef32_pk_f32_fp4 v[134:135], v244, 1.0
	v_cvt_scalef32_pk_f32_fp4 v[136:137], v244, 1.0 op_sel:[1,0,0]
	v_cvt_scalef32_pk_f32_fp4 v[138:139], v244, 1.0 op_sel:[0,1,0]
	v_cvt_scalef32_pk_f32_fp4 v[140:141], v244, 1.0 op_sel:[1,1,0]
	s_waitcnt lgkmcnt(0)
	v_pk_fma_f32 v[128:129], v[130:131], v[134:135], v[128:129] op_sel_hi:[0,1,1]
	v_pk_fma_f32 v[126:127], v[130:131], v[136:137], v[126:127] op_sel_hi:[0,1,1]
	v_pk_fma_f32 v[122:123], v[130:131], v[138:139], v[122:123] op_sel_hi:[0,1,1]
	v_pk_fma_f32 v[120:121], v[130:131], v[140:141], v[120:121] op_sel_hi:[0,1,1]
	v_cvt_scalef32_pk_f32_fp4 v[134:135], v245, 1.0
	v_cvt_scalef32_pk_f32_fp4 v[136:137], v245, 1.0 op_sel:[1,0,0]
	v_cvt_scalef32_pk_f32_fp4 v[138:139], v245, 1.0 op_sel:[0,1,0]
	v_cvt_scalef32_pk_f32_fp4 v[140:141], v245, 1.0 op_sel:[1,1,0]
	v_pk_fma_f32 v[118:119], v[130:131], v[134:135], v[118:119] op_sel_hi:[0,1,1]
	v_pk_fma_f32 v[116:117], v[130:131], v[136:137], v[116:117] op_sel_hi:[0,1,1]
	v_pk_fma_f32 v[114:115], v[130:131], v[138:139], v[114:115] op_sel_hi:[0,1,1]
	v_pk_fma_f32 v[112:113], v[130:131], v[140:141], v[112:113] op_sel_hi:[0,1,1]
	v_cvt_scalef32_pk_f32_fp4 v[134:135], v246, 1.0
	v_cvt_scalef32_pk_f32_fp4 v[136:137], v246, 1.0 op_sel:[1,0,0]
	v_cvt_scalef32_pk_f32_fp4 v[138:139], v246, 1.0 op_sel:[0,1,0]
	v_cvt_scalef32_pk_f32_fp4 v[140:141], v246, 1.0 op_sel:[1,1,0]
	v_pk_fma_f32 v[80:81], v[130:131], v[134:135], v[80:81] op_sel_hi:[0,1,1]
	v_pk_fma_f32 v[78:79], v[130:131], v[136:137], v[78:79] op_sel_hi:[0,1,1]
	v_pk_fma_f32 v[76:77], v[130:131], v[138:139], v[76:77] op_sel_hi:[0,1,1]
	v_pk_fma_f32 v[74:75], v[130:131], v[140:141], v[74:75] op_sel_hi:[0,1,1]
	v_cvt_scalef32_pk_f32_fp4 v[134:135], v247, 1.0
	v_cvt_scalef32_pk_f32_fp4 v[136:137], v247, 1.0 op_sel:[1,0,0]
	v_cvt_scalef32_pk_f32_fp4 v[138:139], v247, 1.0 op_sel:[0,1,0]
	v_cvt_scalef32_pk_f32_fp4 v[140:141], v247, 1.0 op_sel:[1,1,0]
	v_pk_fma_f32 v[72:73], v[130:131], v[134:135], v[72:73] op_sel_hi:[0,1,1]
	v_pk_fma_f32 v[70:71], v[130:131], v[136:137], v[70:71] op_sel_hi:[0,1,1]
	v_pk_fma_f32 v[68:69], v[130:131], v[138:139], v[68:69] op_sel_hi:[0,1,1]
	v_pk_fma_f32 v[66:67], v[130:131], v[140:141], v[66:67] op_sel_hi:[0,1,1]
	s_waitcnt vmcnt(0)
	v_cvt_scalef32_pk_f32_fp4 v[134:135], v228, 1.0
	v_cvt_scalef32_pk_f32_fp4 v[136:137], v228, 1.0 op_sel:[1,0,0]
	v_cvt_scalef32_pk_f32_fp4 v[138:139], v228, 1.0 op_sel:[0,1,0]
	v_cvt_scalef32_pk_f32_fp4 v[140:141], v228, 1.0 op_sel:[1,1,0]
	v_pk_fma_f32 v[34:35], v[130:131], v[134:135], v[34:35] op_sel_hi:[0,1,1]
	v_pk_fma_f32 v[36:37], v[130:131], v[136:137], v[36:37] op_sel_hi:[0,1,1]
	v_pk_fma_f32 v[38:39], v[130:131], v[138:139], v[38:39] op_sel_hi:[0,1,1]
	v_pk_fma_f32 v[40:41], v[130:131], v[140:141], v[40:41] op_sel_hi:[0,1,1]
	v_cvt_scalef32_pk_f32_fp4 v[134:135], v229, 1.0
	v_cvt_scalef32_pk_f32_fp4 v[136:137], v229, 1.0 op_sel:[1,0,0]
	v_cvt_scalef32_pk_f32_fp4 v[138:139], v229, 1.0 op_sel:[0,1,0]
	v_cvt_scalef32_pk_f32_fp4 v[140:141], v229, 1.0 op_sel:[1,1,0]
	v_pk_fma_f32 v[42:43], v[130:131], v[134:135], v[42:43] op_sel_hi:[0,1,1]
	v_pk_fma_f32 v[44:45], v[130:131], v[136:137], v[44:45] op_sel_hi:[0,1,1]
	v_pk_fma_f32 v[46:47], v[130:131], v[138:139], v[46:47] op_sel_hi:[0,1,1]
	v_pk_fma_f32 v[48:49], v[130:131], v[140:141], v[48:49] op_sel_hi:[0,1,1]
	v_cvt_scalef32_pk_f32_fp4 v[134:135], v230, 1.0
	v_cvt_scalef32_pk_f32_fp4 v[136:137], v230, 1.0 op_sel:[1,0,0]
	v_cvt_scalef32_pk_f32_fp4 v[138:139], v230, 1.0 op_sel:[0,1,0]
	v_cvt_scalef32_pk_f32_fp4 v[140:141], v230, 1.0 op_sel:[1,1,0]
	v_pk_fma_f32 v[50:51], v[130:131], v[134:135], v[50:51] op_sel_hi:[0,1,1]
	v_pk_fma_f32 v[52:53], v[130:131], v[136:137], v[52:53] op_sel_hi:[0,1,1]
	v_pk_fma_f32 v[54:55], v[130:131], v[138:139], v[54:55] op_sel_hi:[0,1,1]
	v_pk_fma_f32 v[56:57], v[130:131], v[140:141], v[56:57] op_sel_hi:[0,1,1]
	v_cvt_scalef32_pk_f32_fp4 v[134:135], v231, 1.0
	v_cvt_scalef32_pk_f32_fp4 v[136:137], v231, 1.0 op_sel:[1,0,0]
	v_cvt_scalef32_pk_f32_fp4 v[138:139], v231, 1.0 op_sel:[0,1,0]
	v_cvt_scalef32_pk_f32_fp4 v[140:141], v231, 1.0 op_sel:[1,1,0]
	v_pk_fma_f32 v[58:59], v[130:131], v[134:135], v[58:59] op_sel_hi:[0,1,1]
	v_pk_fma_f32 v[60:61], v[130:131], v[136:137], v[60:61] op_sel_hi:[0,1,1]
	v_pk_fma_f32 v[62:63], v[130:131], v[138:139], v[62:63] op_sel_hi:[0,1,1]
	v_pk_fma_f32 v[64:65], v[130:131], v[140:141], v[64:65] op_sel_hi:[0,1,1]
	v_lshlrev_b64 v[94:95], 10, v[94:95]
	v_or_b32_e32 v94, v94, v82
	s_waitcnt vmcnt(5)
	v_mov_b32_e32 v10, v128
	v_lshlrev_b64 v[130:131], 2, v[94:95]
	v_lshl_add_u64 v[132:133], s[18:19], 0, v[130:131]
	global_load_dwordx4 v[2:5], v[132:133], off
	global_load_dwordx4 v[6:9], v[132:133], off offset:16
	global_load_dwordx4 v[22:25], v[132:133], off offset:48
	global_load_dwordx4 v[18:21], v[132:133], off offset:32
	v_mov_b32_e32 v11, v129
	v_mov_b32_e32 v12, v126
	v_mov_b32_e32 v13, v127
	s_waitcnt vmcnt(7)
	v_mov_b32_e32 v14, v122
	v_mov_b32_e32 v15, v123
	v_mov_b32_e32 v16, v120
	v_mov_b32_e32 v17, v121
	v_mov_b32_e32 v26, v118
	v_permlane16_swap_b32_e32 v128, v10
	v_permlane16_swap_b32_e32 v129, v11
	v_permlane16_swap_b32_e32 v126, v12
	v_permlane16_swap_b32_e32 v127, v13
	v_permlane16_swap_b32_e32 v122, v14
	v_permlane16_swap_b32_e32 v123, v15
	v_permlane16_swap_b32_e32 v120, v16
	v_permlane16_swap_b32_e32 v121, v17
	v_permlane16_swap_b32_e32 v118, v26
	v_add_f32_e32 v10, v128, v10
	v_add_f32_e32 v11, v129, v11
	v_add_f32_e32 v12, v126, v12
	v_add_f32_e32 v13, v127, v13
	v_add_f32_e32 v14, v122, v14
	v_add_f32_e32 v15, v123, v15
	v_add_f32_e32 v16, v120, v16
	v_add_f32_e32 v17, v121, v17
	v_add_f32_e32 v118, v118, v26
	v_mov_b32_e32 v26, v10
	v_mov_b32_e32 v27, v11
	v_mov_b32_e32 v28, v12
	v_mov_b32_e32 v29, v13
	v_mov_b32_e32 v30, v14
	v_mov_b32_e32 v31, v15
	v_mov_b32_e32 v32, v16
	v_mov_b32_e32 v33, v17
	v_permlane32_swap_b32_e32 v10, v26
	v_permlane32_swap_b32_e32 v11, v27
	v_permlane32_swap_b32_e32 v12, v28
	v_permlane32_swap_b32_e32 v13, v29
	v_permlane32_swap_b32_e32 v14, v30
	v_permlane32_swap_b32_e32 v15, v31
	v_permlane32_swap_b32_e32 v16, v32
	v_permlane32_swap_b32_e32 v17, v33
	v_pk_add_f32 v[10:11], v[10:11], v[26:27]
	v_pk_add_f32 v[12:13], v[12:13], v[28:29]
	v_pk_add_f32 v[120:121], v[14:15], v[30:31]
	v_pk_add_f32 v[122:123], v[16:17], v[32:33]
	global_load_dwordx4 v[26:29], v[132:133], off offset:80
	global_load_dwordx4 v[30:33], v[132:133], off offset:64
	v_mov_b32_e32 v135, v119
	s_nop 1
	v_permlane16_swap_b32_e32 v119, v135
	v_add_f32_e32 v119, v119, v135
	v_mov_b32_e32 v134, v118
	v_mov_b32_e32 v135, v119
	s_nop 0
	v_permlane32_swap_b32_e32 v118, v134
	v_permlane32_swap_b32_e32 v119, v135
	v_mov_b32_e32 v227, v52
	s_nop 1
	v_permlane16_swap_b32_e32 v52, v227
	s_waitcnt vmcnt(5)
	v_pk_add_f32 v[14:15], v[2:3], v[10:11]
	v_pk_add_f32 v[2:3], v[118:119], v[134:135]
	global_load_dwordx4 v[134:137], v[132:133], off offset:112
	global_load_dwordx4 v[138:141], v[132:133], off offset:96
	global_load_dwordx4 v[142:145], v[132:133], off offset:2064
	global_load_dwordx4 v[146:149], v[132:133], off offset:2048
	s_waitcnt vmcnt(6)
	v_pk_add_f32 v[18:19], v[18:19], v[2:3]
	v_mov_b32_e32 v2, v116
	v_mov_b32_e32 v3, v117
	s_nop 0
	v_permlane16_swap_b32_e32 v116, v2
	v_permlane16_swap_b32_e32 v117, v3
	v_add_f32_e32 v2, v116, v2
	v_add_f32_e32 v3, v117, v3
	global_load_dwordx4 v[150:153], v[132:133], off offset:2096
	global_load_dwordx4 v[196:199], v[132:133], off offset:2080
	v_pk_add_f32 v[16:17], v[4:5], v[12:13]
	v_mov_b32_e32 v4, v2
	v_mov_b32_e32 v5, v3
	s_nop 0
	v_permlane32_swap_b32_e32 v2, v4
	v_permlane32_swap_b32_e32 v3, v5
	v_pk_add_f32 v[2:3], v[2:3], v[4:5]
	v_pk_add_f32 v[10:11], v[6:7], v[120:121]
	v_pk_add_f32 v[20:21], v[20:21], v[2:3]
	v_mov_b32_e32 v2, v114
	v_mov_b32_e32 v3, v115
	s_nop 0
	v_permlane16_swap_b32_e32 v114, v2
	v_permlane16_swap_b32_e32 v115, v3
	v_add_f32_e32 v2, v114, v2
	v_add_f32_e32 v3, v115, v3
	v_mov_b32_e32 v4, v2
	v_mov_b32_e32 v5, v3
	s_nop 0
	v_permlane32_swap_b32_e32 v2, v4
	v_permlane32_swap_b32_e32 v3, v5
	v_pk_add_f32 v[2:3], v[2:3], v[4:5]
	v_pk_add_f32 v[12:13], v[8:9], v[122:123]
	v_pk_add_f32 v[22:23], v[22:23], v[2:3]
	v_mov_b32_e32 v2, v112
	v_mov_b32_e32 v3, v113
	s_nop 0
	v_permlane16_swap_b32_e32 v112, v2
	v_permlane16_swap_b32_e32 v113, v3
	v_add_f32_e32 v2, v112, v2
	v_add_f32_e32 v3, v113, v3
	v_mov_b32_e32 v4, v2
	v_mov_b32_e32 v5, v3
	s_nop 0
	v_permlane32_swap_b32_e32 v2, v4
	v_permlane32_swap_b32_e32 v3, v5
	v_pk_add_f32 v[2:3], v[2:3], v[4:5]
	v_pk_mul_f32 v[128:129], v[14:15], v[14:15]
	v_pk_add_f32 v[24:25], v[24:25], v[2:3]
	v_mov_b32_e32 v2, v80
	v_mov_b32_e32 v3, v81
	s_nop 0
	v_permlane16_swap_b32_e32 v80, v2
	v_permlane16_swap_b32_e32 v81, v3
	v_add_f32_e32 v2, v80, v2
	v_add_f32_e32 v3, v81, v3
	v_mov_b32_e32 v4, v2
	v_mov_b32_e32 v5, v3
	s_nop 0
	v_permlane32_swap_b32_e32 v2, v4
	v_permlane32_swap_b32_e32 v3, v5
	v_pk_add_f32 v[2:3], v[2:3], v[4:5]
	v_mov_b32_e32 v4, v78
	v_mov_b32_e32 v5, v79
	s_nop 0
	v_permlane16_swap_b32_e32 v78, v4
	v_permlane16_swap_b32_e32 v79, v5
	v_add_f32_e32 v4, v78, v4
	v_add_f32_e32 v5, v79, v5
	v_mov_b32_e32 v6, v4
	v_mov_b32_e32 v7, v5
	s_nop 0
	v_permlane32_swap_b32_e32 v4, v6
	v_permlane32_swap_b32_e32 v5, v7
	v_pk_add_f32 v[4:5], v[4:5], v[6:7]
	v_mov_b32_e32 v6, v76
	v_mov_b32_e32 v7, v77
	s_nop 0
	v_permlane16_swap_b32_e32 v76, v6
	v_permlane16_swap_b32_e32 v77, v7
	v_add_f32_e32 v6, v76, v6
	v_add_f32_e32 v7, v77, v7
	v_mov_b32_e32 v8, v6
	v_mov_b32_e32 v9, v7
	s_nop 0
	v_permlane32_swap_b32_e32 v6, v8
	v_permlane32_swap_b32_e32 v7, v9
	v_pk_add_f32 v[6:7], v[6:7], v[8:9]
	v_mov_b32_e32 v8, v74
	v_mov_b32_e32 v9, v75
	s_nop 0
	v_permlane16_swap_b32_e32 v74, v8
	v_permlane16_swap_b32_e32 v75, v9
	v_add_f32_e32 v8, v74, v8
	v_add_f32_e32 v9, v75, v9
	s_waitcnt vmcnt(7)
	v_pk_add_f32 v[6:7], v[26:27], v[6:7]
	v_mov_b32_e32 v26, v8
	v_mov_b32_e32 v27, v9
	s_nop 0
	v_permlane32_swap_b32_e32 v8, v26
	v_permlane32_swap_b32_e32 v9, v27
	v_pk_add_f32 v[8:9], v[8:9], v[26:27]
	v_mov_b32_e32 v26, v72
	v_mov_b32_e32 v27, v73
	s_nop 0
	v_permlane16_swap_b32_e32 v72, v26
	v_permlane16_swap_b32_e32 v73, v27
	v_add_f32_e32 v26, v72, v26
	v_add_f32_e32 v27, v73, v27
	v_pk_add_f32 v[8:9], v[28:29], v[8:9]
	v_mov_b32_e32 v28, v26
	v_mov_b32_e32 v29, v27
	s_nop 0
	v_permlane32_swap_b32_e32 v26, v28
	v_permlane32_swap_b32_e32 v27, v29
	v_pk_add_f32 v[26:27], v[26:27], v[28:29]
	v_mov_b32_e32 v28, v70
	v_mov_b32_e32 v29, v71
	s_nop 0
	v_permlane16_swap_b32_e32 v70, v28
	v_permlane16_swap_b32_e32 v71, v29
	v_add_f32_e32 v28, v70, v28
	v_add_f32_e32 v29, v71, v29
	s_waitcnt vmcnt(6)
	v_pk_add_f32 v[2:3], v[30:31], v[2:3]
	v_mov_b32_e32 v30, v28
	v_mov_b32_e32 v31, v29
	s_nop 0
	v_permlane32_swap_b32_e32 v28, v30
	v_permlane32_swap_b32_e32 v29, v31
	v_pk_add_f32 v[28:29], v[28:29], v[30:31]
	v_mov_b32_e32 v30, v68
	v_mov_b32_e32 v31, v69
	s_nop 0
	v_permlane16_swap_b32_e32 v68, v30
	v_permlane16_swap_b32_e32 v69, v31
	v_add_f32_e32 v30, v68, v30
	v_add_f32_e32 v31, v69, v31
	v_pk_add_f32 v[4:5], v[32:33], v[4:5]
	v_mov_b32_e32 v32, v30
	v_mov_b32_e32 v33, v31
	s_nop 0
	v_permlane32_swap_b32_e32 v30, v32
	v_permlane32_swap_b32_e32 v31, v33
	v_pk_add_f32 v[30:31], v[30:31], v[32:33]
	v_mov_b32_e32 v32, v66
	v_mov_b32_e32 v33, v67
	s_nop 0
	v_permlane16_swap_b32_e32 v66, v32
	v_permlane16_swap_b32_e32 v67, v33
	v_add_f32_e32 v32, v66, v32
	v_add_f32_e32 v33, v67, v33
	v_mov_b32_e32 v66, v32
	v_mov_b32_e32 v67, v33
	s_nop 0
	v_permlane32_swap_b32_e32 v32, v66
	v_permlane32_swap_b32_e32 v33, v67
	v_pk_add_f32 v[32:33], v[32:33], v[66:67]
	s_waitcnt vmcnt(4)
	v_pk_add_f32 v[28:29], v[140:141], v[28:29]
	v_pk_add_f32 v[32:33], v[136:137], v[32:33]
	v_mov_b32_e32 v136, v36
	v_mov_b32_e32 v137, v37
	s_nop 0
	v_permlane16_swap_b32_e32 v36, v136
	v_permlane16_swap_b32_e32 v37, v137
	v_add_f32_e32 v36, v36, v136
	v_add_f32_e32 v37, v37, v137
	v_mov_b32_e32 v136, v36
	v_mov_b32_e32 v137, v37
	s_nop 0
	v_permlane32_swap_b32_e32 v36, v136
	v_permlane32_swap_b32_e32 v37, v137
	v_pk_add_f32 v[36:37], v[36:37], v[136:137]
	v_pk_add_f32 v[30:31], v[134:135], v[30:31]
	s_waitcnt vmcnt(2)
	v_pk_add_f32 v[36:37], v[148:149], v[36:37]
	v_mov_b32_e32 v148, v44
	v_mov_b32_e32 v149, v45
	v_mov_b32_e32 v134, v34
	v_mov_b32_e32 v135, v35
	v_mov_b32_e32 v140, v40
	v_mov_b32_e32 v141, v41
	v_permlane16_swap_b32_e32 v44, v148
	v_permlane16_swap_b32_e32 v45, v149
	v_permlane16_swap_b32_e32 v34, v134
	v_permlane16_swap_b32_e32 v35, v135
	v_permlane16_swap_b32_e32 v40, v140
	v_permlane16_swap_b32_e32 v41, v141
	v_add_f32_e32 v44, v44, v148
	v_add_f32_e32 v45, v45, v149
	v_add_f32_e32 v34, v34, v134
	v_add_f32_e32 v35, v35, v135
	v_add_f32_e32 v40, v40, v140
	v_add_f32_e32 v41, v41, v141
	v_mov_b32_e32 v148, v44
	v_mov_b32_e32 v149, v45
	v_mov_b32_e32 v134, v34
	v_mov_b32_e32 v135, v35
	v_mov_b32_e32 v140, v40
	v_mov_b32_e32 v141, v41
	v_permlane32_swap_b32_e32 v44, v148
	v_permlane32_swap_b32_e32 v45, v149
	v_pk_add_f32 v[26:27], v[138:139], v[26:27]
	v_permlane32_swap_b32_e32 v34, v134
	v_permlane32_swap_b32_e32 v35, v135
	v_mov_b32_e32 v138, v38
	v_mov_b32_e32 v139, v39
	v_permlane32_swap_b32_e32 v40, v140
	v_permlane32_swap_b32_e32 v41, v141
	v_pk_add_f32 v[44:45], v[44:45], v[148:149]
	v_mov_b32_e32 v148, v46
	v_mov_b32_e32 v149, v47
	v_pk_add_f32 v[34:35], v[34:35], v[134:135]
	v_permlane16_swap_b32_e32 v38, v138
	v_permlane16_swap_b32_e32 v39, v139
	v_pk_add_f32 v[40:41], v[40:41], v[140:141]
	v_permlane16_swap_b32_e32 v46, v148
	v_permlane16_swap_b32_e32 v47, v149
	v_pk_add_f32 v[34:35], v[146:147], v[34:35]
	v_add_f32_e32 v38, v38, v138
	v_add_f32_e32 v39, v39, v139
	v_pk_add_f32 v[40:41], v[144:145], v[40:41]
	global_load_dwordx4 v[144:147], v[132:133], off offset:2128
	global_load_dwordx4 v[228:231], v[132:133], off offset:2112
	v_add_f32_e32 v46, v46, v148
	v_add_f32_e32 v47, v47, v149
	v_mov_b32_e32 v138, v38
	v_mov_b32_e32 v139, v39
	v_mov_b32_e32 v148, v46
	v_mov_b32_e32 v149, v47
	v_permlane32_swap_b32_e32 v38, v138
	v_permlane32_swap_b32_e32 v39, v139
	v_permlane32_swap_b32_e32 v46, v148
	v_permlane32_swap_b32_e32 v47, v149
	v_pk_add_f32 v[38:39], v[38:39], v[138:139]
	v_pk_add_f32 v[46:47], v[46:47], v[148:149]
	v_mov_b32_e32 v148, v48
	v_mov_b32_e32 v149, v49
	v_pk_add_f32 v[38:39], v[142:143], v[38:39]
	v_mov_b32_e32 v142, v42
	v_mov_b32_e32 v143, v43
	v_permlane16_swap_b32_e32 v48, v148
	v_permlane16_swap_b32_e32 v49, v149
	v_permlane16_swap_b32_e32 v42, v142
	v_permlane16_swap_b32_e32 v43, v143
	v_add_f32_e32 v48, v48, v148
	v_add_f32_e32 v49, v49, v149
	v_add_f32_e32 v42, v42, v142
	v_add_f32_e32 v43, v43, v143
	v_mov_b32_e32 v148, v48
	v_mov_b32_e32 v149, v49
	v_mov_b32_e32 v142, v42
	v_mov_b32_e32 v143, v43
	v_permlane32_swap_b32_e32 v48, v148
	v_permlane32_swap_b32_e32 v49, v149
	v_permlane32_swap_b32_e32 v42, v142
	v_permlane32_swap_b32_e32 v43, v143
	v_pk_add_f32 v[48:49], v[48:49], v[148:149]
	v_mov_b32_e32 v148, v50
	v_pk_add_f32 v[42:43], v[42:43], v[142:143]
	s_nop 0
	v_permlane16_swap_b32_e32 v50, v148
	s_waitcnt vmcnt(2)
	v_pk_add_f32 v[42:43], v[196:197], v[42:43]
	v_pk_add_f32 v[44:45], v[198:199], v[44:45]
	v_pk_add_f32 v[46:47], v[150:151], v[46:47]
	v_add_f32_e32 v50, v50, v148
	global_load_dwordx4 v[148:151], v[132:133], off offset:2160
	global_load_dwordx4 v[196:199], v[132:133], off offset:2144
	v_pk_mul_f32 v[126:127], v[16:17], v[16:17]
	v_add_f32_e32 v128, v128, v129
	v_add_f32_e32 v126, v128, v126
	v_pk_mul_f32 v[122:123], v[10:11], v[10:11]
	v_add_f32_e32 v126, v126, v127
	v_add_f32_e32 v122, v126, v122
	v_pk_mul_f32 v[120:121], v[12:13], v[12:13]
	v_add_f32_e32 v122, v122, v123
	v_add_f32_e32 v120, v122, v120
	v_pk_mul_f32 v[118:119], v[18:19], v[18:19]
	v_add_f32_e32 v120, v120, v121
	v_add_f32_e32 v118, v120, v118
	v_pk_mul_f32 v[116:117], v[20:21], v[20:21]
	v_add_f32_e32 v118, v118, v119
	v_add_f32_e32 v116, v118, v116
	v_pk_mul_f32 v[114:115], v[22:23], v[22:23]
	v_add_f32_e32 v116, v116, v117
	v_add_f32_e32 v114, v116, v114
	v_pk_mul_f32 v[112:113], v[24:25], v[24:25]
	v_add_f32_e32 v114, v114, v115
	v_add_f32_e32 v112, v114, v112
	v_pk_mul_f32 v[80:81], v[2:3], v[2:3]
	v_add_f32_e32 v112, v112, v113
	v_add_f32_e32 v80, v112, v80
	v_pk_mul_f32 v[78:79], v[4:5], v[4:5]
	v_add_f32_e32 v80, v80, v81
	v_add_f32_e32 v78, v80, v78
	v_pk_mul_f32 v[76:77], v[6:7], v[6:7]
	v_add_f32_e32 v78, v78, v79
	v_add_f32_e32 v76, v78, v76
	v_pk_mul_f32 v[74:75], v[8:9], v[8:9]
	v_add_f32_e32 v76, v76, v77
	v_add_f32_e32 v74, v76, v74
	v_pk_mul_f32 v[72:73], v[26:27], v[26:27]
	v_add_f32_e32 v74, v74, v75
	v_add_f32_e32 v72, v74, v72
	v_pk_mul_f32 v[70:71], v[28:29], v[28:29]
	v_add_f32_e32 v72, v72, v73
	v_add_f32_e32 v70, v72, v70
	v_pk_mul_f32 v[68:69], v[30:31], v[30:31]
	v_add_f32_e32 v70, v70, v71
	v_add_f32_e32 v68, v70, v68
	v_pk_mul_f32 v[66:67], v[32:33], v[32:33]
	v_add_f32_e32 v68, v68, v69
	v_add_f32_e32 v52, v52, v227
	v_mov_b32_e32 v227, v53
	v_add_f32_e32 v66, v68, v66
	v_pk_mul_f32 v[134:135], v[34:35], v[34:35]
	v_permlane16_swap_b32_e32 v53, v227
	v_add_f32_e32 v66, v66, v67
	v_add_f32_e32 v53, v53, v227
	v_mov_b32_e32 v227, v54
	v_add_f32_e32 v66, v66, v134
	v_pk_mul_f32 v[136:137], v[36:37], v[36:37]
	v_permlane16_swap_b32_e32 v54, v227
	v_add_f32_e32 v66, v66, v135
	v_add_f32_e32 v54, v54, v227
	v_mov_b32_e32 v227, v55
	v_add_f32_e32 v66, v66, v136
	v_pk_mul_f32 v[138:139], v[38:39], v[38:39]
	v_permlane16_swap_b32_e32 v55, v227
	v_add_f32_e32 v66, v66, v137
	v_add_f32_e32 v55, v55, v227
	v_mov_b32_e32 v227, v56
	v_add_f32_e32 v66, v66, v138
	v_pk_mul_f32 v[140:141], v[40:41], v[40:41]
	v_permlane16_swap_b32_e32 v56, v227
	v_add_f32_e32 v66, v66, v139
	v_mov_b32_e32 v133, v51
	v_add_f32_e32 v56, v56, v227
	v_mov_b32_e32 v227, v57
	v_add_f32_e32 v66, v66, v140
	v_pk_mul_f32 v[142:143], v[42:43], v[42:43]
	v_permlane16_swap_b32_e32 v51, v133
	v_permlane16_swap_b32_e32 v57, v227
	v_add_f32_e32 v66, v66, v141
	v_add_f32_e32 v51, v51, v133
	v_add_f32_e32 v57, v57, v227
	v_mov_b32_e32 v227, v58
	v_add_f32_e32 v66, v66, v142
	v_pk_mul_f32 v[232:233], v[44:45], v[44:45]
	v_mov_b32_e32 v132, v50
	v_mov_b32_e32 v133, v51
	v_permlane16_swap_b32_e32 v58, v227
	v_add_f32_e32 v66, v66, v143
	v_permlane32_swap_b32_e32 v50, v132
	v_permlane32_swap_b32_e32 v51, v133
	v_add_f32_e32 v58, v58, v227
	v_mov_b32_e32 v227, v59
	v_add_f32_e32 v66, v66, v232
	v_pk_mul_f32 v[234:235], v[46:47], v[46:47]
	v_pk_add_f32 v[50:51], v[50:51], v[132:133]
	v_permlane16_swap_b32_e32 v59, v227
	v_add_f32_e32 v66, v66, v233
	v_pk_add_f32 v[48:49], v[152:153], v[48:49]
	s_waitcnt vmcnt(2)
	v_pk_add_f32 v[50:51], v[228:229], v[50:51]
	v_mov_b32_e32 v228, v52
	v_mov_b32_e32 v229, v53
	v_add_f32_e32 v59, v59, v227
	v_mov_b32_e32 v227, v60
	v_add_f32_e32 v66, v66, v234
	v_pk_mul_f32 v[152:153], v[48:49], v[48:49]
	v_permlane32_swap_b32_e32 v52, v228
	v_permlane32_swap_b32_e32 v53, v229
	v_permlane16_swap_b32_e32 v60, v227
	v_add_f32_e32 v66, v66, v235
	v_pk_add_f32 v[52:53], v[52:53], v[228:229]
	v_add_f32_e32 v60, v60, v227
	v_mov_b32_e32 v227, v61
	v_add_f32_e32 v66, v66, v152
	v_pk_mul_f32 v[132:133], v[50:51], v[50:51]
	v_pk_add_f32 v[52:53], v[230:231], v[52:53]
	v_mov_b32_e32 v230, v54
	v_mov_b32_e32 v231, v55
	v_permlane16_swap_b32_e32 v61, v227
	v_add_f32_e32 v66, v66, v153
	v_permlane32_swap_b32_e32 v54, v230
	v_permlane32_swap_b32_e32 v55, v231
	v_add_f32_e32 v61, v61, v227
	v_mov_b32_e32 v227, v62
	v_add_f32_e32 v66, v66, v132
	v_pk_mul_f32 v[228:229], v[52:53], v[52:53]
	v_pk_add_f32 v[54:55], v[54:55], v[230:231]
	v_mov_b32_e32 v230, v56
	v_mov_b32_e32 v231, v57
	v_permlane16_swap_b32_e32 v62, v227
	v_add_f32_e32 v66, v66, v133
	v_pk_add_f32 v[54:55], v[144:145], v[54:55]
	v_permlane32_swap_b32_e32 v56, v230
	v_permlane32_swap_b32_e32 v57, v231
	v_add_f32_e32 v62, v62, v227
	v_mov_b32_e32 v227, v63
	v_add_f32_e32 v66, v66, v228
	v_pk_mul_f32 v[144:145], v[54:55], v[54:55]
	v_pk_add_f32 v[56:57], v[56:57], v[230:231]
	v_mov_b32_e32 v230, v58
	v_mov_b32_e32 v231, v59
	v_permlane16_swap_b32_e32 v63, v227
	v_add_f32_e32 v66, v66, v229
	v_pk_add_f32 v[56:57], v[146:147], v[56:57]
	v_permlane32_swap_b32_e32 v58, v230
	v_permlane32_swap_b32_e32 v59, v231
	v_add_f32_e32 v63, v63, v227
	v_mov_b32_e32 v227, v64
	v_add_f32_e32 v66, v66, v144
	v_pk_mul_f32 v[146:147], v[56:57], v[56:57]
	v_pk_add_f32 v[58:59], v[58:59], v[230:231]
	v_mov_b32_e32 v230, v60
	v_mov_b32_e32 v231, v61
	v_permlane16_swap_b32_e32 v64, v227
	v_add_f32_e32 v66, v66, v145
	s_waitcnt vmcnt(0)
	v_pk_add_f32 v[58:59], v[196:197], v[58:59]
	v_permlane32_swap_b32_e32 v60, v230
	v_permlane32_swap_b32_e32 v61, v231
	v_add_f32_e32 v64, v64, v227
	v_mov_b32_e32 v227, v65
	v_add_f32_e32 v66, v66, v146
	v_pk_mul_f32 v[196:197], v[58:59], v[58:59]
	v_pk_add_f32 v[60:61], v[60:61], v[230:231]
	v_mov_b32_e32 v230, v62
	v_mov_b32_e32 v231, v63
	v_permlane16_swap_b32_e32 v65, v227
	v_add_f32_e32 v66, v66, v147
	v_pk_add_f32 v[60:61], v[198:199], v[60:61]
	v_permlane32_swap_b32_e32 v62, v230
	v_permlane32_swap_b32_e32 v63, v231
	v_add_f32_e32 v65, v65, v227
	v_add_f32_e32 v66, v66, v196
	v_pk_mul_f32 v[198:199], v[60:61], v[60:61]
	v_pk_add_f32 v[62:63], v[62:63], v[230:231]
	v_mov_b32_e32 v230, v64
	v_mov_b32_e32 v231, v65
	v_add_f32_e32 v66, v66, v197
	v_pk_add_f32 v[62:63], v[148:149], v[62:63]
	v_permlane32_swap_b32_e32 v64, v230
	v_permlane32_swap_b32_e32 v65, v231
	v_add_f32_e32 v66, v66, v198
	v_pk_mul_f32 v[148:149], v[62:63], v[62:63]
	v_pk_add_f32 v[64:65], v[64:65], v[230:231]
	v_add_f32_e32 v66, v66, v199
	v_pk_add_f32 v[64:65], v[150:151], v[64:65]
	v_add_f32_e32 v66, v66, v148
	v_pk_mul_f32 v[150:151], v[64:65], v[64:65]
	v_add_f32_e32 v66, v66, v149
	v_add_f32_e32 v66, v66, v150
	v_add_f32_e32 v66, v66, v151
	ds_bpermute_b32 v67, v207, v66
	v_readlane_b32 s60, v254, 29
	v_readlane_b32 s61, v254, 30
	v_lshl_add_u64 v[112:113], s[20:21], 0, v[130:131]
	v_lshl_add_u64 v[94:95], v[94:95], 1, s[16:17]
	s_waitcnt lgkmcnt(0)
	v_add_f32_e32 v66, v66, v67
	ds_bpermute_b32 v67, v208, v66
	v_lshl_add_u64 v[114:115], s[60:61], 0, v[130:131]
	v_readlane_b32 s62, v254, 31
	v_readlane_b32 s63, v254, 32
	s_waitcnt lgkmcnt(0)
	v_add_f32_e32 v66, v66, v67
	ds_bpermute_b32 v67, v209, v66
	s_waitcnt lgkmcnt(0)
	v_add_f32_e32 v66, v66, v67
	ds_bpermute_b32 v67, v210, v66
	s_waitcnt lgkmcnt(0)
	v_add_f32_e32 v66, v66, v67
	ds_bpermute_b32 v67, v211, v66
	s_waitcnt lgkmcnt(0)
	v_add_f32_e32 v66, v66, v67
	ds_bpermute_b32 v67, v212, v66
	s_waitcnt lgkmcnt(0)
	v_add_f32_e32 v66, v66, v67
	v_mul_f32_e32 v66, 0x3e800000, v66
	v_fmamk_f32 v66, v66, 0x3a800000, v172
	v_mul_f32_e32 v67, 0x4b800000, v66
	v_cmp_gt_f32_e32 vcc, s96, v66
	s_nop 1
	v_cndmask_b32_e32 v66, v66, v67, vcc
	v_rsq_f32_e32 v66, v66
	s_nop 0
	v_mul_f32_e32 v67, 0x45800000, v66
	v_cndmask_b32_e32 v116, v66, v67, vcc
	s_and_saveexec_b64 s[6:7], s[54:55]
	s_cbranch_execz .LBB0_195
	global_load_dwordx4 v[66:69], v[88:89], off
	global_load_dwordx4 v[70:73], v[88:89], off offset:16
	global_load_dwordx4 v[74:77], v[88:89], off offset:32
	global_load_dwordx4 v[78:81], v[88:89], off offset:48
	s_mov_b64 s[10:11], -1
	s_andn2_b64 vcc, exec, s[22:23]
	s_waitcnt vmcnt(3)
	v_pk_mul_f32 v[66:67], v[116:117], v[66:67] op_sel_hi:[0,1]
	v_pk_mul_f32 v[68:69], v[116:117], v[68:69] op_sel_hi:[0,1]
	s_waitcnt vmcnt(2)
	v_pk_mul_f32 v[70:71], v[116:117], v[70:71] op_sel_hi:[0,1]
	v_pk_mul_f32 v[72:73], v[116:117], v[72:73] op_sel_hi:[0,1]
	s_waitcnt vmcnt(1)
	v_pk_mul_f32 v[118:119], v[116:117], v[74:75] op_sel_hi:[0,1]
	v_pk_mul_f32 v[120:121], v[116:117], v[76:77] op_sel_hi:[0,1]
	s_waitcnt vmcnt(0)
	v_pk_mul_f32 v[122:123], v[116:117], v[78:79] op_sel_hi:[0,1]
	v_pk_mul_f32 v[126:127], v[116:117], v[80:81] op_sel_hi:[0,1]
	v_pk_mul_f32 v[78:79], v[14:15], v[66:67]
	v_pk_mul_f32 v[80:81], v[16:17], v[68:69]
	v_pk_mul_f32 v[74:75], v[10:11], v[70:71]
	v_pk_mul_f32 v[76:77], v[12:13], v[72:73]
	v_pk_mul_f32 v[70:71], v[18:19], v[118:119]
	v_pk_mul_f32 v[72:73], v[20:21], v[120:121]
	v_pk_mul_f32 v[66:67], v[22:23], v[122:123]
	v_pk_mul_f32 v[68:69], v[24:25], v[126:127]
	s_cbranch_vccnz .LBB0_193
	s_mov_b64 s[10:11], 0
	global_store_dwordx4 v[114:115], v[78:81], off
	global_store_dwordx4 v[114:115], v[74:77], off offset:16
	global_store_dwordx4 v[114:115], v[70:73], off offset:32
	global_store_dwordx4 v[114:115], v[66:69], off offset:48
